# K-loop edge: exit compare moved ahead of the closing barrier (one SALU off the post-barrier path), all four GEMM loops
# speedup vs baseline: 1.0133x; 1.0133x over previous
; #define PG8_STAGE(bufoff, gbase, voff) do { _Pragma("unroll") for (int _i = 0; _i < 2; ++_i) \
;         __builtin_amdgcn_global_load_lds((const unsigned*)((const char*)(gbase) + (voff)[_i]), (PG8_LAS unsigned*)(lds + (bufoff) + ldsw + _i * 8192), 16, 0, 0); } while (0)
; #define PG8_LDA(dst, b, h) do { _Pragma("unroll") for (int m = 0; m < 4; ++m) _Pragma("unroll") for (int k = 0; k < 2; ++k) dst[m][k] = *(const PG8_LAS bf16x8*)(lds + PG8_SA(b, h) + aoff + m * 2048 + k * 1024); } while (0)
; #define PG8_LDB(dst, b, h) do { _Pragma("unroll") for (int n = 0; n < 2; ++n) _Pragma("unroll") for (int k = 0; k < 2; ++k) dst[n][k] = *(const PG8_LAS bf16x8*)(lds + PG8_SB(b, h) + boff + n * 2048 + k * 1024); } while (0)
; #define PG8_MMA(ai, bj, At, Bt) do { __builtin_amdgcn_s_setprio(1); _Pragma("unroll") for (int m = 0; m < 4; ++m) _Pragma("unroll") for (int n = 0; n < 2; ++n) _Pragma("unroll") for (int k = 0; k < 2; ++k) \
;         acc[ai][bj][m][n] = __builtin_amdgcn_mfma_f32_16x16x32_bf16(Bt[n][k], At[m][k], acc[ai][bj][m][n], 0, 0, 0); __builtin_amdgcn_s_setprio(0); } while (0)
; #define PG8_WAIT_V(n) asm volatile("s_waitcnt vmcnt(" #n ")" ::: "memory")
; #define PG8_WAIT_L(n) asm volatile("s_waitcnt lgkmcnt(" #n ")" ::: "memory")
; #define PG8_BAR __builtin_amdgcn_s_barrier()
; #define PG8_SCHED __builtin_amdgcn_sched_barrier(0)
; template <class Epi, class Sched, bool ALIGN_EPI = false, bool SP2 = false>
; __device__ __forceinline__ void gemm_phase(PG8_LAS unsigned char* lds, const Gemm g, const Sched& S, const Epi& E) {
;     ...
;             PG8_LDB(B0, 0, 0); PG8_LDB(B1, 0, 1); PG8_SCHED; PG8_LDA(At, 0, 0); PG8_STAGE(PG8_SA(1, 1), a1 + hstep, voffA);
;             PG8_WAIT_V(8); PG8_WAIT_L(0); PG8_BAR; PG8_MMA(0, 0, At, B0); PG8_MMA(0, 1, At, B1); PG8_BAR; PG8_SCHED;
;             PG8_LDA(At, 0, 1); PG8_STAGE(PG8_SB(0, 0), b2, voffB); PG8_STAGE(PG8_SB(0, 1), b2 + hstep, voffB); PG8_STAGE(PG8_SA(0, 0), a2, voffA);
;             PG8_WAIT_V(8); PG8_WAIT_L(0); PG8_BAR; PG8_MMA(1, 0, At, B0); PG8_MMA(1, 1, At, B1); PG8_BAR; PG8_SCHED;
.Lz_enter_339:
	s_add_u32 s16, s16, 0x80
	s_addc_u32 s17, s17, 0
	s_add_u32 s33, s20, 0x100
	s_addc_u32 s39, s21, 0
	s_mov_b32 s20, 0
	ds_read_b128 v[82:85], v167
	ds_read_b128 v[86:89], v167 offset:1024
	ds_read_b128 v[138:141], v167 offset:2048
	ds_read_b128 v[142:145], v167 offset:3072
	ds_read_b128 v[158:161], v167 offset:16384
	ds_read_b128 v[162:165], v167 offset:17408
	ds_read_b128 v[170:173], v167 offset:18432
	ds_read_b128 v[174:177], v167 offset:19456
	s_add_i32 m0, s63, 0xc000
	ds_read_b128 v[178:181], v169
	ds_read_b128 v[182:185], v169 offset:1024
	ds_read_b128 v[186:189], v169 offset:2048
	ds_read_b128 v[190:193], v169 offset:3072
	ds_read_b128 v[194:197], v169 offset:4096
	ds_read_b128 v[198:201], v169 offset:5120
	ds_read_b128 v[202:205], v169 offset:6144
	global_load_lds_dwordx4 v154, s[16:17]
	s_add_i32 m0, s63, 0xe000
	ds_read_b128 v[206:209], v169 offset:7168
	global_load_lds_dwordx4 v156, s[16:17]
	s_waitcnt vmcnt(8) lgkmcnt(0)
	s_barrier
	s_setprio 1
	v_mfma_f32_16x16x32_bf16 v[134:137], v[82:85], v[178:181], 0
	v_mfma_f32_16x16x32_bf16 v[130:133], v[138:141], v[178:181], 0
	v_mfma_f32_16x16x32_bf16 v[126:129], v[82:85], v[186:189], 0
	v_mfma_f32_16x16x32_bf16 v[122:125], v[138:141], v[186:189], 0
	s_add_i32 s44, s20, 2
	v_mfma_f32_16x16x32_bf16 v[118:121], v[82:85], v[194:197], 0
	s_add_u32 s45, s16, 0x80
	v_mfma_f32_16x16x32_bf16 v[114:117], v[138:141], v[194:197], 0
	s_addc_u32 s21, s17, 0
	v_mfma_f32_16x16x32_bf16 v[110:113], v[82:85], v[202:205], 0
	s_cmp_eq_u32 s70, s20
	v_mfma_f32_16x16x32_bf16 v[106:109], v[138:141], v[202:205], 0
	s_cselect_b32 s21, s7, s21
	v_mfma_f32_16x16x32_bf16 v[134:137], v[86:89], v[182:185], v[134:137]
	s_cselect_b32 s20, s6, s45
	v_mfma_f32_16x16x32_bf16 v[130:133], v[142:145], v[182:185], v[130:133]
	s_cselect_b32 s47, s57, s39
	v_mfma_f32_16x16x32_bf16 v[126:129], v[86:89], v[190:193], v[126:129]
	s_cselect_b32 s46, s56, s33
	v_mfma_f32_16x16x32_bf16 v[122:125], v[142:145], v[190:193], v[122:125]
	v_mfma_f32_16x16x32_bf16 v[118:121], v[86:89], v[198:201], v[118:121]
	v_mfma_f32_16x16x32_bf16 v[114:117], v[142:145], v[198:201], v[114:117]
	v_mfma_f32_16x16x32_bf16 v[110:113], v[86:89], v[206:209], v[110:113]
	v_mfma_f32_16x16x32_bf16 v[106:109], v[142:145], v[206:209], v[106:109]
	v_mfma_f32_16x16x32_bf16 v[62:65], v[158:161], v[178:181], 0
	v_mfma_f32_16x16x32_bf16 v[58:61], v[170:173], v[178:181], 0
	v_mfma_f32_16x16x32_bf16 v[54:57], v[158:161], v[186:189], 0
	v_mfma_f32_16x16x32_bf16 v[50:53], v[170:173], v[186:189], 0
	v_mfma_f32_16x16x32_bf16 v[46:49], v[158:161], v[194:197], 0
	v_mfma_f32_16x16x32_bf16 v[42:45], v[170:173], v[194:197], 0
	v_mfma_f32_16x16x32_bf16 v[38:41], v[158:161], v[202:205], 0
	v_mfma_f32_16x16x32_bf16 v[34:37], v[170:173], v[202:205], 0
	v_mfma_f32_16x16x32_bf16 v[62:65], v[162:165], v[182:185], v[62:65]
	v_mfma_f32_16x16x32_bf16 v[58:61], v[174:177], v[182:185], v[58:61]
	v_mfma_f32_16x16x32_bf16 v[54:57], v[162:165], v[190:193], v[54:57]
	v_mfma_f32_16x16x32_bf16 v[50:53], v[174:177], v[190:193], v[50:53]
	v_mfma_f32_16x16x32_bf16 v[46:49], v[162:165], v[198:201], v[46:49]
	v_mfma_f32_16x16x32_bf16 v[42:45], v[174:177], v[198:201], v[42:45]
	v_mfma_f32_16x16x32_bf16 v[38:41], v[162:165], v[206:209], v[38:41]
	v_mfma_f32_16x16x32_bf16 v[34:37], v[174:177], v[206:209], v[34:37]
	s_setprio 0
	s_barrier
	s_add_i32 m0, s62, 0x10000
	s_add_u32 s100, s46, s10
	s_addc_u32 s101, s47, s11
	ds_read_b128 v[178:181], v169 offset:16384
	ds_read_b128 v[182:185], v169 offset:17408
	ds_read_b128 v[186:189], v169 offset:18432
	global_load_lds_dwordx4 v148, s[46:47]
	s_add_i32 m0, s62, 0x12000
	ds_read_b128 v[190:193], v169 offset:19456
	global_load_lds_dwordx4 v152, s[46:47]
	s_add_i32 m0, s62, 0x14000
	ds_read_b128 v[194:197], v169 offset:20480
	global_load_lds_dwordx4 v148, s[100:101]
	s_add_i32 m0, s62, 0x16000
	ds_read_b128 v[198:201], v169 offset:21504
	global_load_lds_dwordx4 v152, s[100:101]
	s_mov_b32 m0, s63
	ds_read_b128 v[202:205], v169 offset:22528
	global_load_lds_dwordx4 v146, s[20:21]
	s_mov_b32 m0, s64
	ds_read_b128 v[206:209], v169 offset:23552
	global_load_lds_dwordx4 v150, s[20:21]
	s_waitcnt vmcnt(8) lgkmcnt(0)
	s_barrier
	s_setprio 1
	v_mfma_f32_16x16x32_bf16 v[102:105], v[82:85], v[178:181], 0
	v_mfma_f32_16x16x32_bf16 v[98:101], v[138:141], v[178:181], 0
	v_mfma_f32_16x16x32_bf16 v[94:97], v[82:85], v[186:189], 0
	v_mfma_f32_16x16x32_bf16 v[90:93], v[138:141], v[186:189], 0
	v_mfma_f32_16x16x32_bf16 v[78:81], v[82:85], v[194:197], 0
	v_mfma_f32_16x16x32_bf16 v[74:77], v[138:141], v[194:197], 0
	v_mfma_f32_16x16x32_bf16 v[70:73], v[82:85], v[202:205], 0
	v_mfma_f32_16x16x32_bf16 v[66:69], v[138:141], v[202:205], 0
	v_mfma_f32_16x16x32_bf16 v[102:105], v[86:89], v[182:185], v[102:105]
	v_mfma_f32_16x16x32_bf16 v[98:101], v[142:145], v[182:185], v[98:101]
	v_mfma_f32_16x16x32_bf16 v[94:97], v[86:89], v[190:193], v[94:97]
	v_mfma_f32_16x16x32_bf16 v[90:93], v[142:145], v[190:193], v[90:93]
	v_mfma_f32_16x16x32_bf16 v[78:81], v[86:89], v[198:201], v[78:81]
	v_mfma_f32_16x16x32_bf16 v[74:77], v[142:145], v[198:201], v[74:77]
	v_mfma_f32_16x16x32_bf16 v[70:73], v[86:89], v[206:209], v[70:73]
	v_mfma_f32_16x16x32_bf16 v[66:69], v[142:145], v[206:209], v[66:69]
	v_mfma_f32_16x16x32_bf16 v[30:33], v[158:161], v[178:181], 0
	v_mfma_f32_16x16x32_bf16 v[26:29], v[170:173], v[178:181], 0
	v_mfma_f32_16x16x32_bf16 v[22:25], v[158:161], v[186:189], 0
	v_mfma_f32_16x16x32_bf16 v[18:21], v[170:173], v[186:189], 0
	v_mfma_f32_16x16x32_bf16 v[14:17], v[158:161], v[194:197], 0
	v_mfma_f32_16x16x32_bf16 v[10:13], v[170:173], v[194:197], 0
	v_mfma_f32_16x16x32_bf16 v[6:9], v[158:161], v[202:205], 0
	v_mfma_f32_16x16x32_bf16 v[2:5], v[170:173], v[202:205], 0
	v_mfma_f32_16x16x32_bf16 v[30:33], v[162:165], v[182:185], v[30:33]
	v_mfma_f32_16x16x32_bf16 v[26:29], v[174:177], v[182:185], v[26:29]
	v_mfma_f32_16x16x32_bf16 v[22:25], v[162:165], v[190:193], v[22:25]
	v_mfma_f32_16x16x32_bf16 v[18:21], v[174:177], v[190:193], v[18:21]
	v_mfma_f32_16x16x32_bf16 v[14:17], v[162:165], v[198:201], v[14:17]
	v_mfma_f32_16x16x32_bf16 v[10:13], v[174:177], v[198:201], v[10:13]
	v_mfma_f32_16x16x32_bf16 v[6:9], v[162:165], v[206:209], v[6:9]
	v_mfma_f32_16x16x32_bf16 v[2:5], v[174:177], v[206:209], v[2:5]
	s_setprio 0
	s_barrier
; #define PG8_STAGE(bufoff, gbase, voff) do { _Pragma("unroll") for (int _i = 0; _i < 2; ++_i) \
;         __builtin_amdgcn_global_load_lds((const unsigned*)((const char*)(gbase) + (voff)[_i]), (PG8_LAS unsigned*)(lds + (bufoff) + ldsw + _i * 8192), 16, 0, 0); } while (0)
; #define PG8_LDA(dst, b, h) do { _Pragma("unroll") for (int m = 0; m < 4; ++m) _Pragma("unroll") for (int k = 0; k < 2; ++k) dst[m][k] = *(const PG8_LAS bf16x8*)(lds + PG8_SA(b, h) + aoff + m * 2048 + k * 1024); } while (0)
; #define PG8_LDB(dst, b, h) do { _Pragma("unroll") for (int n = 0; n < 2; ++n) _Pragma("unroll") for (int k = 0; k < 2; ++k) dst[n][k] = *(const PG8_LAS bf16x8*)(lds + PG8_SB(b, h) + boff + n * 2048 + k * 1024); } while (0)
; #define PG8_MMA(ai, bj, At, Bt) do { __builtin_amdgcn_s_setprio(1); _Pragma("unroll") for (int m = 0; m < 4; ++m) _Pragma("unroll") for (int n = 0; n < 2; ++n) _Pragma("unroll") for (int k = 0; k < 2; ++k) \
;         acc[ai][bj][m][n] = __builtin_amdgcn_mfma_f32_16x16x32_bf16(Bt[n][k], At[m][k], acc[ai][bj][m][n], 0, 0, 0); __builtin_amdgcn_s_setprio(0); } while (0)
; #define PG8_WAIT_V(n) asm volatile("s_waitcnt vmcnt(" #n ")" ::: "memory")
; #define PG8_WAIT_L(n) asm volatile("s_waitcnt lgkmcnt(" #n ")" ::: "memory")
; #define PG8_BAR __builtin_amdgcn_s_barrier()
; #define PG8_SCHED __builtin_amdgcn_sched_barrier(0)
; template <class Epi, class Sched, bool ALIGN_EPI = false, bool SP2 = false>
; __device__ __forceinline__ void gemm_phase(PG8_LAS unsigned char* lds, const Gemm g, const Sched& S, const Epi& E) {
;     ...
;             PG8_LDB(B0, 1, 0); PG8_LDB(B1, 1, 1); PG8_SCHED; PG8_LDA(At, 1, 0); PG8_STAGE(PG8_SA(0, 1), a2 + hstep, voffA);
;             PG8_WAIT_V(8); PG8_WAIT_L(0); PG8_BAR; PG8_MMA(0, 0, At, B0); PG8_MMA(0, 1, At, B1); PG8_BAR; PG8_SCHED;
;             PG8_LDA(At, 1, 1); PG8_STAGE(PG8_SB(1, 0), b3, voffB); PG8_STAGE(PG8_SB(1, 1), b3 + hstep, voffB); PG8_STAGE(PG8_SA(1, 0), a3, voffA);
;             PG8_WAIT_V(8); PG8_WAIT_L(0); PG8_BAR; PG8_MMA(1, 0, At, B0); PG8_MMA(1, 1, At, B1); PG8_BAR; PG8_SCHED;
	ds_read_b128 v[82:85], v167 offset:32768
	ds_read_b128 v[86:89], v167 offset:33792
	ds_read_b128 v[138:141], v167 offset:34816
	ds_read_b128 v[142:145], v167 offset:35840
	ds_read_b128 v[158:161], v167 offset:49152
	ds_read_b128 v[162:165], v167 offset:50176
	ds_read_b128 v[170:173], v167 offset:51200
	ds_read_b128 v[174:177], v167 offset:52224
	s_mov_b32 m0, s65
	ds_read_b128 v[178:181], v169 offset:32768
	ds_read_b128 v[182:185], v169 offset:33792
	ds_read_b128 v[186:189], v169 offset:34816
	ds_read_b128 v[190:193], v169 offset:35840
	ds_read_b128 v[194:197], v169 offset:36864
	ds_read_b128 v[198:201], v169 offset:37888
	ds_read_b128 v[202:205], v169 offset:38912
	global_load_lds_dwordx4 v154, s[20:21]
	s_mov_b32 m0, s66
	ds_read_b128 v[206:209], v169 offset:39936
	global_load_lds_dwordx4 v156, s[20:21]
	s_waitcnt vmcnt(8) lgkmcnt(0)
	s_barrier
	s_setprio 1
	v_mfma_f32_16x16x32_bf16 v[134:137], v[82:85], v[178:181], v[134:137]
	v_mfma_f32_16x16x32_bf16 v[130:133], v[138:141], v[178:181], v[130:133]
	v_mfma_f32_16x16x32_bf16 v[126:129], v[82:85], v[186:189], v[126:129]
	v_mfma_f32_16x16x32_bf16 v[122:125], v[138:141], v[186:189], v[122:125]
	v_mfma_f32_16x16x32_bf16 v[118:121], v[82:85], v[194:197], v[118:121]
	v_mfma_f32_16x16x32_bf16 v[114:117], v[138:141], v[194:197], v[114:117]
	v_mfma_f32_16x16x32_bf16 v[110:113], v[82:85], v[202:205], v[110:113]
	v_mfma_f32_16x16x32_bf16 v[106:109], v[138:141], v[202:205], v[106:109]
	v_mfma_f32_16x16x32_bf16 v[134:137], v[86:89], v[182:185], v[134:137]
	v_mfma_f32_16x16x32_bf16 v[130:133], v[142:145], v[182:185], v[130:133]
	v_mfma_f32_16x16x32_bf16 v[126:129], v[86:89], v[190:193], v[126:129]
	v_mfma_f32_16x16x32_bf16 v[122:125], v[142:145], v[190:193], v[122:125]
	v_mfma_f32_16x16x32_bf16 v[118:121], v[86:89], v[198:201], v[118:121]
	v_mfma_f32_16x16x32_bf16 v[114:117], v[142:145], v[198:201], v[114:117]
	v_mfma_f32_16x16x32_bf16 v[110:113], v[86:89], v[206:209], v[110:113]
	v_mfma_f32_16x16x32_bf16 v[106:109], v[142:145], v[206:209], v[106:109]
	v_mfma_f32_16x16x32_bf16 v[62:65], v[158:161], v[178:181], v[62:65]
	v_mfma_f32_16x16x32_bf16 v[58:61], v[170:173], v[178:181], v[58:61]
	v_mfma_f32_16x16x32_bf16 v[54:57], v[158:161], v[186:189], v[54:57]
	v_mfma_f32_16x16x32_bf16 v[50:53], v[170:173], v[186:189], v[50:53]
	v_mfma_f32_16x16x32_bf16 v[46:49], v[158:161], v[194:197], v[46:49]
	v_mfma_f32_16x16x32_bf16 v[42:45], v[170:173], v[194:197], v[42:45]
	v_mfma_f32_16x16x32_bf16 v[38:41], v[158:161], v[202:205], v[38:41]
	v_mfma_f32_16x16x32_bf16 v[34:37], v[170:173], v[202:205], v[34:37]
	v_mfma_f32_16x16x32_bf16 v[62:65], v[162:165], v[182:185], v[62:65]
	v_mfma_f32_16x16x32_bf16 v[58:61], v[174:177], v[182:185], v[58:61]
	v_mfma_f32_16x16x32_bf16 v[54:57], v[162:165], v[190:193], v[54:57]
	v_mfma_f32_16x16x32_bf16 v[50:53], v[174:177], v[190:193], v[50:53]
	v_mfma_f32_16x16x32_bf16 v[46:49], v[162:165], v[198:201], v[46:49]
	v_mfma_f32_16x16x32_bf16 v[42:45], v[174:177], v[198:201], v[42:45]
	v_mfma_f32_16x16x32_bf16 v[38:41], v[162:165], v[206:209], v[38:41]
	v_mfma_f32_16x16x32_bf16 v[34:37], v[174:177], v[206:209], v[34:37]
	s_setprio 0
	s_barrier
	s_add_i32 m0, s62, 0x17f80
	ds_read_b128 v[178:181], v169 offset:49152
	ds_read_b128 v[182:185], v169 offset:50176
	ds_read_b128 v[186:189], v169 offset:51200
	global_load_lds_dwordx4 v148, s[46:47] offset:128
	s_add_i32 m0, s62, 0x19f80
	ds_read_b128 v[190:193], v169 offset:52224
	global_load_lds_dwordx4 v152, s[46:47] offset:128
	s_add_i32 m0, s62, 0x1bf80
	ds_read_b128 v[194:197], v169 offset:53248
	global_load_lds_dwordx4 v148, s[100:101] offset:128
	s_add_i32 m0, s62, 0x1df80
	ds_read_b128 v[198:201], v169 offset:54272
	global_load_lds_dwordx4 v152, s[100:101] offset:128
	s_sub_i32 m0, s68, 0x80
	ds_read_b128 v[202:205], v169 offset:55296
	global_load_lds_dwordx4 v146, s[20:21] offset:128
	s_sub_i32 m0, s69, 0x80
	ds_read_b128 v[206:209], v169 offset:56320
	global_load_lds_dwordx4 v150, s[20:21] offset:128
	s_waitcnt vmcnt(8) lgkmcnt(0)
	s_barrier
	s_setprio 1
	v_mfma_f32_16x16x32_bf16 v[102:105], v[82:85], v[178:181], v[102:105]
	v_mfma_f32_16x16x32_bf16 v[98:101], v[138:141], v[178:181], v[98:101]
	v_mfma_f32_16x16x32_bf16 v[94:97], v[82:85], v[186:189], v[94:97]
	v_mfma_f32_16x16x32_bf16 v[90:93], v[138:141], v[186:189], v[90:93]
	s_add_u32 s16, s16, 0x100
	v_mfma_f32_16x16x32_bf16 v[78:81], v[82:85], v[194:197], v[78:81]
	s_addc_u32 s17, s17, 0
	v_mfma_f32_16x16x32_bf16 v[74:77], v[138:141], v[194:197], v[74:77]
	s_add_u32 s33, s33, 0x100
	v_mfma_f32_16x16x32_bf16 v[70:73], v[82:85], v[202:205], v[70:73]
	s_addc_u32 s39, s39, 0
	v_mfma_f32_16x16x32_bf16 v[66:69], v[138:141], v[202:205], v[66:69]
	s_mov_b32 s20, s44
	v_mfma_f32_16x16x32_bf16 v[102:105], v[86:89], v[182:185], v[102:105]
	v_mfma_f32_16x16x32_bf16 v[98:101], v[142:145], v[182:185], v[98:101]
	v_mfma_f32_16x16x32_bf16 v[94:97], v[86:89], v[190:193], v[94:97]
	v_mfma_f32_16x16x32_bf16 v[90:93], v[142:145], v[190:193], v[90:93]
	v_mfma_f32_16x16x32_bf16 v[78:81], v[86:89], v[198:201], v[78:81]
	v_mfma_f32_16x16x32_bf16 v[74:77], v[142:145], v[198:201], v[74:77]
	v_mfma_f32_16x16x32_bf16 v[70:73], v[86:89], v[206:209], v[70:73]
	v_mfma_f32_16x16x32_bf16 v[66:69], v[142:145], v[206:209], v[66:69]
	v_mfma_f32_16x16x32_bf16 v[30:33], v[158:161], v[178:181], v[30:33]
	v_mfma_f32_16x16x32_bf16 v[26:29], v[170:173], v[178:181], v[26:29]
	v_mfma_f32_16x16x32_bf16 v[22:25], v[158:161], v[186:189], v[22:25]
	v_mfma_f32_16x16x32_bf16 v[18:21], v[170:173], v[186:189], v[18:21]
	v_mfma_f32_16x16x32_bf16 v[14:17], v[158:161], v[194:197], v[14:17]
	v_mfma_f32_16x16x32_bf16 v[10:13], v[170:173], v[194:197], v[10:13]
	v_mfma_f32_16x16x32_bf16 v[6:9], v[158:161], v[202:205], v[6:9]
	v_mfma_f32_16x16x32_bf16 v[2:5], v[170:173], v[202:205], v[2:5]
	v_mfma_f32_16x16x32_bf16 v[30:33], v[162:165], v[182:185], v[30:33]
	v_mfma_f32_16x16x32_bf16 v[26:29], v[174:177], v[182:185], v[26:29]
	v_mfma_f32_16x16x32_bf16 v[22:25], v[162:165], v[190:193], v[22:25]
	v_mfma_f32_16x16x32_bf16 v[18:21], v[174:177], v[190:193], v[18:21]
	v_mfma_f32_16x16x32_bf16 v[14:17], v[162:165], v[198:201], v[14:17]
	v_mfma_f32_16x16x32_bf16 v[10:13], v[174:177], v[198:201], v[10:13]
	v_mfma_f32_16x16x32_bf16 v[6:9], v[162:165], v[206:209], v[6:9]
	v_mfma_f32_16x16x32_bf16 v[2:5], v[174:177], v[206:209], v[2:5]
	s_setprio 0
	s_cmp_ge_i32 s44, s67
	s_barrier
	s_cbranch_scc1 .Lpz_exit_341
; #define PG8_STAGE(bufoff, gbase, voff) do { _Pragma("unroll") for (int _i = 0; _i < 2; ++_i) \
;         __builtin_amdgcn_global_load_lds((const unsigned*)((const char*)(gbase) + (voff)[_i]), (PG8_LAS unsigned*)(lds + (bufoff) + ldsw + _i * 8192), 16, 0, 0); } while (0)
; #define PG8_LDA(dst, b, h) do { _Pragma("unroll") for (int m = 0; m < 4; ++m) _Pragma("unroll") for (int k = 0; k < 2; ++k) dst[m][k] = *(const PG8_LAS bf16x8*)(lds + PG8_SA(b, h) + aoff + m * 2048 + k * 1024); } while (0)
; #define PG8_LDB(dst, b, h) do { _Pragma("unroll") for (int n = 0; n < 2; ++n) _Pragma("unroll") for (int k = 0; k < 2; ++k) dst[n][k] = *(const PG8_LAS bf16x8*)(lds + PG8_SB(b, h) + boff + n * 2048 + k * 1024); } while (0)
; #define PG8_MMA(ai, bj, At, Bt) do { __builtin_amdgcn_s_setprio(1); _Pragma("unroll") for (int m = 0; m < 4; ++m) _Pragma("unroll") for (int n = 0; n < 2; ++n) _Pragma("unroll") for (int k = 0; k < 2; ++k) \
;         acc[ai][bj][m][n] = __builtin_amdgcn_mfma_f32_16x16x32_bf16(Bt[n][k], At[m][k], acc[ai][bj][m][n], 0, 0, 0); __builtin_amdgcn_s_setprio(0); } while (0)
; #define PG8_WAIT_V(n) asm volatile("s_waitcnt vmcnt(" #n ")" ::: "memory")
; #define PG8_WAIT_L(n) asm volatile("s_waitcnt lgkmcnt(" #n ")" ::: "memory")
; #define PG8_BAR __builtin_amdgcn_s_barrier()
; #define PG8_SCHED __builtin_amdgcn_sched_barrier(0)
; template <class Epi, class Sched, bool ALIGN_EPI = false, bool SP2 = false>
; __device__ __forceinline__ void gemm_phase(PG8_LAS unsigned char* lds, const Gemm g, const Sched& S, const Epi& E) {
;     ...
;             PG8_LDB(B0, 0, 0); PG8_LDB(B1, 0, 1); PG8_SCHED; PG8_LDA(At, 0, 0); PG8_STAGE(PG8_SA(1, 1), a1 + hstep, voffA);
;             PG8_WAIT_V(8); PG8_WAIT_L(0); PG8_BAR; PG8_MMA(0, 0, At, B0); PG8_MMA(0, 1, At, B1); PG8_BAR; PG8_SCHED;
;             PG8_LDA(At, 0, 1); PG8_STAGE(PG8_SB(0, 0), b2, voffB); PG8_STAGE(PG8_SB(0, 1), b2 + hstep, voffB); PG8_STAGE(PG8_SA(0, 0), a2, voffA);
;             PG8_WAIT_V(8); PG8_WAIT_L(0); PG8_BAR; PG8_MMA(1, 0, At, B0); PG8_MMA(1, 1, At, B1); PG8_BAR; PG8_SCHED;
.LBB0_341:
	ds_read_b128 v[82:85], v167
	ds_read_b128 v[86:89], v167 offset:1024
	ds_read_b128 v[138:141], v167 offset:2048
	ds_read_b128 v[142:145], v167 offset:3072
	ds_read_b128 v[158:161], v167 offset:16384
	ds_read_b128 v[162:165], v167 offset:17408
	ds_read_b128 v[170:173], v167 offset:18432
	ds_read_b128 v[174:177], v167 offset:19456
	s_add_i32 m0, s63, 0xc000
	ds_read_b128 v[178:181], v169
	ds_read_b128 v[182:185], v169 offset:1024
	ds_read_b128 v[186:189], v169 offset:2048
	ds_read_b128 v[190:193], v169 offset:3072
	ds_read_b128 v[194:197], v169 offset:4096
	ds_read_b128 v[198:201], v169 offset:5120
	ds_read_b128 v[202:205], v169 offset:6144
	global_load_lds_dwordx4 v154, s[16:17]
	s_add_i32 m0, s63, 0xe000
	ds_read_b128 v[206:209], v169 offset:7168
	global_load_lds_dwordx4 v156, s[16:17]
	s_waitcnt vmcnt(8) lgkmcnt(0)
	s_barrier
	s_setprio 1
	v_mfma_f32_16x16x32_bf16 v[134:137], v[82:85], v[178:181], v[134:137]
	v_mfma_f32_16x16x32_bf16 v[130:133], v[138:141], v[178:181], v[130:133]
	v_mfma_f32_16x16x32_bf16 v[126:129], v[82:85], v[186:189], v[126:129]
	v_mfma_f32_16x16x32_bf16 v[122:125], v[138:141], v[186:189], v[122:125]
	s_add_i32 s44, s20, 2
	v_mfma_f32_16x16x32_bf16 v[118:121], v[82:85], v[194:197], v[118:121]
	s_add_u32 s45, s16, 0x80
	v_mfma_f32_16x16x32_bf16 v[114:117], v[138:141], v[194:197], v[114:117]
	s_addc_u32 s21, s17, 0
	v_mfma_f32_16x16x32_bf16 v[110:113], v[82:85], v[202:205], v[110:113]
	s_cmp_eq_u32 s70, s20
	v_mfma_f32_16x16x32_bf16 v[106:109], v[138:141], v[202:205], v[106:109]
	s_cselect_b32 s21, s7, s21
	v_mfma_f32_16x16x32_bf16 v[134:137], v[86:89], v[182:185], v[134:137]
	s_cselect_b32 s20, s6, s45
	v_mfma_f32_16x16x32_bf16 v[130:133], v[142:145], v[182:185], v[130:133]
	s_cselect_b32 s47, s57, s39
	v_mfma_f32_16x16x32_bf16 v[126:129], v[86:89], v[190:193], v[126:129]
	s_cselect_b32 s46, s56, s33
	v_mfma_f32_16x16x32_bf16 v[122:125], v[142:145], v[190:193], v[122:125]
	v_mfma_f32_16x16x32_bf16 v[118:121], v[86:89], v[198:201], v[118:121]
	v_mfma_f32_16x16x32_bf16 v[114:117], v[142:145], v[198:201], v[114:117]
	v_mfma_f32_16x16x32_bf16 v[110:113], v[86:89], v[206:209], v[110:113]
	v_mfma_f32_16x16x32_bf16 v[106:109], v[142:145], v[206:209], v[106:109]
	v_mfma_f32_16x16x32_bf16 v[62:65], v[158:161], v[178:181], v[62:65]
	v_mfma_f32_16x16x32_bf16 v[58:61], v[170:173], v[178:181], v[58:61]
	v_mfma_f32_16x16x32_bf16 v[54:57], v[158:161], v[186:189], v[54:57]
	v_mfma_f32_16x16x32_bf16 v[50:53], v[170:173], v[186:189], v[50:53]
	v_mfma_f32_16x16x32_bf16 v[46:49], v[158:161], v[194:197], v[46:49]
	v_mfma_f32_16x16x32_bf16 v[42:45], v[170:173], v[194:197], v[42:45]
	v_mfma_f32_16x16x32_bf16 v[38:41], v[158:161], v[202:205], v[38:41]
	v_mfma_f32_16x16x32_bf16 v[34:37], v[170:173], v[202:205], v[34:37]
	v_mfma_f32_16x16x32_bf16 v[62:65], v[162:165], v[182:185], v[62:65]
	v_mfma_f32_16x16x32_bf16 v[58:61], v[174:177], v[182:185], v[58:61]
	v_mfma_f32_16x16x32_bf16 v[54:57], v[162:165], v[190:193], v[54:57]
	v_mfma_f32_16x16x32_bf16 v[50:53], v[174:177], v[190:193], v[50:53]
	v_mfma_f32_16x16x32_bf16 v[46:49], v[162:165], v[198:201], v[46:49]
	v_mfma_f32_16x16x32_bf16 v[42:45], v[174:177], v[198:201], v[42:45]
	v_mfma_f32_16x16x32_bf16 v[38:41], v[162:165], v[206:209], v[38:41]
	v_mfma_f32_16x16x32_bf16 v[34:37], v[174:177], v[206:209], v[34:37]
	s_setprio 0
	s_barrier
	s_add_i32 m0, s62, 0x10000
	s_add_u32 s100, s46, s10
	s_addc_u32 s101, s47, s11
	ds_read_b128 v[178:181], v169 offset:16384
	ds_read_b128 v[182:185], v169 offset:17408
	ds_read_b128 v[186:189], v169 offset:18432
	global_load_lds_dwordx4 v148, s[46:47]
	s_add_i32 m0, s62, 0x12000
	ds_read_b128 v[190:193], v169 offset:19456
	global_load_lds_dwordx4 v152, s[46:47]
	s_add_i32 m0, s62, 0x14000
	ds_read_b128 v[194:197], v169 offset:20480
	global_load_lds_dwordx4 v148, s[100:101]
	s_add_i32 m0, s62, 0x16000
	ds_read_b128 v[198:201], v169 offset:21504
	global_load_lds_dwordx4 v152, s[100:101]
	s_mov_b32 m0, s63
	ds_read_b128 v[202:205], v169 offset:22528
	global_load_lds_dwordx4 v146, s[20:21]
	s_mov_b32 m0, s64
	ds_read_b128 v[206:209], v169 offset:23552
	global_load_lds_dwordx4 v150, s[20:21]
	s_waitcnt vmcnt(8) lgkmcnt(0)
	s_barrier
	s_setprio 1
	v_mfma_f32_16x16x32_bf16 v[102:105], v[82:85], v[178:181], v[102:105]
	v_mfma_f32_16x16x32_bf16 v[98:101], v[138:141], v[178:181], v[98:101]
	v_mfma_f32_16x16x32_bf16 v[94:97], v[82:85], v[186:189], v[94:97]
	v_mfma_f32_16x16x32_bf16 v[90:93], v[138:141], v[186:189], v[90:93]
	v_mfma_f32_16x16x32_bf16 v[78:81], v[82:85], v[194:197], v[78:81]
	v_mfma_f32_16x16x32_bf16 v[74:77], v[138:141], v[194:197], v[74:77]
	v_mfma_f32_16x16x32_bf16 v[70:73], v[82:85], v[202:205], v[70:73]
	v_mfma_f32_16x16x32_bf16 v[66:69], v[138:141], v[202:205], v[66:69]
	v_mfma_f32_16x16x32_bf16 v[102:105], v[86:89], v[182:185], v[102:105]
	v_mfma_f32_16x16x32_bf16 v[98:101], v[142:145], v[182:185], v[98:101]
	v_mfma_f32_16x16x32_bf16 v[94:97], v[86:89], v[190:193], v[94:97]
	v_mfma_f32_16x16x32_bf16 v[90:93], v[142:145], v[190:193], v[90:93]
	v_mfma_f32_16x16x32_bf16 v[78:81], v[86:89], v[198:201], v[78:81]
	v_mfma_f32_16x16x32_bf16 v[74:77], v[142:145], v[198:201], v[74:77]
	v_mfma_f32_16x16x32_bf16 v[70:73], v[86:89], v[206:209], v[70:73]
	v_mfma_f32_16x16x32_bf16 v[66:69], v[142:145], v[206:209], v[66:69]
	v_mfma_f32_16x16x32_bf16 v[30:33], v[158:161], v[178:181], v[30:33]
	v_mfma_f32_16x16x32_bf16 v[26:29], v[170:173], v[178:181], v[26:29]
	v_mfma_f32_16x16x32_bf16 v[22:25], v[158:161], v[186:189], v[22:25]
	v_mfma_f32_16x16x32_bf16 v[18:21], v[170:173], v[186:189], v[18:21]
	v_mfma_f32_16x16x32_bf16 v[14:17], v[158:161], v[194:197], v[14:17]
	v_mfma_f32_16x16x32_bf16 v[10:13], v[170:173], v[194:197], v[10:13]
	v_mfma_f32_16x16x32_bf16 v[6:9], v[158:161], v[202:205], v[6:9]
	v_mfma_f32_16x16x32_bf16 v[2:5], v[170:173], v[202:205], v[2:5]
	v_mfma_f32_16x16x32_bf16 v[30:33], v[162:165], v[182:185], v[30:33]
	v_mfma_f32_16x16x32_bf16 v[26:29], v[174:177], v[182:185], v[26:29]
	v_mfma_f32_16x16x32_bf16 v[22:25], v[162:165], v[190:193], v[22:25]
	v_mfma_f32_16x16x32_bf16 v[18:21], v[174:177], v[190:193], v[18:21]
	v_mfma_f32_16x16x32_bf16 v[14:17], v[162:165], v[198:201], v[14:17]
	v_mfma_f32_16x16x32_bf16 v[10:13], v[174:177], v[198:201], v[10:13]
	v_mfma_f32_16x16x32_bf16 v[6:9], v[162:165], v[206:209], v[6:9]
	v_mfma_f32_16x16x32_bf16 v[2:5], v[174:177], v[206:209], v[2:5]
	s_setprio 0
	s_barrier
; #define PG8_STAGE(bufoff, gbase, voff) do { _Pragma("unroll") for (int _i = 0; _i < 2; ++_i) \
;         __builtin_amdgcn_global_load_lds((const unsigned*)((const char*)(gbase) + (voff)[_i]), (PG8_LAS unsigned*)(lds + (bufoff) + ldsw + _i * 8192), 16, 0, 0); } while (0)
; #define PG8_LDA(dst, b, h) do { _Pragma("unroll") for (int m = 0; m < 4; ++m) _Pragma("unroll") for (int k = 0; k < 2; ++k) dst[m][k] = *(const PG8_LAS bf16x8*)(lds + PG8_SA(b, h) + aoff + m * 2048 + k * 1024); } while (0)
; #define PG8_LDB(dst, b, h) do { _Pragma("unroll") for (int n = 0; n < 2; ++n) _Pragma("unroll") for (int k = 0; k < 2; ++k) dst[n][k] = *(const PG8_LAS bf16x8*)(lds + PG8_SB(b, h) + boff + n * 2048 + k * 1024); } while (0)
; #define PG8_MMA(ai, bj, At, Bt) do { __builtin_amdgcn_s_setprio(1); _Pragma("unroll") for (int m = 0; m < 4; ++m) _Pragma("unroll") for (int n = 0; n < 2; ++n) _Pragma("unroll") for (int k = 0; k < 2; ++k) \
;         acc[ai][bj][m][n] = __builtin_amdgcn_mfma_f32_16x16x32_bf16(Bt[n][k], At[m][k], acc[ai][bj][m][n], 0, 0, 0); __builtin_amdgcn_s_setprio(0); } while (0)
; #define PG8_WAIT_V(n) asm volatile("s_waitcnt vmcnt(" #n ")" ::: "memory")
; #define PG8_WAIT_L(n) asm volatile("s_waitcnt lgkmcnt(" #n ")" ::: "memory")
; #define PG8_BAR __builtin_amdgcn_s_barrier()
; #define PG8_SCHED __builtin_amdgcn_sched_barrier(0)
; template <class Epi, class Sched, bool ALIGN_EPI = false, bool SP2 = false>
; __device__ __forceinline__ void gemm_phase(PG8_LAS unsigned char* lds, const Gemm g, const Sched& S, const Epi& E) {
;     ...
;             PG8_LDB(B0, 1, 0); PG8_LDB(B1, 1, 1); PG8_SCHED; PG8_LDA(At, 1, 0); PG8_STAGE(PG8_SA(0, 1), a2 + hstep, voffA);
;             PG8_WAIT_V(8); PG8_WAIT_L(0); PG8_BAR; PG8_MMA(0, 0, At, B0); PG8_MMA(0, 1, At, B1); PG8_BAR; PG8_SCHED;
;             PG8_LDA(At, 1, 1); PG8_STAGE(PG8_SB(1, 0), b3, voffB); PG8_STAGE(PG8_SB(1, 1), b3 + hstep, voffB); PG8_STAGE(PG8_SA(1, 0), a3, voffA);
;             PG8_WAIT_V(8); PG8_WAIT_L(0); PG8_BAR; PG8_MMA(1, 0, At, B0); PG8_MMA(1, 1, At, B1); PG8_BAR; PG8_SCHED;
	ds_read_b128 v[82:85], v167 offset:32768
	ds_read_b128 v[86:89], v167 offset:33792
	ds_read_b128 v[138:141], v167 offset:34816
	ds_read_b128 v[142:145], v167 offset:35840
	ds_read_b128 v[158:161], v167 offset:49152
	ds_read_b128 v[162:165], v167 offset:50176
	ds_read_b128 v[170:173], v167 offset:51200
	ds_read_b128 v[174:177], v167 offset:52224
	s_mov_b32 m0, s65
	ds_read_b128 v[178:181], v169 offset:32768
	ds_read_b128 v[182:185], v169 offset:33792
	ds_read_b128 v[186:189], v169 offset:34816
	ds_read_b128 v[190:193], v169 offset:35840
	ds_read_b128 v[194:197], v169 offset:36864
	ds_read_b128 v[198:201], v169 offset:37888
	ds_read_b128 v[202:205], v169 offset:38912
	global_load_lds_dwordx4 v154, s[20:21]
	s_mov_b32 m0, s66
	ds_read_b128 v[206:209], v169 offset:39936
	global_load_lds_dwordx4 v156, s[20:21]
	s_waitcnt vmcnt(8) lgkmcnt(0)
	s_barrier
	s_setprio 1
	v_mfma_f32_16x16x32_bf16 v[134:137], v[82:85], v[178:181], v[134:137]
	v_mfma_f32_16x16x32_bf16 v[130:133], v[138:141], v[178:181], v[130:133]
	v_mfma_f32_16x16x32_bf16 v[126:129], v[82:85], v[186:189], v[126:129]
	v_mfma_f32_16x16x32_bf16 v[122:125], v[138:141], v[186:189], v[122:125]
	v_mfma_f32_16x16x32_bf16 v[118:121], v[82:85], v[194:197], v[118:121]
	v_mfma_f32_16x16x32_bf16 v[114:117], v[138:141], v[194:197], v[114:117]
	v_mfma_f32_16x16x32_bf16 v[110:113], v[82:85], v[202:205], v[110:113]
	v_mfma_f32_16x16x32_bf16 v[106:109], v[138:141], v[202:205], v[106:109]
	v_mfma_f32_16x16x32_bf16 v[134:137], v[86:89], v[182:185], v[134:137]
	v_mfma_f32_16x16x32_bf16 v[130:133], v[142:145], v[182:185], v[130:133]
	v_mfma_f32_16x16x32_bf16 v[126:129], v[86:89], v[190:193], v[126:129]
	v_mfma_f32_16x16x32_bf16 v[122:125], v[142:145], v[190:193], v[122:125]
	v_mfma_f32_16x16x32_bf16 v[118:121], v[86:89], v[198:201], v[118:121]
	v_mfma_f32_16x16x32_bf16 v[114:117], v[142:145], v[198:201], v[114:117]
	v_mfma_f32_16x16x32_bf16 v[110:113], v[86:89], v[206:209], v[110:113]
	v_mfma_f32_16x16x32_bf16 v[106:109], v[142:145], v[206:209], v[106:109]
	v_mfma_f32_16x16x32_bf16 v[62:65], v[158:161], v[178:181], v[62:65]
	v_mfma_f32_16x16x32_bf16 v[58:61], v[170:173], v[178:181], v[58:61]
	v_mfma_f32_16x16x32_bf16 v[54:57], v[158:161], v[186:189], v[54:57]
	v_mfma_f32_16x16x32_bf16 v[50:53], v[170:173], v[186:189], v[50:53]
	v_mfma_f32_16x16x32_bf16 v[46:49], v[158:161], v[194:197], v[46:49]
	v_mfma_f32_16x16x32_bf16 v[42:45], v[170:173], v[194:197], v[42:45]
	v_mfma_f32_16x16x32_bf16 v[38:41], v[158:161], v[202:205], v[38:41]
	v_mfma_f32_16x16x32_bf16 v[34:37], v[170:173], v[202:205], v[34:37]
	v_mfma_f32_16x16x32_bf16 v[62:65], v[162:165], v[182:185], v[62:65]
	v_mfma_f32_16x16x32_bf16 v[58:61], v[174:177], v[182:185], v[58:61]
	v_mfma_f32_16x16x32_bf16 v[54:57], v[162:165], v[190:193], v[54:57]
	v_mfma_f32_16x16x32_bf16 v[50:53], v[174:177], v[190:193], v[50:53]
	v_mfma_f32_16x16x32_bf16 v[46:49], v[162:165], v[198:201], v[46:49]
	v_mfma_f32_16x16x32_bf16 v[42:45], v[174:177], v[198:201], v[42:45]
	v_mfma_f32_16x16x32_bf16 v[38:41], v[162:165], v[206:209], v[38:41]
	v_mfma_f32_16x16x32_bf16 v[34:37], v[174:177], v[206:209], v[34:37]
	s_setprio 0
	s_barrier
	s_add_i32 m0, s62, 0x17f80
	ds_read_b128 v[178:181], v169 offset:49152
	ds_read_b128 v[182:185], v169 offset:50176
	ds_read_b128 v[186:189], v169 offset:51200
	global_load_lds_dwordx4 v148, s[46:47] offset:128
	s_add_i32 m0, s62, 0x19f80
	ds_read_b128 v[190:193], v169 offset:52224
	global_load_lds_dwordx4 v152, s[46:47] offset:128
	s_add_i32 m0, s62, 0x1bf80
	ds_read_b128 v[194:197], v169 offset:53248
	global_load_lds_dwordx4 v148, s[100:101] offset:128
	s_add_i32 m0, s62, 0x1df80
	ds_read_b128 v[198:201], v169 offset:54272
	global_load_lds_dwordx4 v152, s[100:101] offset:128
	s_sub_i32 m0, s68, 0x80
	ds_read_b128 v[202:205], v169 offset:55296
	global_load_lds_dwordx4 v146, s[20:21] offset:128
	s_sub_i32 m0, s69, 0x80
	ds_read_b128 v[206:209], v169 offset:56320
	global_load_lds_dwordx4 v150, s[20:21] offset:128
	s_waitcnt vmcnt(8) lgkmcnt(0)
	s_barrier
	s_setprio 1
	v_mfma_f32_16x16x32_bf16 v[102:105], v[82:85], v[178:181], v[102:105]
	v_mfma_f32_16x16x32_bf16 v[98:101], v[138:141], v[178:181], v[98:101]
	v_mfma_f32_16x16x32_bf16 v[94:97], v[82:85], v[186:189], v[94:97]
	v_mfma_f32_16x16x32_bf16 v[90:93], v[138:141], v[186:189], v[90:93]
	s_add_u32 s16, s16, 0x100
	v_mfma_f32_16x16x32_bf16 v[78:81], v[82:85], v[194:197], v[78:81]
	s_addc_u32 s17, s17, 0
	v_mfma_f32_16x16x32_bf16 v[74:77], v[138:141], v[194:197], v[74:77]
	s_add_u32 s33, s33, 0x100
	v_mfma_f32_16x16x32_bf16 v[70:73], v[82:85], v[202:205], v[70:73]
	s_addc_u32 s39, s39, 0
	v_mfma_f32_16x16x32_bf16 v[66:69], v[138:141], v[202:205], v[66:69]
	s_mov_b32 s20, s44
	v_mfma_f32_16x16x32_bf16 v[102:105], v[86:89], v[182:185], v[102:105]
	v_mfma_f32_16x16x32_bf16 v[98:101], v[142:145], v[182:185], v[98:101]
	v_mfma_f32_16x16x32_bf16 v[94:97], v[86:89], v[190:193], v[94:97]
	v_mfma_f32_16x16x32_bf16 v[90:93], v[142:145], v[190:193], v[90:93]
	v_mfma_f32_16x16x32_bf16 v[78:81], v[86:89], v[198:201], v[78:81]
	v_mfma_f32_16x16x32_bf16 v[74:77], v[142:145], v[198:201], v[74:77]
	v_mfma_f32_16x16x32_bf16 v[70:73], v[86:89], v[206:209], v[70:73]
	v_mfma_f32_16x16x32_bf16 v[66:69], v[142:145], v[206:209], v[66:69]
	v_mfma_f32_16x16x32_bf16 v[30:33], v[158:161], v[178:181], v[30:33]
	v_mfma_f32_16x16x32_bf16 v[26:29], v[170:173], v[178:181], v[26:29]
	v_mfma_f32_16x16x32_bf16 v[22:25], v[158:161], v[186:189], v[22:25]
	v_mfma_f32_16x16x32_bf16 v[18:21], v[170:173], v[186:189], v[18:21]
	v_mfma_f32_16x16x32_bf16 v[14:17], v[158:161], v[194:197], v[14:17]
	v_mfma_f32_16x16x32_bf16 v[10:13], v[170:173], v[194:197], v[10:13]
	v_mfma_f32_16x16x32_bf16 v[6:9], v[158:161], v[202:205], v[6:9]
	v_mfma_f32_16x16x32_bf16 v[2:5], v[170:173], v[202:205], v[2:5]
	v_mfma_f32_16x16x32_bf16 v[30:33], v[162:165], v[182:185], v[30:33]
	v_mfma_f32_16x16x32_bf16 v[26:29], v[174:177], v[182:185], v[26:29]
	v_mfma_f32_16x16x32_bf16 v[22:25], v[162:165], v[190:193], v[22:25]
	v_mfma_f32_16x16x32_bf16 v[18:21], v[174:177], v[190:193], v[18:21]
	v_mfma_f32_16x16x32_bf16 v[14:17], v[162:165], v[198:201], v[14:17]
	v_mfma_f32_16x16x32_bf16 v[10:13], v[174:177], v[198:201], v[10:13]
	v_mfma_f32_16x16x32_bf16 v[6:9], v[162:165], v[206:209], v[6:9]
	v_mfma_f32_16x16x32_bf16 v[2:5], v[174:177], v[206:209], v[2:5]
	s_setprio 0
	s_cmp_ge_i32 s44, s67
	s_barrier
	s_cbranch_scc0 .LBB0_341

; #define PG8_STAGE(bufoff, gbase, voff) do { _Pragma("unroll") for (int _i = 0; _i < 2; ++_i) \
;         __builtin_amdgcn_global_load_lds((const unsigned*)((const char*)(gbase) + (voff)[_i]), (PG8_LAS unsigned*)(lds + (bufoff) + ldsw + _i * 8192), 16, 0, 0); } while (0)
; #define PG8_LDA(dst, b, h) do { _Pragma("unroll") for (int m = 0; m < 4; ++m) _Pragma("unroll") for (int k = 0; k < 2; ++k) dst[m][k] = *(const PG8_LAS bf16x8*)(lds + PG8_SA(b, h) + aoff + m * 2048 + k * 1024); } while (0)
; #define PG8_LDB(dst, b, h) do { _Pragma("unroll") for (int n = 0; n < 2; ++n) _Pragma("unroll") for (int k = 0; k < 2; ++k) dst[n][k] = *(const PG8_LAS bf16x8*)(lds + PG8_SB(b, h) + boff + n * 2048 + k * 1024); } while (0)
; #define PG8_MMA(ai, bj, At, Bt) do { __builtin_amdgcn_s_setprio(1); _Pragma("unroll") for (int m = 0; m < 4; ++m) _Pragma("unroll") for (int n = 0; n < 2; ++n) _Pragma("unroll") for (int k = 0; k < 2; ++k) \
;         acc[ai][bj][m][n] = __builtin_amdgcn_mfma_f32_16x16x32_bf16(Bt[n][k], At[m][k], acc[ai][bj][m][n], 0, 0, 0); __builtin_amdgcn_s_setprio(0); } while (0)
; #define PG8_WAIT_V(n) asm volatile("s_waitcnt vmcnt(" #n ")" ::: "memory")
; #define PG8_WAIT_L(n) asm volatile("s_waitcnt lgkmcnt(" #n ")" ::: "memory")
; #define PG8_BAR __builtin_amdgcn_s_barrier()
; #define PG8_SCHED __builtin_amdgcn_sched_barrier(0)
; template <class Epi, class Sched, bool ALIGN_EPI = false, bool SP2 = false>
; __device__ __forceinline__ void gemm_phase(PG8_LAS unsigned char* lds, const Gemm g, const Sched& S, const Epi& E) {
;     ...
;             PG8_LDB(B0, 0, 0); PG8_LDB(B1, 0, 1); PG8_SCHED; PG8_LDA(At, 0, 0); PG8_STAGE(PG8_SA(1, 1), a1 + hstep, voffA);
;             PG8_WAIT_V(8); PG8_WAIT_L(0); PG8_BAR; PG8_MMA(0, 0, At, B0); PG8_MMA(0, 1, At, B1); PG8_BAR; PG8_SCHED;
;             PG8_LDA(At, 0, 1); PG8_STAGE(PG8_SB(0, 0), b2, voffB); PG8_STAGE(PG8_SB(0, 1), b2 + hstep, voffB); PG8_STAGE(PG8_SA(0, 0), a2, voffA);
;             PG8_WAIT_V(8); PG8_WAIT_L(0); PG8_BAR; PG8_MMA(1, 0, At, B0); PG8_MMA(1, 1, At, B1); PG8_BAR; PG8_SCHED;
.Lz_enter_518:
	s_add_u32 s8, s52, 0x80
	s_addc_u32 s9, s53, 0
	s_add_u32 s52, s20, 0x100
	s_addc_u32 s53, s21, 0
	s_mov_b32 s20, 0
	ds_read_b128 v[130:133], v185
	ds_read_b128 v[134:137], v185 offset:1024
	ds_read_b128 v[138:141], v185 offset:2048
	ds_read_b128 v[142:145], v185 offset:3072
	ds_read_b128 v[146:149], v185 offset:16384
	ds_read_b128 v[150:153], v185 offset:17408
	ds_read_b128 v[166:169], v185 offset:18432
	ds_read_b128 v[170:173], v185 offset:19456
	s_add_i32 m0, s56, 0xc000
	ds_read_b128 v[174:177], v189
	ds_read_b128 v[178:181], v189 offset:1024
	ds_read_b128 v[190:193], v189 offset:2048
	ds_read_b128 v[194:197], v189 offset:3072
	ds_read_b128 v[198:201], v189 offset:4096
	ds_read_b128 v[202:205], v189 offset:5120
	ds_read_b128 v[206:209], v189 offset:6144
	global_load_lds_dwordx4 v162, s[8:9]
	s_add_i32 m0, s56, 0xe000
	ds_read_b128 v[210:213], v189 offset:7168
	global_load_lds_dwordx4 v164, s[8:9]
	s_waitcnt vmcnt(8) lgkmcnt(0)
	s_barrier
	s_setprio 1
	v_mfma_f32_16x16x32_bf16 v[126:129], v[130:133], v[174:177], 0
	v_mfma_f32_16x16x32_bf16 v[122:125], v[138:141], v[174:177], 0
	v_mfma_f32_16x16x32_bf16 v[110:113], v[130:133], v[190:193], 0
	v_mfma_f32_16x16x32_bf16 v[106:109], v[138:141], v[190:193], 0
	s_add_i32 s69, s20, 2
	v_mfma_f32_16x16x32_bf16 v[94:97], v[130:133], v[198:201], 0
	s_add_u32 s70, s8, 0x80
	v_mfma_f32_16x16x32_bf16 v[90:93], v[138:141], v[198:201], 0
	s_addc_u32 s21, s9, 0
	v_mfma_f32_16x16x32_bf16 v[78:81], v[130:133], v[206:209], 0
	s_cmp_eq_u32 s63, s20
	v_mfma_f32_16x16x32_bf16 v[74:77], v[138:141], v[206:209], 0
	s_cselect_b32 s21, s49, s21
	v_mfma_f32_16x16x32_bf16 v[126:129], v[134:137], v[178:181], v[126:129]
	s_cselect_b32 s20, s48, s70
	v_mfma_f32_16x16x32_bf16 v[122:125], v[142:145], v[178:181], v[122:125]
	s_cselect_b32 s71, s51, s53
	v_mfma_f32_16x16x32_bf16 v[110:113], v[134:137], v[194:197], v[110:113]
	s_cselect_b32 s70, s50, s52
	v_mfma_f32_16x16x32_bf16 v[106:109], v[142:145], v[194:197], v[106:109]
	v_mfma_f32_16x16x32_bf16 v[94:97], v[134:137], v[202:205], v[94:97]
	v_mfma_f32_16x16x32_bf16 v[90:93], v[142:145], v[202:205], v[90:93]
	v_mfma_f32_16x16x32_bf16 v[78:81], v[134:137], v[210:213], v[78:81]
	v_mfma_f32_16x16x32_bf16 v[74:77], v[142:145], v[210:213], v[74:77]
	v_mfma_f32_16x16x32_bf16 v[118:121], v[146:149], v[174:177], 0
	v_mfma_f32_16x16x32_bf16 v[114:117], v[166:169], v[174:177], 0
	v_mfma_f32_16x16x32_bf16 v[102:105], v[146:149], v[190:193], 0
	v_mfma_f32_16x16x32_bf16 v[98:101], v[166:169], v[190:193], 0
	v_mfma_f32_16x16x32_bf16 v[86:89], v[146:149], v[198:201], 0
	v_mfma_f32_16x16x32_bf16 v[82:85], v[166:169], v[198:201], 0
	v_mfma_f32_16x16x32_bf16 v[70:73], v[146:149], v[206:209], 0
	v_mfma_f32_16x16x32_bf16 v[66:69], v[166:169], v[206:209], 0
	v_mfma_f32_16x16x32_bf16 v[118:121], v[150:153], v[178:181], v[118:121]
	v_mfma_f32_16x16x32_bf16 v[114:117], v[170:173], v[178:181], v[114:117]
	v_mfma_f32_16x16x32_bf16 v[102:105], v[150:153], v[194:197], v[102:105]
	v_mfma_f32_16x16x32_bf16 v[98:101], v[170:173], v[194:197], v[98:101]
	v_mfma_f32_16x16x32_bf16 v[86:89], v[150:153], v[202:205], v[86:89]
	v_mfma_f32_16x16x32_bf16 v[82:85], v[170:173], v[202:205], v[82:85]
	v_mfma_f32_16x16x32_bf16 v[70:73], v[150:153], v[210:213], v[70:73]
	v_mfma_f32_16x16x32_bf16 v[66:69], v[170:173], v[210:213], v[66:69]
	s_setprio 0
	s_barrier
	s_add_i32 m0, s30, 0x10000
	s_add_u32 s100, s70, s12
	s_addc_u32 s101, s71, s13
	ds_read_b128 v[174:177], v189 offset:16384
	ds_read_b128 v[178:181], v189 offset:17408
	ds_read_b128 v[190:193], v189 offset:18432
	global_load_lds_dwordx4 v0, s[70:71]
	s_add_i32 m0, s30, 0x12000
	ds_read_b128 v[194:197], v189 offset:19456
	global_load_lds_dwordx4 v154, s[70:71]
	s_add_i32 m0, s30, 0x14000
	ds_read_b128 v[198:201], v189 offset:20480
	global_load_lds_dwordx4 v0, s[100:101]
	s_add_i32 m0, s30, 0x16000
	ds_read_b128 v[202:205], v189 offset:21504
	global_load_lds_dwordx4 v154, s[100:101]
	s_mov_b32 m0, s56
	ds_read_b128 v[206:209], v189 offset:22528
	global_load_lds_dwordx4 v158, s[20:21]
	s_mov_b32 m0, s57
	ds_read_b128 v[210:213], v189 offset:23552
	global_load_lds_dwordx4 v156, s[20:21]
	s_waitcnt vmcnt(8) lgkmcnt(0)
	s_barrier
	s_setprio 1
	v_mfma_f32_16x16x32_bf16 v[62:65], v[130:133], v[174:177], 0
	v_mfma_f32_16x16x32_bf16 v[58:61], v[138:141], v[174:177], 0
	v_mfma_f32_16x16x32_bf16 v[46:49], v[130:133], v[190:193], 0
	v_mfma_f32_16x16x32_bf16 v[42:45], v[138:141], v[190:193], 0
	v_mfma_f32_16x16x32_bf16 v[30:33], v[130:133], v[198:201], 0
	v_mfma_f32_16x16x32_bf16 v[26:29], v[138:141], v[198:201], 0
	v_mfma_f32_16x16x32_bf16 v[14:17], v[130:133], v[206:209], 0
	v_mfma_f32_16x16x32_bf16 v[10:13], v[138:141], v[206:209], 0
	v_mfma_f32_16x16x32_bf16 v[62:65], v[134:137], v[178:181], v[62:65]
	v_mfma_f32_16x16x32_bf16 v[58:61], v[142:145], v[178:181], v[58:61]
	v_mfma_f32_16x16x32_bf16 v[46:49], v[134:137], v[194:197], v[46:49]
	v_mfma_f32_16x16x32_bf16 v[42:45], v[142:145], v[194:197], v[42:45]
	v_mfma_f32_16x16x32_bf16 v[30:33], v[134:137], v[202:205], v[30:33]
	v_mfma_f32_16x16x32_bf16 v[26:29], v[142:145], v[202:205], v[26:29]
	v_mfma_f32_16x16x32_bf16 v[14:17], v[134:137], v[210:213], v[14:17]
	v_mfma_f32_16x16x32_bf16 v[10:13], v[142:145], v[210:213], v[10:13]
	v_mfma_f32_16x16x32_bf16 v[54:57], v[146:149], v[174:177], 0
	v_mfma_f32_16x16x32_bf16 v[50:53], v[166:169], v[174:177], 0
	v_mfma_f32_16x16x32_bf16 v[38:41], v[146:149], v[190:193], 0
	v_mfma_f32_16x16x32_bf16 v[34:37], v[166:169], v[190:193], 0
	v_mfma_f32_16x16x32_bf16 v[22:25], v[146:149], v[198:201], 0
	v_mfma_f32_16x16x32_bf16 v[18:21], v[166:169], v[198:201], 0
	v_mfma_f32_16x16x32_bf16 v[6:9], v[146:149], v[206:209], 0
	v_mfma_f32_16x16x32_bf16 v[2:5], v[166:169], v[206:209], 0
	v_mfma_f32_16x16x32_bf16 v[54:57], v[150:153], v[178:181], v[54:57]
	v_mfma_f32_16x16x32_bf16 v[50:53], v[170:173], v[178:181], v[50:53]
	v_mfma_f32_16x16x32_bf16 v[38:41], v[150:153], v[194:197], v[38:41]
	v_mfma_f32_16x16x32_bf16 v[34:37], v[170:173], v[194:197], v[34:37]
	v_mfma_f32_16x16x32_bf16 v[22:25], v[150:153], v[202:205], v[22:25]
	v_mfma_f32_16x16x32_bf16 v[18:21], v[170:173], v[202:205], v[18:21]
	v_mfma_f32_16x16x32_bf16 v[6:9], v[150:153], v[210:213], v[6:9]
	v_mfma_f32_16x16x32_bf16 v[2:5], v[170:173], v[210:213], v[2:5]
	s_setprio 0
	s_barrier
; #define PG8_STAGE(bufoff, gbase, voff) do { _Pragma("unroll") for (int _i = 0; _i < 2; ++_i) \
;         __builtin_amdgcn_global_load_lds((const unsigned*)((const char*)(gbase) + (voff)[_i]), (PG8_LAS unsigned*)(lds + (bufoff) + ldsw + _i * 8192), 16, 0, 0); } while (0)
; #define PG8_LDA(dst, b, h) do { _Pragma("unroll") for (int m = 0; m < 4; ++m) _Pragma("unroll") for (int k = 0; k < 2; ++k) dst[m][k] = *(const PG8_LAS bf16x8*)(lds + PG8_SA(b, h) + aoff + m * 2048 + k * 1024); } while (0)
; #define PG8_LDB(dst, b, h) do { _Pragma("unroll") for (int n = 0; n < 2; ++n) _Pragma("unroll") for (int k = 0; k < 2; ++k) dst[n][k] = *(const PG8_LAS bf16x8*)(lds + PG8_SB(b, h) + boff + n * 2048 + k * 1024); } while (0)
; #define PG8_MMA(ai, bj, At, Bt) do { __builtin_amdgcn_s_setprio(1); _Pragma("unroll") for (int m = 0; m < 4; ++m) _Pragma("unroll") for (int n = 0; n < 2; ++n) _Pragma("unroll") for (int k = 0; k < 2; ++k) \
;         acc[ai][bj][m][n] = __builtin_amdgcn_mfma_f32_16x16x32_bf16(Bt[n][k], At[m][k], acc[ai][bj][m][n], 0, 0, 0); __builtin_amdgcn_s_setprio(0); } while (0)
; #define PG8_WAIT_V(n) asm volatile("s_waitcnt vmcnt(" #n ")" ::: "memory")
; #define PG8_WAIT_L(n) asm volatile("s_waitcnt lgkmcnt(" #n ")" ::: "memory")
; #define PG8_BAR __builtin_amdgcn_s_barrier()
; #define PG8_SCHED __builtin_amdgcn_sched_barrier(0)
; template <class Epi, class Sched, bool ALIGN_EPI = false, bool SP2 = false>
; __device__ __forceinline__ void gemm_phase(PG8_LAS unsigned char* lds, const Gemm g, const Sched& S, const Epi& E) {
;     ...
;             PG8_LDB(B0, 1, 0); PG8_LDB(B1, 1, 1); PG8_SCHED; PG8_LDA(At, 1, 0); PG8_STAGE(PG8_SA(0, 1), a2 + hstep, voffA);
;             PG8_WAIT_V(8); PG8_WAIT_L(0); PG8_BAR; PG8_MMA(0, 0, At, B0); PG8_MMA(0, 1, At, B1); PG8_BAR; PG8_SCHED;
;             PG8_LDA(At, 1, 1); PG8_STAGE(PG8_SB(1, 0), b3, voffB); PG8_STAGE(PG8_SB(1, 1), b3 + hstep, voffB); PG8_STAGE(PG8_SA(1, 0), a3, voffA);
;             PG8_WAIT_V(8); PG8_WAIT_L(0); PG8_BAR; PG8_MMA(1, 0, At, B0); PG8_MMA(1, 1, At, B1); PG8_BAR; PG8_SCHED;
	ds_read_b128 v[130:133], v185 offset:32768
	ds_read_b128 v[134:137], v185 offset:33792
	ds_read_b128 v[138:141], v185 offset:34816
	ds_read_b128 v[142:145], v185 offset:35840
	ds_read_b128 v[146:149], v185 offset:49152
	ds_read_b128 v[150:153], v185 offset:50176
	ds_read_b128 v[166:169], v185 offset:51200
	ds_read_b128 v[170:173], v185 offset:52224
	s_mov_b32 m0, s58
	ds_read_b128 v[174:177], v189 offset:32768
	ds_read_b128 v[178:181], v189 offset:33792
	ds_read_b128 v[190:193], v189 offset:34816
	ds_read_b128 v[194:197], v189 offset:35840
	ds_read_b128 v[198:201], v189 offset:36864
	ds_read_b128 v[202:205], v189 offset:37888
	ds_read_b128 v[206:209], v189 offset:38912
	global_load_lds_dwordx4 v162, s[20:21]
	s_mov_b32 m0, s59
	ds_read_b128 v[210:213], v189 offset:39936
	global_load_lds_dwordx4 v164, s[20:21]
	s_waitcnt vmcnt(8) lgkmcnt(0)
	s_barrier
	s_setprio 1
	v_mfma_f32_16x16x32_bf16 v[126:129], v[130:133], v[174:177], v[126:129]
	v_mfma_f32_16x16x32_bf16 v[122:125], v[138:141], v[174:177], v[122:125]
	v_mfma_f32_16x16x32_bf16 v[110:113], v[130:133], v[190:193], v[110:113]
	v_mfma_f32_16x16x32_bf16 v[106:109], v[138:141], v[190:193], v[106:109]
	v_mfma_f32_16x16x32_bf16 v[94:97], v[130:133], v[198:201], v[94:97]
	v_mfma_f32_16x16x32_bf16 v[90:93], v[138:141], v[198:201], v[90:93]
	v_mfma_f32_16x16x32_bf16 v[78:81], v[130:133], v[206:209], v[78:81]
	v_mfma_f32_16x16x32_bf16 v[74:77], v[138:141], v[206:209], v[74:77]
	v_mfma_f32_16x16x32_bf16 v[126:129], v[134:137], v[178:181], v[126:129]
	v_mfma_f32_16x16x32_bf16 v[122:125], v[142:145], v[178:181], v[122:125]
	v_mfma_f32_16x16x32_bf16 v[110:113], v[134:137], v[194:197], v[110:113]
	v_mfma_f32_16x16x32_bf16 v[106:109], v[142:145], v[194:197], v[106:109]
	v_mfma_f32_16x16x32_bf16 v[94:97], v[134:137], v[202:205], v[94:97]
	v_mfma_f32_16x16x32_bf16 v[90:93], v[142:145], v[202:205], v[90:93]
	v_mfma_f32_16x16x32_bf16 v[78:81], v[134:137], v[210:213], v[78:81]
	v_mfma_f32_16x16x32_bf16 v[74:77], v[142:145], v[210:213], v[74:77]
	v_mfma_f32_16x16x32_bf16 v[118:121], v[146:149], v[174:177], v[118:121]
	v_mfma_f32_16x16x32_bf16 v[114:117], v[166:169], v[174:177], v[114:117]
	v_mfma_f32_16x16x32_bf16 v[102:105], v[146:149], v[190:193], v[102:105]
	v_mfma_f32_16x16x32_bf16 v[98:101], v[166:169], v[190:193], v[98:101]
	v_mfma_f32_16x16x32_bf16 v[86:89], v[146:149], v[198:201], v[86:89]
	v_mfma_f32_16x16x32_bf16 v[82:85], v[166:169], v[198:201], v[82:85]
	v_mfma_f32_16x16x32_bf16 v[70:73], v[146:149], v[206:209], v[70:73]
	v_mfma_f32_16x16x32_bf16 v[66:69], v[166:169], v[206:209], v[66:69]
	v_mfma_f32_16x16x32_bf16 v[118:121], v[150:153], v[178:181], v[118:121]
	v_mfma_f32_16x16x32_bf16 v[114:117], v[170:173], v[178:181], v[114:117]
	v_mfma_f32_16x16x32_bf16 v[102:105], v[150:153], v[194:197], v[102:105]
	v_mfma_f32_16x16x32_bf16 v[98:101], v[170:173], v[194:197], v[98:101]
	v_mfma_f32_16x16x32_bf16 v[86:89], v[150:153], v[202:205], v[86:89]
	v_mfma_f32_16x16x32_bf16 v[82:85], v[170:173], v[202:205], v[82:85]
	v_mfma_f32_16x16x32_bf16 v[70:73], v[150:153], v[210:213], v[70:73]
	v_mfma_f32_16x16x32_bf16 v[66:69], v[170:173], v[210:213], v[66:69]
	s_setprio 0
	s_barrier
	s_add_i32 m0, s30, 0x17f80
	ds_read_b128 v[174:177], v189 offset:49152
	ds_read_b128 v[178:181], v189 offset:50176
	ds_read_b128 v[190:193], v189 offset:51200
	global_load_lds_dwordx4 v0, s[70:71] offset:128
	s_add_i32 m0, s30, 0x19f80
	ds_read_b128 v[194:197], v189 offset:52224
	global_load_lds_dwordx4 v154, s[70:71] offset:128
	s_add_i32 m0, s30, 0x1bf80
	ds_read_b128 v[198:201], v189 offset:53248
	global_load_lds_dwordx4 v0, s[100:101] offset:128
	s_add_i32 m0, s30, 0x1df80
	ds_read_b128 v[202:205], v189 offset:54272
	global_load_lds_dwordx4 v154, s[100:101] offset:128
	s_sub_i32 m0, s60, 0x80
	ds_read_b128 v[206:209], v189 offset:55296
	global_load_lds_dwordx4 v158, s[20:21] offset:128
	s_sub_i32 m0, s61, 0x80
	ds_read_b128 v[210:213], v189 offset:56320
	global_load_lds_dwordx4 v156, s[20:21] offset:128
	s_waitcnt vmcnt(8) lgkmcnt(0)
	s_barrier
	s_setprio 1
	v_mfma_f32_16x16x32_bf16 v[62:65], v[130:133], v[174:177], v[62:65]
	v_mfma_f32_16x16x32_bf16 v[58:61], v[138:141], v[174:177], v[58:61]
	v_mfma_f32_16x16x32_bf16 v[46:49], v[130:133], v[190:193], v[46:49]
	v_mfma_f32_16x16x32_bf16 v[42:45], v[138:141], v[190:193], v[42:45]
	s_add_u32 s8, s8, 0x100
	v_mfma_f32_16x16x32_bf16 v[30:33], v[130:133], v[198:201], v[30:33]
	s_addc_u32 s9, s9, 0
	v_mfma_f32_16x16x32_bf16 v[26:29], v[138:141], v[198:201], v[26:29]
	s_add_u32 s52, s52, 0x100
	v_mfma_f32_16x16x32_bf16 v[14:17], v[130:133], v[206:209], v[14:17]
	s_addc_u32 s53, s53, 0
	v_mfma_f32_16x16x32_bf16 v[10:13], v[138:141], v[206:209], v[10:13]
	s_mov_b32 s20, s69
	v_mfma_f32_16x16x32_bf16 v[62:65], v[134:137], v[178:181], v[62:65]
	v_mfma_f32_16x16x32_bf16 v[58:61], v[142:145], v[178:181], v[58:61]
	v_mfma_f32_16x16x32_bf16 v[46:49], v[134:137], v[194:197], v[46:49]
	v_mfma_f32_16x16x32_bf16 v[42:45], v[142:145], v[194:197], v[42:45]
	v_mfma_f32_16x16x32_bf16 v[30:33], v[134:137], v[202:205], v[30:33]
	v_mfma_f32_16x16x32_bf16 v[26:29], v[142:145], v[202:205], v[26:29]
	v_mfma_f32_16x16x32_bf16 v[14:17], v[134:137], v[210:213], v[14:17]
	v_mfma_f32_16x16x32_bf16 v[10:13], v[142:145], v[210:213], v[10:13]
	v_mfma_f32_16x16x32_bf16 v[54:57], v[146:149], v[174:177], v[54:57]
	v_mfma_f32_16x16x32_bf16 v[50:53], v[166:169], v[174:177], v[50:53]
	v_mfma_f32_16x16x32_bf16 v[38:41], v[146:149], v[190:193], v[38:41]
	v_mfma_f32_16x16x32_bf16 v[34:37], v[166:169], v[190:193], v[34:37]
	v_mfma_f32_16x16x32_bf16 v[22:25], v[146:149], v[198:201], v[22:25]
	v_mfma_f32_16x16x32_bf16 v[18:21], v[166:169], v[198:201], v[18:21]
	v_mfma_f32_16x16x32_bf16 v[6:9], v[146:149], v[206:209], v[6:9]
	v_mfma_f32_16x16x32_bf16 v[2:5], v[166:169], v[206:209], v[2:5]
	v_mfma_f32_16x16x32_bf16 v[54:57], v[150:153], v[178:181], v[54:57]
	v_mfma_f32_16x16x32_bf16 v[50:53], v[170:173], v[178:181], v[50:53]
	v_mfma_f32_16x16x32_bf16 v[38:41], v[150:153], v[194:197], v[38:41]
	v_mfma_f32_16x16x32_bf16 v[34:37], v[170:173], v[194:197], v[34:37]
	v_mfma_f32_16x16x32_bf16 v[22:25], v[150:153], v[202:205], v[22:25]
	v_mfma_f32_16x16x32_bf16 v[18:21], v[170:173], v[202:205], v[18:21]
	v_mfma_f32_16x16x32_bf16 v[6:9], v[150:153], v[210:213], v[6:9]
	v_mfma_f32_16x16x32_bf16 v[2:5], v[170:173], v[210:213], v[2:5]
	s_setprio 0
	s_cmp_ge_i32 s69, s62
	s_barrier
	s_cbranch_scc1 .Lpz_exit_520
; #define PG8_STAGE(bufoff, gbase, voff) do { _Pragma("unroll") for (int _i = 0; _i < 2; ++_i) \
;         __builtin_amdgcn_global_load_lds((const unsigned*)((const char*)(gbase) + (voff)[_i]), (PG8_LAS unsigned*)(lds + (bufoff) + ldsw + _i * 8192), 16, 0, 0); } while (0)
; #define PG8_LDA(dst, b, h) do { _Pragma("unroll") for (int m = 0; m < 4; ++m) _Pragma("unroll") for (int k = 0; k < 2; ++k) dst[m][k] = *(const PG8_LAS bf16x8*)(lds + PG8_SA(b, h) + aoff + m * 2048 + k * 1024); } while (0)
; #define PG8_LDB(dst, b, h) do { _Pragma("unroll") for (int n = 0; n < 2; ++n) _Pragma("unroll") for (int k = 0; k < 2; ++k) dst[n][k] = *(const PG8_LAS bf16x8*)(lds + PG8_SB(b, h) + boff + n * 2048 + k * 1024); } while (0)
; #define PG8_MMA(ai, bj, At, Bt) do { __builtin_amdgcn_s_setprio(1); _Pragma("unroll") for (int m = 0; m < 4; ++m) _Pragma("unroll") for (int n = 0; n < 2; ++n) _Pragma("unroll") for (int k = 0; k < 2; ++k) \
;         acc[ai][bj][m][n] = __builtin_amdgcn_mfma_f32_16x16x32_bf16(Bt[n][k], At[m][k], acc[ai][bj][m][n], 0, 0, 0); __builtin_amdgcn_s_setprio(0); } while (0)
; #define PG8_WAIT_V(n) asm volatile("s_waitcnt vmcnt(" #n ")" ::: "memory")
; #define PG8_WAIT_L(n) asm volatile("s_waitcnt lgkmcnt(" #n ")" ::: "memory")
; #define PG8_BAR __builtin_amdgcn_s_barrier()
; #define PG8_SCHED __builtin_amdgcn_sched_barrier(0)
; template <class Epi, class Sched, bool ALIGN_EPI = false, bool SP2 = false>
; __device__ __forceinline__ void gemm_phase(PG8_LAS unsigned char* lds, const Gemm g, const Sched& S, const Epi& E) {
;     ...
;             PG8_LDB(B0, 0, 0); PG8_LDB(B1, 0, 1); PG8_SCHED; PG8_LDA(At, 0, 0); PG8_STAGE(PG8_SA(1, 1), a1 + hstep, voffA);
;             PG8_WAIT_V(8); PG8_WAIT_L(0); PG8_BAR; PG8_MMA(0, 0, At, B0); PG8_MMA(0, 1, At, B1); PG8_BAR; PG8_SCHED;
;             PG8_LDA(At, 0, 1); PG8_STAGE(PG8_SB(0, 0), b2, voffB); PG8_STAGE(PG8_SB(0, 1), b2 + hstep, voffB); PG8_STAGE(PG8_SA(0, 0), a2, voffA);
;             PG8_WAIT_V(8); PG8_WAIT_L(0); PG8_BAR; PG8_MMA(1, 0, At, B0); PG8_MMA(1, 1, At, B1); PG8_BAR; PG8_SCHED;
.LBB0_520:
	ds_read_b128 v[130:133], v185
	ds_read_b128 v[134:137], v185 offset:1024
	ds_read_b128 v[138:141], v185 offset:2048
	ds_read_b128 v[142:145], v185 offset:3072
	ds_read_b128 v[146:149], v185 offset:16384
	ds_read_b128 v[150:153], v185 offset:17408
	ds_read_b128 v[166:169], v185 offset:18432
	ds_read_b128 v[170:173], v185 offset:19456
	s_add_i32 m0, s56, 0xc000
	ds_read_b128 v[174:177], v189
	ds_read_b128 v[178:181], v189 offset:1024
	ds_read_b128 v[190:193], v189 offset:2048
	ds_read_b128 v[194:197], v189 offset:3072
	ds_read_b128 v[198:201], v189 offset:4096
	ds_read_b128 v[202:205], v189 offset:5120
	ds_read_b128 v[206:209], v189 offset:6144
	global_load_lds_dwordx4 v162, s[8:9]
	s_add_i32 m0, s56, 0xe000
	ds_read_b128 v[210:213], v189 offset:7168
	global_load_lds_dwordx4 v164, s[8:9]
	s_waitcnt vmcnt(8) lgkmcnt(0)
	s_barrier
	s_setprio 1
	v_mfma_f32_16x16x32_bf16 v[126:129], v[130:133], v[174:177], v[126:129]
	v_mfma_f32_16x16x32_bf16 v[122:125], v[138:141], v[174:177], v[122:125]
	v_mfma_f32_16x16x32_bf16 v[110:113], v[130:133], v[190:193], v[110:113]
	v_mfma_f32_16x16x32_bf16 v[106:109], v[138:141], v[190:193], v[106:109]
	s_add_i32 s69, s20, 2
	v_mfma_f32_16x16x32_bf16 v[94:97], v[130:133], v[198:201], v[94:97]
	s_add_u32 s70, s8, 0x80
	v_mfma_f32_16x16x32_bf16 v[90:93], v[138:141], v[198:201], v[90:93]
	s_addc_u32 s21, s9, 0
	v_mfma_f32_16x16x32_bf16 v[78:81], v[130:133], v[206:209], v[78:81]
	s_cmp_eq_u32 s63, s20
	v_mfma_f32_16x16x32_bf16 v[74:77], v[138:141], v[206:209], v[74:77]
	s_cselect_b32 s21, s49, s21
	v_mfma_f32_16x16x32_bf16 v[126:129], v[134:137], v[178:181], v[126:129]
	s_cselect_b32 s20, s48, s70
	v_mfma_f32_16x16x32_bf16 v[122:125], v[142:145], v[178:181], v[122:125]
	s_cselect_b32 s71, s51, s53
	v_mfma_f32_16x16x32_bf16 v[110:113], v[134:137], v[194:197], v[110:113]
	s_cselect_b32 s70, s50, s52
	v_mfma_f32_16x16x32_bf16 v[106:109], v[142:145], v[194:197], v[106:109]
	v_mfma_f32_16x16x32_bf16 v[94:97], v[134:137], v[202:205], v[94:97]
	v_mfma_f32_16x16x32_bf16 v[90:93], v[142:145], v[202:205], v[90:93]
	v_mfma_f32_16x16x32_bf16 v[78:81], v[134:137], v[210:213], v[78:81]
	v_mfma_f32_16x16x32_bf16 v[74:77], v[142:145], v[210:213], v[74:77]
	v_mfma_f32_16x16x32_bf16 v[118:121], v[146:149], v[174:177], v[118:121]
	v_mfma_f32_16x16x32_bf16 v[114:117], v[166:169], v[174:177], v[114:117]
	v_mfma_f32_16x16x32_bf16 v[102:105], v[146:149], v[190:193], v[102:105]
	v_mfma_f32_16x16x32_bf16 v[98:101], v[166:169], v[190:193], v[98:101]
	v_mfma_f32_16x16x32_bf16 v[86:89], v[146:149], v[198:201], v[86:89]
	v_mfma_f32_16x16x32_bf16 v[82:85], v[166:169], v[198:201], v[82:85]
	v_mfma_f32_16x16x32_bf16 v[70:73], v[146:149], v[206:209], v[70:73]
	v_mfma_f32_16x16x32_bf16 v[66:69], v[166:169], v[206:209], v[66:69]
	v_mfma_f32_16x16x32_bf16 v[118:121], v[150:153], v[178:181], v[118:121]
	v_mfma_f32_16x16x32_bf16 v[114:117], v[170:173], v[178:181], v[114:117]
	v_mfma_f32_16x16x32_bf16 v[102:105], v[150:153], v[194:197], v[102:105]
	v_mfma_f32_16x16x32_bf16 v[98:101], v[170:173], v[194:197], v[98:101]
	v_mfma_f32_16x16x32_bf16 v[86:89], v[150:153], v[202:205], v[86:89]
	v_mfma_f32_16x16x32_bf16 v[82:85], v[170:173], v[202:205], v[82:85]
	v_mfma_f32_16x16x32_bf16 v[70:73], v[150:153], v[210:213], v[70:73]
	v_mfma_f32_16x16x32_bf16 v[66:69], v[170:173], v[210:213], v[66:69]
	s_setprio 0
	s_barrier
	s_add_i32 m0, s30, 0x10000
	s_add_u32 s100, s70, s12
	s_addc_u32 s101, s71, s13
	ds_read_b128 v[174:177], v189 offset:16384
	ds_read_b128 v[178:181], v189 offset:17408
	ds_read_b128 v[190:193], v189 offset:18432
	global_load_lds_dwordx4 v0, s[70:71]
	s_add_i32 m0, s30, 0x12000
	ds_read_b128 v[194:197], v189 offset:19456
	global_load_lds_dwordx4 v154, s[70:71]
	s_add_i32 m0, s30, 0x14000
	ds_read_b128 v[198:201], v189 offset:20480
	global_load_lds_dwordx4 v0, s[100:101]
	s_add_i32 m0, s30, 0x16000
	ds_read_b128 v[202:205], v189 offset:21504
	global_load_lds_dwordx4 v154, s[100:101]
	s_mov_b32 m0, s56
	ds_read_b128 v[206:209], v189 offset:22528
	global_load_lds_dwordx4 v158, s[20:21]
	s_mov_b32 m0, s57
	ds_read_b128 v[210:213], v189 offset:23552
	global_load_lds_dwordx4 v156, s[20:21]
	s_waitcnt vmcnt(8) lgkmcnt(0)
	s_barrier
	s_setprio 1
	v_mfma_f32_16x16x32_bf16 v[62:65], v[130:133], v[174:177], v[62:65]
	v_mfma_f32_16x16x32_bf16 v[58:61], v[138:141], v[174:177], v[58:61]
	v_mfma_f32_16x16x32_bf16 v[46:49], v[130:133], v[190:193], v[46:49]
	v_mfma_f32_16x16x32_bf16 v[42:45], v[138:141], v[190:193], v[42:45]
	v_mfma_f32_16x16x32_bf16 v[30:33], v[130:133], v[198:201], v[30:33]
	v_mfma_f32_16x16x32_bf16 v[26:29], v[138:141], v[198:201], v[26:29]
	v_mfma_f32_16x16x32_bf16 v[14:17], v[130:133], v[206:209], v[14:17]
	v_mfma_f32_16x16x32_bf16 v[10:13], v[138:141], v[206:209], v[10:13]
	v_mfma_f32_16x16x32_bf16 v[62:65], v[134:137], v[178:181], v[62:65]
	v_mfma_f32_16x16x32_bf16 v[58:61], v[142:145], v[178:181], v[58:61]
	v_mfma_f32_16x16x32_bf16 v[46:49], v[134:137], v[194:197], v[46:49]
	v_mfma_f32_16x16x32_bf16 v[42:45], v[142:145], v[194:197], v[42:45]
	v_mfma_f32_16x16x32_bf16 v[30:33], v[134:137], v[202:205], v[30:33]
	v_mfma_f32_16x16x32_bf16 v[26:29], v[142:145], v[202:205], v[26:29]
	v_mfma_f32_16x16x32_bf16 v[14:17], v[134:137], v[210:213], v[14:17]
	v_mfma_f32_16x16x32_bf16 v[10:13], v[142:145], v[210:213], v[10:13]
	v_mfma_f32_16x16x32_bf16 v[54:57], v[146:149], v[174:177], v[54:57]
	v_mfma_f32_16x16x32_bf16 v[50:53], v[166:169], v[174:177], v[50:53]
	v_mfma_f32_16x16x32_bf16 v[38:41], v[146:149], v[190:193], v[38:41]
	v_mfma_f32_16x16x32_bf16 v[34:37], v[166:169], v[190:193], v[34:37]
	v_mfma_f32_16x16x32_bf16 v[22:25], v[146:149], v[198:201], v[22:25]
	v_mfma_f32_16x16x32_bf16 v[18:21], v[166:169], v[198:201], v[18:21]
	v_mfma_f32_16x16x32_bf16 v[6:9], v[146:149], v[206:209], v[6:9]
	v_mfma_f32_16x16x32_bf16 v[2:5], v[166:169], v[206:209], v[2:5]
	v_mfma_f32_16x16x32_bf16 v[54:57], v[150:153], v[178:181], v[54:57]
	v_mfma_f32_16x16x32_bf16 v[50:53], v[170:173], v[178:181], v[50:53]
	v_mfma_f32_16x16x32_bf16 v[38:41], v[150:153], v[194:197], v[38:41]
	v_mfma_f32_16x16x32_bf16 v[34:37], v[170:173], v[194:197], v[34:37]
	v_mfma_f32_16x16x32_bf16 v[22:25], v[150:153], v[202:205], v[22:25]
	v_mfma_f32_16x16x32_bf16 v[18:21], v[170:173], v[202:205], v[18:21]
	v_mfma_f32_16x16x32_bf16 v[6:9], v[150:153], v[210:213], v[6:9]
	v_mfma_f32_16x16x32_bf16 v[2:5], v[170:173], v[210:213], v[2:5]
	s_setprio 0
	s_barrier
; #define PG8_STAGE(bufoff, gbase, voff) do { _Pragma("unroll") for (int _i = 0; _i < 2; ++_i) \
;         __builtin_amdgcn_global_load_lds((const unsigned*)((const char*)(gbase) + (voff)[_i]), (PG8_LAS unsigned*)(lds + (bufoff) + ldsw + _i * 8192), 16, 0, 0); } while (0)
; #define PG8_LDA(dst, b, h) do { _Pragma("unroll") for (int m = 0; m < 4; ++m) _Pragma("unroll") for (int k = 0; k < 2; ++k) dst[m][k] = *(const PG8_LAS bf16x8*)(lds + PG8_SA(b, h) + aoff + m * 2048 + k * 1024); } while (0)
; #define PG8_LDB(dst, b, h) do { _Pragma("unroll") for (int n = 0; n < 2; ++n) _Pragma("unroll") for (int k = 0; k < 2; ++k) dst[n][k] = *(const PG8_LAS bf16x8*)(lds + PG8_SB(b, h) + boff + n * 2048 + k * 1024); } while (0)
; #define PG8_MMA(ai, bj, At, Bt) do { __builtin_amdgcn_s_setprio(1); _Pragma("unroll") for (int m = 0; m < 4; ++m) _Pragma("unroll") for (int n = 0; n < 2; ++n) _Pragma("unroll") for (int k = 0; k < 2; ++k) \
;         acc[ai][bj][m][n] = __builtin_amdgcn_mfma_f32_16x16x32_bf16(Bt[n][k], At[m][k], acc[ai][bj][m][n], 0, 0, 0); __builtin_amdgcn_s_setprio(0); } while (0)
; #define PG8_WAIT_V(n) asm volatile("s_waitcnt vmcnt(" #n ")" ::: "memory")
; #define PG8_WAIT_L(n) asm volatile("s_waitcnt lgkmcnt(" #n ")" ::: "memory")
; #define PG8_BAR __builtin_amdgcn_s_barrier()
; #define PG8_SCHED __builtin_amdgcn_sched_barrier(0)
; template <class Epi, class Sched, bool ALIGN_EPI = false, bool SP2 = false>
; __device__ __forceinline__ void gemm_phase(PG8_LAS unsigned char* lds, const Gemm g, const Sched& S, const Epi& E) {
;     ...
;             PG8_LDB(B0, 1, 0); PG8_LDB(B1, 1, 1); PG8_SCHED; PG8_LDA(At, 1, 0); PG8_STAGE(PG8_SA(0, 1), a2 + hstep, voffA);
;             PG8_WAIT_V(8); PG8_WAIT_L(0); PG8_BAR; PG8_MMA(0, 0, At, B0); PG8_MMA(0, 1, At, B1); PG8_BAR; PG8_SCHED;
;             PG8_LDA(At, 1, 1); PG8_STAGE(PG8_SB(1, 0), b3, voffB); PG8_STAGE(PG8_SB(1, 1), b3 + hstep, voffB); PG8_STAGE(PG8_SA(1, 0), a3, voffA);
;             PG8_WAIT_V(8); PG8_WAIT_L(0); PG8_BAR; PG8_MMA(1, 0, At, B0); PG8_MMA(1, 1, At, B1); PG8_BAR; PG8_SCHED;
	ds_read_b128 v[130:133], v185 offset:32768
	ds_read_b128 v[134:137], v185 offset:33792
	ds_read_b128 v[138:141], v185 offset:34816
	ds_read_b128 v[142:145], v185 offset:35840
	ds_read_b128 v[146:149], v185 offset:49152
	ds_read_b128 v[150:153], v185 offset:50176
	ds_read_b128 v[166:169], v185 offset:51200
	ds_read_b128 v[170:173], v185 offset:52224
	s_mov_b32 m0, s58
	ds_read_b128 v[174:177], v189 offset:32768
	ds_read_b128 v[178:181], v189 offset:33792
	ds_read_b128 v[190:193], v189 offset:34816
	ds_read_b128 v[194:197], v189 offset:35840
	ds_read_b128 v[198:201], v189 offset:36864
	ds_read_b128 v[202:205], v189 offset:37888
	ds_read_b128 v[206:209], v189 offset:38912
	global_load_lds_dwordx4 v162, s[20:21]
	s_mov_b32 m0, s59
	ds_read_b128 v[210:213], v189 offset:39936
	global_load_lds_dwordx4 v164, s[20:21]
	s_waitcnt vmcnt(8) lgkmcnt(0)
	s_barrier
	s_setprio 1
	v_mfma_f32_16x16x32_bf16 v[126:129], v[130:133], v[174:177], v[126:129]
	v_mfma_f32_16x16x32_bf16 v[122:125], v[138:141], v[174:177], v[122:125]
	v_mfma_f32_16x16x32_bf16 v[110:113], v[130:133], v[190:193], v[110:113]
	v_mfma_f32_16x16x32_bf16 v[106:109], v[138:141], v[190:193], v[106:109]
	v_mfma_f32_16x16x32_bf16 v[94:97], v[130:133], v[198:201], v[94:97]
	v_mfma_f32_16x16x32_bf16 v[90:93], v[138:141], v[198:201], v[90:93]
	v_mfma_f32_16x16x32_bf16 v[78:81], v[130:133], v[206:209], v[78:81]
	v_mfma_f32_16x16x32_bf16 v[74:77], v[138:141], v[206:209], v[74:77]
	v_mfma_f32_16x16x32_bf16 v[126:129], v[134:137], v[178:181], v[126:129]
	v_mfma_f32_16x16x32_bf16 v[122:125], v[142:145], v[178:181], v[122:125]
	v_mfma_f32_16x16x32_bf16 v[110:113], v[134:137], v[194:197], v[110:113]
	v_mfma_f32_16x16x32_bf16 v[106:109], v[142:145], v[194:197], v[106:109]
	v_mfma_f32_16x16x32_bf16 v[94:97], v[134:137], v[202:205], v[94:97]
	v_mfma_f32_16x16x32_bf16 v[90:93], v[142:145], v[202:205], v[90:93]
	v_mfma_f32_16x16x32_bf16 v[78:81], v[134:137], v[210:213], v[78:81]
	v_mfma_f32_16x16x32_bf16 v[74:77], v[142:145], v[210:213], v[74:77]
	v_mfma_f32_16x16x32_bf16 v[118:121], v[146:149], v[174:177], v[118:121]
	v_mfma_f32_16x16x32_bf16 v[114:117], v[166:169], v[174:177], v[114:117]
	v_mfma_f32_16x16x32_bf16 v[102:105], v[146:149], v[190:193], v[102:105]
	v_mfma_f32_16x16x32_bf16 v[98:101], v[166:169], v[190:193], v[98:101]
	v_mfma_f32_16x16x32_bf16 v[86:89], v[146:149], v[198:201], v[86:89]
	v_mfma_f32_16x16x32_bf16 v[82:85], v[166:169], v[198:201], v[82:85]
	v_mfma_f32_16x16x32_bf16 v[70:73], v[146:149], v[206:209], v[70:73]
	v_mfma_f32_16x16x32_bf16 v[66:69], v[166:169], v[206:209], v[66:69]
	v_mfma_f32_16x16x32_bf16 v[118:121], v[150:153], v[178:181], v[118:121]
	v_mfma_f32_16x16x32_bf16 v[114:117], v[170:173], v[178:181], v[114:117]
	v_mfma_f32_16x16x32_bf16 v[102:105], v[150:153], v[194:197], v[102:105]
	v_mfma_f32_16x16x32_bf16 v[98:101], v[170:173], v[194:197], v[98:101]
	v_mfma_f32_16x16x32_bf16 v[86:89], v[150:153], v[202:205], v[86:89]
	v_mfma_f32_16x16x32_bf16 v[82:85], v[170:173], v[202:205], v[82:85]
	v_mfma_f32_16x16x32_bf16 v[70:73], v[150:153], v[210:213], v[70:73]
	v_mfma_f32_16x16x32_bf16 v[66:69], v[170:173], v[210:213], v[66:69]
	s_setprio 0
	s_barrier
	s_add_i32 m0, s30, 0x17f80
	ds_read_b128 v[174:177], v189 offset:49152
	ds_read_b128 v[178:181], v189 offset:50176
	ds_read_b128 v[190:193], v189 offset:51200
	global_load_lds_dwordx4 v0, s[70:71] offset:128
	s_add_i32 m0, s30, 0x19f80
	ds_read_b128 v[194:197], v189 offset:52224
	global_load_lds_dwordx4 v154, s[70:71] offset:128
	s_add_i32 m0, s30, 0x1bf80
	ds_read_b128 v[198:201], v189 offset:53248
	global_load_lds_dwordx4 v0, s[100:101] offset:128
	s_add_i32 m0, s30, 0x1df80
	ds_read_b128 v[202:205], v189 offset:54272
	global_load_lds_dwordx4 v154, s[100:101] offset:128
	s_sub_i32 m0, s60, 0x80
	ds_read_b128 v[206:209], v189 offset:55296
	global_load_lds_dwordx4 v158, s[20:21] offset:128
	s_sub_i32 m0, s61, 0x80
	ds_read_b128 v[210:213], v189 offset:56320
	global_load_lds_dwordx4 v156, s[20:21] offset:128
	s_waitcnt vmcnt(8) lgkmcnt(0)
	s_barrier
	s_setprio 1
	v_mfma_f32_16x16x32_bf16 v[62:65], v[130:133], v[174:177], v[62:65]
	v_mfma_f32_16x16x32_bf16 v[58:61], v[138:141], v[174:177], v[58:61]
	v_mfma_f32_16x16x32_bf16 v[46:49], v[130:133], v[190:193], v[46:49]
	v_mfma_f32_16x16x32_bf16 v[42:45], v[138:141], v[190:193], v[42:45]
	s_add_u32 s8, s8, 0x100
	v_mfma_f32_16x16x32_bf16 v[30:33], v[130:133], v[198:201], v[30:33]
	s_addc_u32 s9, s9, 0
	v_mfma_f32_16x16x32_bf16 v[26:29], v[138:141], v[198:201], v[26:29]
	s_add_u32 s52, s52, 0x100
	v_mfma_f32_16x16x32_bf16 v[14:17], v[130:133], v[206:209], v[14:17]
	s_addc_u32 s53, s53, 0
	v_mfma_f32_16x16x32_bf16 v[10:13], v[138:141], v[206:209], v[10:13]
	s_mov_b32 s20, s69
	v_mfma_f32_16x16x32_bf16 v[62:65], v[134:137], v[178:181], v[62:65]
	v_mfma_f32_16x16x32_bf16 v[58:61], v[142:145], v[178:181], v[58:61]
	v_mfma_f32_16x16x32_bf16 v[46:49], v[134:137], v[194:197], v[46:49]
	v_mfma_f32_16x16x32_bf16 v[42:45], v[142:145], v[194:197], v[42:45]
	v_mfma_f32_16x16x32_bf16 v[30:33], v[134:137], v[202:205], v[30:33]
	v_mfma_f32_16x16x32_bf16 v[26:29], v[142:145], v[202:205], v[26:29]
	v_mfma_f32_16x16x32_bf16 v[14:17], v[134:137], v[210:213], v[14:17]
	v_mfma_f32_16x16x32_bf16 v[10:13], v[142:145], v[210:213], v[10:13]
	v_mfma_f32_16x16x32_bf16 v[54:57], v[146:149], v[174:177], v[54:57]
	v_mfma_f32_16x16x32_bf16 v[50:53], v[166:169], v[174:177], v[50:53]
	v_mfma_f32_16x16x32_bf16 v[38:41], v[146:149], v[190:193], v[38:41]
	v_mfma_f32_16x16x32_bf16 v[34:37], v[166:169], v[190:193], v[34:37]
	v_mfma_f32_16x16x32_bf16 v[22:25], v[146:149], v[198:201], v[22:25]
	v_mfma_f32_16x16x32_bf16 v[18:21], v[166:169], v[198:201], v[18:21]
	v_mfma_f32_16x16x32_bf16 v[6:9], v[146:149], v[206:209], v[6:9]
	v_mfma_f32_16x16x32_bf16 v[2:5], v[166:169], v[206:209], v[2:5]
	v_mfma_f32_16x16x32_bf16 v[54:57], v[150:153], v[178:181], v[54:57]
	v_mfma_f32_16x16x32_bf16 v[50:53], v[170:173], v[178:181], v[50:53]
	v_mfma_f32_16x16x32_bf16 v[38:41], v[150:153], v[194:197], v[38:41]
	v_mfma_f32_16x16x32_bf16 v[34:37], v[170:173], v[194:197], v[34:37]
	v_mfma_f32_16x16x32_bf16 v[22:25], v[150:153], v[202:205], v[22:25]
	v_mfma_f32_16x16x32_bf16 v[18:21], v[170:173], v[202:205], v[18:21]
	v_mfma_f32_16x16x32_bf16 v[6:9], v[150:153], v[210:213], v[6:9]
	v_mfma_f32_16x16x32_bf16 v[2:5], v[170:173], v[210:213], v[2:5]
	s_setprio 0
	s_cmp_ge_i32 s69, s62
	s_barrier
	s_cbranch_scc0 .LBB0_520

; #define PG8_STAGE(bufoff, gbase, voff) do { _Pragma("unroll") for (int _i = 0; _i < 2; ++_i) \
;         __builtin_amdgcn_global_load_lds((const unsigned*)((const char*)(gbase) + (voff)[_i]), (PG8_LAS unsigned*)(lds + (bufoff) + ldsw + _i * 8192), 16, 0, 0); } while (0)
; #define PG8_LDA(dst, b, h) do { _Pragma("unroll") for (int m = 0; m < 4; ++m) _Pragma("unroll") for (int k = 0; k < 2; ++k) dst[m][k] = *(const PG8_LAS bf16x8*)(lds + PG8_SA(b, h) + aoff + m * 2048 + k * 1024); } while (0)
; #define PG8_LDB(dst, b, h) do { _Pragma("unroll") for (int n = 0; n < 2; ++n) _Pragma("unroll") for (int k = 0; k < 2; ++k) dst[n][k] = *(const PG8_LAS bf16x8*)(lds + PG8_SB(b, h) + boff + n * 2048 + k * 1024); } while (0)
; #define PG8_WAIT_V(n) asm volatile("s_waitcnt vmcnt(" #n ")" ::: "memory")
; #define PG8_WAIT_L(n) asm volatile("s_waitcnt lgkmcnt(" #n ")" ::: "memory")
; #define PG8_BAR __builtin_amdgcn_s_barrier()
; #define PG8_SCHED __builtin_amdgcn_sched_barrier(0)
; template <class Epi, class Sched, bool ALIGN_EPI = false, bool SP2 = false>
; __device__ __forceinline__ void gemm_phase(PG8_LAS unsigned char* lds, const Gemm g, const Sched& S, const Epi& E) {
;     ...
;         const char* nA = has_next ? (const char*)g.A + (size_t)nxt.pm * tstep : cA; const char* nB = has_next ? (const char*)g.Bt + (size_t)nxt.pn * tstep : cB;
;         for (int t = 0; t < nt; t += 2) {
;             const bool last = (t == nt - 2);
;             const char* a1 = cA + (size_t)(t + 1) * kstep;
;             const char* a2 = last ? nA : cA + (size_t)(t + 2) * kstep; const char* b2 = last ? nB : cB + (size_t)(t + 2) * kstep;
;             const char* a3 = a2 + kstep; const char* b3 = b2 + kstep;
;             if (last && has_next) S.a_ready(nxt);
;             if constexpr (SP2) {
;             PG8_LDB(B0, 0, 0); PG8_LDB(B1, 0, 1); PG8_SCHED; PG8_LDA(At, 0, 0); PG8_STAGE(PG8_SA(1, 1), a1 + hstep, voffA);
;             PG8_WAIT_V(8); PG8_WAIT_L(0); PG8_BAR; PG8_MMA(0, 0, At, B0); PG8_MMA(0, 1, At, B1); PG8_BAR; PG8_SCHED;
;             PG8_LDA(At, 0, 1); PG8_STAGE(PG8_SB(0, 0), b2, voffB); PG8_STAGE(PG8_SB(0, 1), b2 + hstep, voffB); PG8_STAGE(PG8_SA(0, 0), a2, voffA);
;             PG8_WAIT_V(8); PG8_WAIT_L(0); PG8_BAR; PG8_MMA(1, 0, At, B0); PG8_MMA(1, 1, At, B1); PG8_BAR; PG8_SCHED;
.Lz_enter_568:
	s_add_u32 s10, s62, 0x80
	s_addc_u32 s11, s63, 0
	s_add_u32 s62, s20, 0x100
	s_addc_u32 s63, s21, 0
	s_mov_b32 s20, 0
	s_add_i32 m0, s64, 0xc000
	ds_read_b128 v[82:85], v246
	global_load_lds_dwordx4 v224, s[10:11]
	s_add_i32 m0, s64, 0xe000
	ds_read_b128 v[98:101], v246 offset:1024
	global_load_lds_dwordx4 v226, s[10:11]
	ds_read_b128 v[102:105], v246 offset:2048
	ds_read_b128 v[106:109], v246 offset:3072
	ds_read_b128 v[146:149], v246 offset:16384
	ds_read_b128 v[150:153], v246 offset:17408
	ds_read_b128 v[154:157], v246 offset:18432
	ds_read_b128 v[158:161], v246 offset:19456
	ds_read_b128 v[162:165], v249
	ds_read_b128 v[166:169], v249 offset:1024
	ds_read_b128 v[170:173], v249 offset:2048
	ds_read_b128 v[174:177], v249 offset:3072
	ds_read_b128 v[178:181], v249 offset:4096
	ds_read_b128 v[182:185], v249 offset:5120
	ds_read_b128 v[186:189], v249 offset:6144
	ds_read_b128 v[190:193], v249 offset:7168
	s_waitcnt vmcnt(8) lgkmcnt(0)
	s_barrier
	s_setprio 1
	v_mfma_f32_16x16x32_bf16 v[142:145], v[82:85], v[162:165], 0
	v_mfma_f32_16x16x32_bf16 v[138:141], v[102:105], v[162:165], 0
	v_mfma_f32_16x16x32_bf16 v[126:129], v[82:85], v[170:173], 0
	v_mfma_f32_16x16x32_bf16 v[122:125], v[102:105], v[170:173], 0
	s_add_i32 s78, s20, 2
	v_mfma_f32_16x16x32_bf16 v[110:113], v[82:85], v[178:181], 0
	s_add_u32 s79, s10, 0x80
	v_mfma_f32_16x16x32_bf16 v[94:97], v[102:105], v[178:181], 0
	s_addc_u32 s21, s11, 0
	v_mfma_f32_16x16x32_bf16 v[78:81], v[82:85], v[186:189], 0
	s_cmp_eq_u32 s68, s20
	v_mfma_f32_16x16x32_bf16 v[74:77], v[102:105], v[186:189], 0
	s_cselect_b32 s21, s59, s21
	v_mfma_f32_16x16x32_bf16 v[142:145], v[98:101], v[166:169], v[142:145]
	s_cselect_b32 s20, s58, s79
	v_mfma_f32_16x16x32_bf16 v[138:141], v[106:109], v[166:169], v[138:141]
	s_cselect_b32 s81, s61, s63
	v_mfma_f32_16x16x32_bf16 v[126:129], v[98:101], v[174:177], v[126:129]
	s_cselect_b32 s80, s60, s62
	v_mfma_f32_16x16x32_bf16 v[122:125], v[106:109], v[174:177], v[122:125]
	v_mfma_f32_16x16x32_bf16 v[110:113], v[98:101], v[182:185], v[110:113]
	v_mfma_f32_16x16x32_bf16 v[94:97], v[106:109], v[182:185], v[94:97]
	v_mfma_f32_16x16x32_bf16 v[78:81], v[98:101], v[190:193], v[78:81]
	v_mfma_f32_16x16x32_bf16 v[74:77], v[106:109], v[190:193], v[74:77]
	v_mfma_f32_16x16x32_bf16 v[134:137], v[146:149], v[162:165], 0
	v_mfma_f32_16x16x32_bf16 v[130:133], v[154:157], v[162:165], 0
	v_mfma_f32_16x16x32_bf16 v[118:121], v[146:149], v[170:173], 0
	v_mfma_f32_16x16x32_bf16 v[114:117], v[154:157], v[170:173], 0
	v_mfma_f32_16x16x32_bf16 v[90:93], v[146:149], v[178:181], 0
	v_mfma_f32_16x16x32_bf16 v[86:89], v[154:157], v[178:181], 0
	v_mfma_f32_16x16x32_bf16 v[70:73], v[146:149], v[186:189], 0
	v_mfma_f32_16x16x32_bf16 v[66:69], v[154:157], v[186:189], 0
	v_mfma_f32_16x16x32_bf16 v[134:137], v[150:153], v[166:169], v[134:137]
	v_mfma_f32_16x16x32_bf16 v[130:133], v[158:161], v[166:169], v[130:133]
	v_mfma_f32_16x16x32_bf16 v[118:121], v[150:153], v[174:177], v[118:121]
	v_mfma_f32_16x16x32_bf16 v[114:117], v[158:161], v[174:177], v[114:117]
	v_mfma_f32_16x16x32_bf16 v[90:93], v[150:153], v[182:185], v[90:93]
	v_mfma_f32_16x16x32_bf16 v[86:89], v[158:161], v[182:185], v[86:89]
	v_mfma_f32_16x16x32_bf16 v[70:73], v[150:153], v[190:193], v[70:73]
	v_mfma_f32_16x16x32_bf16 v[66:69], v[158:161], v[190:193], v[66:69]
	s_setprio 0
	s_barrier
	s_add_u32 s100, s80, s46
	s_addc_u32 s101, s81, s47
	s_add_i32 m0, s22, 0x10000
	ds_read_b128 v[162:165], v249 offset:16384
	global_load_lds_dwordx4 v0, s[80:81]
	s_add_i32 m0, s22, 0x12000
	ds_read_b128 v[166:169], v249 offset:17408
	global_load_lds_dwordx4 v218, s[80:81]
	s_add_i32 m0, s22, 0x14000
	ds_read_b128 v[170:173], v249 offset:18432
	global_load_lds_dwordx4 v0, s[100:101]
	s_add_i32 m0, s22, 0x16000
	ds_read_b128 v[174:177], v249 offset:19456
	global_load_lds_dwordx4 v218, s[100:101]
	s_mov_b32 m0, s64
	ds_read_b128 v[178:181], v249 offset:20480
	global_load_lds_dwordx4 v0, s[20:21]
	s_mov_b32 m0, s30
	ds_read_b128 v[182:185], v249 offset:21504
	global_load_lds_dwordx4 v218, s[20:21]
	ds_read_b128 v[186:189], v249 offset:22528
	ds_read_b128 v[190:193], v249 offset:23552
	s_waitcnt vmcnt(8) lgkmcnt(0)
	s_barrier
	s_setprio 1
	v_mfma_f32_16x16x32_bf16 v[62:65], v[82:85], v[162:165], 0
	v_mfma_f32_16x16x32_bf16 v[58:61], v[102:105], v[162:165], 0
	v_mfma_f32_16x16x32_bf16 v[46:49], v[82:85], v[170:173], 0
	v_mfma_f32_16x16x32_bf16 v[42:45], v[102:105], v[170:173], 0
	v_mfma_f32_16x16x32_bf16 v[30:33], v[82:85], v[178:181], 0
	v_mfma_f32_16x16x32_bf16 v[26:29], v[102:105], v[178:181], 0
	v_mfma_f32_16x16x32_bf16 v[14:17], v[82:85], v[186:189], 0
	v_mfma_f32_16x16x32_bf16 v[10:13], v[102:105], v[186:189], 0
	v_mfma_f32_16x16x32_bf16 v[62:65], v[98:101], v[166:169], v[62:65]
	v_mfma_f32_16x16x32_bf16 v[58:61], v[106:109], v[166:169], v[58:61]
	v_mfma_f32_16x16x32_bf16 v[46:49], v[98:101], v[174:177], v[46:49]
	v_mfma_f32_16x16x32_bf16 v[42:45], v[106:109], v[174:177], v[42:45]
	v_mfma_f32_16x16x32_bf16 v[30:33], v[98:101], v[182:185], v[30:33]
	v_mfma_f32_16x16x32_bf16 v[26:29], v[106:109], v[182:185], v[26:29]
	v_mfma_f32_16x16x32_bf16 v[14:17], v[98:101], v[190:193], v[14:17]
	v_mfma_f32_16x16x32_bf16 v[10:13], v[106:109], v[190:193], v[10:13]
	v_mfma_f32_16x16x32_bf16 v[54:57], v[146:149], v[162:165], 0
	v_mfma_f32_16x16x32_bf16 v[50:53], v[154:157], v[162:165], 0
	v_mfma_f32_16x16x32_bf16 v[38:41], v[146:149], v[170:173], 0
	v_mfma_f32_16x16x32_bf16 v[34:37], v[154:157], v[170:173], 0
	v_mfma_f32_16x16x32_bf16 v[22:25], v[146:149], v[178:181], 0
	v_mfma_f32_16x16x32_bf16 v[18:21], v[154:157], v[178:181], 0
	v_mfma_f32_16x16x32_bf16 v[6:9], v[146:149], v[186:189], 0
	v_mfma_f32_16x16x32_bf16 v[2:5], v[154:157], v[186:189], 0
	v_mfma_f32_16x16x32_bf16 v[54:57], v[150:153], v[166:169], v[54:57]
	v_mfma_f32_16x16x32_bf16 v[50:53], v[158:161], v[166:169], v[50:53]
	v_mfma_f32_16x16x32_bf16 v[38:41], v[150:153], v[174:177], v[38:41]
	v_mfma_f32_16x16x32_bf16 v[34:37], v[158:161], v[174:177], v[34:37]
	v_mfma_f32_16x16x32_bf16 v[22:25], v[150:153], v[182:185], v[22:25]
	v_mfma_f32_16x16x32_bf16 v[18:21], v[158:161], v[182:185], v[18:21]
	v_mfma_f32_16x16x32_bf16 v[6:9], v[150:153], v[190:193], v[6:9]
	v_mfma_f32_16x16x32_bf16 v[2:5], v[158:161], v[190:193], v[2:5]
	s_setprio 0
	s_barrier
; #define PG8_STAGE(bufoff, gbase, voff) do { _Pragma("unroll") for (int _i = 0; _i < 2; ++_i) \
;         __builtin_amdgcn_global_load_lds((const unsigned*)((const char*)(gbase) + (voff)[_i]), (PG8_LAS unsigned*)(lds + (bufoff) + ldsw + _i * 8192), 16, 0, 0); } while (0)
; #define PG8_LDA(dst, b, h) do { _Pragma("unroll") for (int m = 0; m < 4; ++m) _Pragma("unroll") for (int k = 0; k < 2; ++k) dst[m][k] = *(const PG8_LAS bf16x8*)(lds + PG8_SA(b, h) + aoff + m * 2048 + k * 1024); } while (0)
; #define PG8_LDB(dst, b, h) do { _Pragma("unroll") for (int n = 0; n < 2; ++n) _Pragma("unroll") for (int k = 0; k < 2; ++k) dst[n][k] = *(const PG8_LAS bf16x8*)(lds + PG8_SB(b, h) + boff + n * 2048 + k * 1024); } while (0)
; #define PG8_MMA(ai, bj, At, Bt) do { __builtin_amdgcn_s_setprio(1); _Pragma("unroll") for (int m = 0; m < 4; ++m) _Pragma("unroll") for (int n = 0; n < 2; ++n) _Pragma("unroll") for (int k = 0; k < 2; ++k) \
;         acc[ai][bj][m][n] = __builtin_amdgcn_mfma_f32_16x16x32_bf16(Bt[n][k], At[m][k], acc[ai][bj][m][n], 0, 0, 0); __builtin_amdgcn_s_setprio(0); } while (0)
; #define PG8_WAIT_V(n) asm volatile("s_waitcnt vmcnt(" #n ")" ::: "memory")
; #define PG8_WAIT_L(n) asm volatile("s_waitcnt lgkmcnt(" #n ")" ::: "memory")
; #define PG8_BAR __builtin_amdgcn_s_barrier()
; #define PG8_SCHED __builtin_amdgcn_sched_barrier(0)
; template <class Epi, class Sched, bool ALIGN_EPI = false, bool SP2 = false>
; __device__ __forceinline__ void gemm_phase(PG8_LAS unsigned char* lds, const Gemm g, const Sched& S, const Epi& E) {
;     ...
;             PG8_LDB(B0, 1, 0); PG8_LDB(B1, 1, 1); PG8_SCHED; PG8_LDA(At, 1, 0); PG8_STAGE(PG8_SA(0, 1), a2 + hstep, voffA);
;             PG8_WAIT_V(8); PG8_WAIT_L(0); PG8_BAR; PG8_MMA(0, 0, At, B0); PG8_MMA(0, 1, At, B1); PG8_BAR; PG8_SCHED;
;             PG8_LDA(At, 1, 1); PG8_STAGE(PG8_SB(1, 0), b3, voffB); PG8_STAGE(PG8_SB(1, 1), b3 + hstep, voffB); PG8_STAGE(PG8_SA(1, 0), a3, voffA);
;             PG8_WAIT_V(8); PG8_WAIT_L(0); PG8_BAR; PG8_MMA(1, 0, At, B0); PG8_MMA(1, 1, At, B1); PG8_BAR; PG8_SCHED;
	s_mov_b32 m0, s31
	ds_read_b128 v[82:85], v246 offset:32768
	global_load_lds_dwordx4 v224, s[20:21]
	s_mov_b32 m0, s33
	ds_read_b128 v[98:101], v246 offset:33792
	global_load_lds_dwordx4 v226, s[20:21]
	ds_read_b128 v[102:105], v246 offset:34816
	ds_read_b128 v[106:109], v246 offset:35840
	ds_read_b128 v[146:149], v246 offset:49152
	ds_read_b128 v[150:153], v246 offset:50176
	ds_read_b128 v[154:157], v246 offset:51200
	ds_read_b128 v[158:161], v246 offset:52224
	ds_read_b128 v[162:165], v249 offset:32768
	ds_read_b128 v[166:169], v249 offset:33792
	ds_read_b128 v[170:173], v249 offset:34816
	ds_read_b128 v[174:177], v249 offset:35840
	ds_read_b128 v[178:181], v249 offset:36864
	ds_read_b128 v[182:185], v249 offset:37888
	ds_read_b128 v[186:189], v249 offset:38912
	ds_read_b128 v[190:193], v249 offset:39936
	s_waitcnt vmcnt(8) lgkmcnt(0)
	s_barrier
	s_setprio 1
	v_mfma_f32_16x16x32_bf16 v[142:145], v[82:85], v[162:165], v[142:145]
	v_mfma_f32_16x16x32_bf16 v[138:141], v[102:105], v[162:165], v[138:141]
	v_mfma_f32_16x16x32_bf16 v[126:129], v[82:85], v[170:173], v[126:129]
	v_mfma_f32_16x16x32_bf16 v[122:125], v[102:105], v[170:173], v[122:125]
	v_mfma_f32_16x16x32_bf16 v[110:113], v[82:85], v[178:181], v[110:113]
	v_mfma_f32_16x16x32_bf16 v[94:97], v[102:105], v[178:181], v[94:97]
	v_mfma_f32_16x16x32_bf16 v[78:81], v[82:85], v[186:189], v[78:81]
	v_mfma_f32_16x16x32_bf16 v[74:77], v[102:105], v[186:189], v[74:77]
	v_mfma_f32_16x16x32_bf16 v[142:145], v[98:101], v[166:169], v[142:145]
	v_mfma_f32_16x16x32_bf16 v[138:141], v[106:109], v[166:169], v[138:141]
	v_mfma_f32_16x16x32_bf16 v[126:129], v[98:101], v[174:177], v[126:129]
	v_mfma_f32_16x16x32_bf16 v[122:125], v[106:109], v[174:177], v[122:125]
	v_mfma_f32_16x16x32_bf16 v[110:113], v[98:101], v[182:185], v[110:113]
	v_mfma_f32_16x16x32_bf16 v[94:97], v[106:109], v[182:185], v[94:97]
	v_mfma_f32_16x16x32_bf16 v[78:81], v[98:101], v[190:193], v[78:81]
	v_mfma_f32_16x16x32_bf16 v[74:77], v[106:109], v[190:193], v[74:77]
	v_mfma_f32_16x16x32_bf16 v[134:137], v[146:149], v[162:165], v[134:137]
	v_mfma_f32_16x16x32_bf16 v[130:133], v[154:157], v[162:165], v[130:133]
	v_mfma_f32_16x16x32_bf16 v[118:121], v[146:149], v[170:173], v[118:121]
	v_mfma_f32_16x16x32_bf16 v[114:117], v[154:157], v[170:173], v[114:117]
	v_mfma_f32_16x16x32_bf16 v[90:93], v[146:149], v[178:181], v[90:93]
	v_mfma_f32_16x16x32_bf16 v[86:89], v[154:157], v[178:181], v[86:89]
	v_mfma_f32_16x16x32_bf16 v[70:73], v[146:149], v[186:189], v[70:73]
	v_mfma_f32_16x16x32_bf16 v[66:69], v[154:157], v[186:189], v[66:69]
	v_mfma_f32_16x16x32_bf16 v[134:137], v[150:153], v[166:169], v[134:137]
	v_mfma_f32_16x16x32_bf16 v[130:133], v[158:161], v[166:169], v[130:133]
	v_mfma_f32_16x16x32_bf16 v[118:121], v[150:153], v[174:177], v[118:121]
	v_mfma_f32_16x16x32_bf16 v[114:117], v[158:161], v[174:177], v[114:117]
	v_mfma_f32_16x16x32_bf16 v[90:93], v[150:153], v[182:185], v[90:93]
	v_mfma_f32_16x16x32_bf16 v[86:89], v[158:161], v[182:185], v[86:89]
	v_mfma_f32_16x16x32_bf16 v[70:73], v[150:153], v[190:193], v[70:73]
	v_mfma_f32_16x16x32_bf16 v[66:69], v[158:161], v[190:193], v[66:69]
	s_setprio 0
	s_barrier
	s_add_i32 m0, s22, 0x17f80
	ds_read_b128 v[162:165], v249 offset:49152
	global_load_lds_dwordx4 v0, s[80:81] offset:128
	s_add_i32 m0, s22, 0x19f80
	ds_read_b128 v[166:169], v249 offset:50176
	global_load_lds_dwordx4 v218, s[80:81] offset:128
	s_add_i32 m0, s22, 0x1bf80
	ds_read_b128 v[170:173], v249 offset:51200
	global_load_lds_dwordx4 v0, s[100:101] offset:128
	s_add_i32 m0, s22, 0x1df80
	ds_read_b128 v[174:177], v249 offset:52224
	global_load_lds_dwordx4 v218, s[100:101] offset:128
	s_sub_i32 m0, s39, 0x80
	ds_read_b128 v[178:181], v249 offset:53248
	global_load_lds_dwordx4 v0, s[20:21] offset:128
	s_sub_i32 m0, s65, 0x80
	ds_read_b128 v[182:185], v249 offset:54272
	global_load_lds_dwordx4 v218, s[20:21] offset:128
	ds_read_b128 v[186:189], v249 offset:55296
	ds_read_b128 v[190:193], v249 offset:56320
	s_waitcnt vmcnt(8) lgkmcnt(0)
	s_barrier
	s_setprio 1
	v_mfma_f32_16x16x32_bf16 v[62:65], v[82:85], v[162:165], v[62:65]
	v_mfma_f32_16x16x32_bf16 v[58:61], v[102:105], v[162:165], v[58:61]
	v_mfma_f32_16x16x32_bf16 v[46:49], v[82:85], v[170:173], v[46:49]
	v_mfma_f32_16x16x32_bf16 v[42:45], v[102:105], v[170:173], v[42:45]
	s_add_u32 s10, s10, 0x100
	v_mfma_f32_16x16x32_bf16 v[30:33], v[82:85], v[178:181], v[30:33]
	s_addc_u32 s11, s11, 0
	v_mfma_f32_16x16x32_bf16 v[26:29], v[102:105], v[178:181], v[26:29]
	s_add_u32 s62, s62, 0x100
	v_mfma_f32_16x16x32_bf16 v[14:17], v[82:85], v[186:189], v[14:17]
	s_addc_u32 s63, s63, 0
	v_mfma_f32_16x16x32_bf16 v[10:13], v[102:105], v[186:189], v[10:13]
	s_mov_b32 s20, s78
	v_mfma_f32_16x16x32_bf16 v[62:65], v[98:101], v[166:169], v[62:65]
	v_mfma_f32_16x16x32_bf16 v[58:61], v[106:109], v[166:169], v[58:61]
	v_mfma_f32_16x16x32_bf16 v[46:49], v[98:101], v[174:177], v[46:49]
	v_mfma_f32_16x16x32_bf16 v[42:45], v[106:109], v[174:177], v[42:45]
	v_mfma_f32_16x16x32_bf16 v[30:33], v[98:101], v[182:185], v[30:33]
	v_mfma_f32_16x16x32_bf16 v[26:29], v[106:109], v[182:185], v[26:29]
	v_mfma_f32_16x16x32_bf16 v[14:17], v[98:101], v[190:193], v[14:17]
	v_mfma_f32_16x16x32_bf16 v[10:13], v[106:109], v[190:193], v[10:13]
	v_mfma_f32_16x16x32_bf16 v[54:57], v[146:149], v[162:165], v[54:57]
	v_mfma_f32_16x16x32_bf16 v[50:53], v[154:157], v[162:165], v[50:53]
	v_mfma_f32_16x16x32_bf16 v[38:41], v[146:149], v[170:173], v[38:41]
	v_mfma_f32_16x16x32_bf16 v[34:37], v[154:157], v[170:173], v[34:37]
	v_mfma_f32_16x16x32_bf16 v[22:25], v[146:149], v[178:181], v[22:25]
	v_mfma_f32_16x16x32_bf16 v[18:21], v[154:157], v[178:181], v[18:21]
	v_mfma_f32_16x16x32_bf16 v[6:9], v[146:149], v[186:189], v[6:9]
	v_mfma_f32_16x16x32_bf16 v[2:5], v[154:157], v[186:189], v[2:5]
	v_mfma_f32_16x16x32_bf16 v[54:57], v[150:153], v[166:169], v[54:57]
	v_mfma_f32_16x16x32_bf16 v[50:53], v[158:161], v[166:169], v[50:53]
	v_mfma_f32_16x16x32_bf16 v[38:41], v[150:153], v[174:177], v[38:41]
	v_mfma_f32_16x16x32_bf16 v[34:37], v[158:161], v[174:177], v[34:37]
	v_mfma_f32_16x16x32_bf16 v[22:25], v[150:153], v[182:185], v[22:25]
	v_mfma_f32_16x16x32_bf16 v[18:21], v[158:161], v[182:185], v[18:21]
	v_mfma_f32_16x16x32_bf16 v[6:9], v[150:153], v[190:193], v[6:9]
	v_mfma_f32_16x16x32_bf16 v[2:5], v[158:161], v[190:193], v[2:5]
	s_setprio 0
	s_cmp_ge_i32 s78, s67
	s_barrier
	s_cbranch_scc1 .Lpz_exit_570
	s_nop 0
; #define PG8_STAGE(bufoff, gbase, voff) do { _Pragma("unroll") for (int _i = 0; _i < 2; ++_i) \
;         __builtin_amdgcn_global_load_lds((const unsigned*)((const char*)(gbase) + (voff)[_i]), (PG8_LAS unsigned*)(lds + (bufoff) + ldsw + _i * 8192), 16, 0, 0); } while (0)
; #define PG8_LDA(dst, b, h) do { _Pragma("unroll") for (int m = 0; m < 4; ++m) _Pragma("unroll") for (int k = 0; k < 2; ++k) dst[m][k] = *(const PG8_LAS bf16x8*)(lds + PG8_SA(b, h) + aoff + m * 2048 + k * 1024); } while (0)
; #define PG8_LDB(dst, b, h) do { _Pragma("unroll") for (int n = 0; n < 2; ++n) _Pragma("unroll") for (int k = 0; k < 2; ++k) dst[n][k] = *(const PG8_LAS bf16x8*)(lds + PG8_SB(b, h) + boff + n * 2048 + k * 1024); } while (0)
; #define PG8_MMA(ai, bj, At, Bt) do { __builtin_amdgcn_s_setprio(1); _Pragma("unroll") for (int m = 0; m < 4; ++m) _Pragma("unroll") for (int n = 0; n < 2; ++n) _Pragma("unroll") for (int k = 0; k < 2; ++k) \
;         acc[ai][bj][m][n] = __builtin_amdgcn_mfma_f32_16x16x32_bf16(Bt[n][k], At[m][k], acc[ai][bj][m][n], 0, 0, 0); __builtin_amdgcn_s_setprio(0); } while (0)
; #define PG8_WAIT_V(n) asm volatile("s_waitcnt vmcnt(" #n ")" ::: "memory")
; #define PG8_BAR __builtin_amdgcn_s_barrier()
; template <class Epi, class Sched, bool ALIGN_EPI = false, bool SP2 = false>
; __device__ __forceinline__ void gemm_phase(PG8_LAS unsigned char* lds, const Gemm g, const Sched& S, const Epi& E) {
;     ...
;         for (int t = 0; t < nt; t += 2) {
;             const bool last = (t == nt - 2);
;             const char* a1 = cA + (size_t)(t + 1) * kstep;
;             const char* a2 = last ? nA : cA + (size_t)(t + 2) * kstep; const char* b2 = last ? nB : cB + (size_t)(t + 2) * kstep;
;             const char* a3 = a2 + kstep; const char* b3 = b2 + kstep;
;             if (last && has_next) S.a_ready(nxt);
;             if constexpr (SP2) {
;             PG8_LDB(B0, 0, 0); PG8_LDB(B1, 0, 1); PG8_SCHED; PG8_LDA(At, 0, 0); PG8_STAGE(PG8_SA(1, 1), a1 + hstep, voffA);
;             PG8_WAIT_V(8); PG8_WAIT_L(0); PG8_BAR; PG8_MMA(0, 0, At, B0); PG8_MMA(0, 1, At, B1); PG8_BAR; PG8_SCHED;
;             PG8_LDA(At, 0, 1); PG8_STAGE(PG8_SB(0, 0), b2, voffB); PG8_STAGE(PG8_SB(0, 1), b2 + hstep, voffB); PG8_STAGE(PG8_SA(0, 0), a2, voffA);
;             PG8_WAIT_V(8); PG8_WAIT_L(0); PG8_BAR; PG8_MMA(1, 0, At, B0); PG8_MMA(1, 1, At, B1); PG8_BAR; PG8_SCHED;
.LBB0_570:
	s_add_i32 m0, s64, 0xc000
	ds_read_b128 v[82:85], v246
	global_load_lds_dwordx4 v224, s[10:11]
	s_add_i32 m0, s64, 0xe000
	ds_read_b128 v[98:101], v246 offset:1024
	global_load_lds_dwordx4 v226, s[10:11]
	ds_read_b128 v[102:105], v246 offset:2048
	ds_read_b128 v[106:109], v246 offset:3072
	ds_read_b128 v[146:149], v246 offset:16384
	ds_read_b128 v[150:153], v246 offset:17408
	ds_read_b128 v[154:157], v246 offset:18432
	ds_read_b128 v[158:161], v246 offset:19456
	ds_read_b128 v[162:165], v249
	ds_read_b128 v[166:169], v249 offset:1024
	ds_read_b128 v[170:173], v249 offset:2048
	ds_read_b128 v[174:177], v249 offset:3072
	ds_read_b128 v[178:181], v249 offset:4096
	ds_read_b128 v[182:185], v249 offset:5120
	ds_read_b128 v[186:189], v249 offset:6144
	ds_read_b128 v[190:193], v249 offset:7168
	s_waitcnt vmcnt(8) lgkmcnt(0)
	s_barrier
	s_setprio 1
	v_mfma_f32_16x16x32_bf16 v[142:145], v[82:85], v[162:165], v[142:145]
	v_mfma_f32_16x16x32_bf16 v[138:141], v[102:105], v[162:165], v[138:141]
	v_mfma_f32_16x16x32_bf16 v[126:129], v[82:85], v[170:173], v[126:129]
	v_mfma_f32_16x16x32_bf16 v[122:125], v[102:105], v[170:173], v[122:125]
	s_add_i32 s78, s20, 2
	v_mfma_f32_16x16x32_bf16 v[110:113], v[82:85], v[178:181], v[110:113]
	s_add_u32 s79, s10, 0x80
	v_mfma_f32_16x16x32_bf16 v[94:97], v[102:105], v[178:181], v[94:97]
	s_addc_u32 s21, s11, 0
	v_mfma_f32_16x16x32_bf16 v[78:81], v[82:85], v[186:189], v[78:81]
	s_cmp_eq_u32 s68, s20
	v_mfma_f32_16x16x32_bf16 v[74:77], v[102:105], v[186:189], v[74:77]
	s_cselect_b32 s21, s59, s21
	v_mfma_f32_16x16x32_bf16 v[142:145], v[98:101], v[166:169], v[142:145]
	s_cselect_b32 s20, s58, s79
	v_mfma_f32_16x16x32_bf16 v[138:141], v[106:109], v[166:169], v[138:141]
	s_cselect_b32 s81, s61, s63
	v_mfma_f32_16x16x32_bf16 v[126:129], v[98:101], v[174:177], v[126:129]
	s_cselect_b32 s80, s60, s62
	v_mfma_f32_16x16x32_bf16 v[122:125], v[106:109], v[174:177], v[122:125]
	v_mfma_f32_16x16x32_bf16 v[110:113], v[98:101], v[182:185], v[110:113]
	v_mfma_f32_16x16x32_bf16 v[94:97], v[106:109], v[182:185], v[94:97]
	v_mfma_f32_16x16x32_bf16 v[78:81], v[98:101], v[190:193], v[78:81]
	v_mfma_f32_16x16x32_bf16 v[74:77], v[106:109], v[190:193], v[74:77]
	v_mfma_f32_16x16x32_bf16 v[134:137], v[146:149], v[162:165], v[134:137]
	v_mfma_f32_16x16x32_bf16 v[130:133], v[154:157], v[162:165], v[130:133]
	v_mfma_f32_16x16x32_bf16 v[118:121], v[146:149], v[170:173], v[118:121]
	v_mfma_f32_16x16x32_bf16 v[114:117], v[154:157], v[170:173], v[114:117]
	v_mfma_f32_16x16x32_bf16 v[90:93], v[146:149], v[178:181], v[90:93]
	v_mfma_f32_16x16x32_bf16 v[86:89], v[154:157], v[178:181], v[86:89]
	v_mfma_f32_16x16x32_bf16 v[70:73], v[146:149], v[186:189], v[70:73]
	v_mfma_f32_16x16x32_bf16 v[66:69], v[154:157], v[186:189], v[66:69]
	v_mfma_f32_16x16x32_bf16 v[134:137], v[150:153], v[166:169], v[134:137]
	v_mfma_f32_16x16x32_bf16 v[130:133], v[158:161], v[166:169], v[130:133]
	v_mfma_f32_16x16x32_bf16 v[118:121], v[150:153], v[174:177], v[118:121]
	v_mfma_f32_16x16x32_bf16 v[114:117], v[158:161], v[174:177], v[114:117]
	v_mfma_f32_16x16x32_bf16 v[90:93], v[150:153], v[182:185], v[90:93]
	v_mfma_f32_16x16x32_bf16 v[86:89], v[158:161], v[182:185], v[86:89]
	v_mfma_f32_16x16x32_bf16 v[70:73], v[150:153], v[190:193], v[70:73]
	v_mfma_f32_16x16x32_bf16 v[66:69], v[158:161], v[190:193], v[66:69]
	s_setprio 0
	s_barrier
	s_add_u32 s100, s80, s46
	s_addc_u32 s101, s81, s47
	s_add_i32 m0, s22, 0x10000
	ds_read_b128 v[162:165], v249 offset:16384
	global_load_lds_dwordx4 v0, s[80:81]
	s_add_i32 m0, s22, 0x12000
	ds_read_b128 v[166:169], v249 offset:17408
	global_load_lds_dwordx4 v218, s[80:81]
	s_add_i32 m0, s22, 0x14000
	ds_read_b128 v[170:173], v249 offset:18432
	global_load_lds_dwordx4 v0, s[100:101]
	s_add_i32 m0, s22, 0x16000
	ds_read_b128 v[174:177], v249 offset:19456
	global_load_lds_dwordx4 v218, s[100:101]
	s_mov_b32 m0, s64
	ds_read_b128 v[178:181], v249 offset:20480
	global_load_lds_dwordx4 v0, s[20:21]
	s_mov_b32 m0, s30
	ds_read_b128 v[182:185], v249 offset:21504
	global_load_lds_dwordx4 v218, s[20:21]
	ds_read_b128 v[186:189], v249 offset:22528
	ds_read_b128 v[190:193], v249 offset:23552
	s_waitcnt vmcnt(8) lgkmcnt(0)
	s_barrier
	s_setprio 1
	v_mfma_f32_16x16x32_bf16 v[62:65], v[82:85], v[162:165], v[62:65]
	v_mfma_f32_16x16x32_bf16 v[58:61], v[102:105], v[162:165], v[58:61]
	v_mfma_f32_16x16x32_bf16 v[46:49], v[82:85], v[170:173], v[46:49]
	v_mfma_f32_16x16x32_bf16 v[42:45], v[102:105], v[170:173], v[42:45]
	v_mfma_f32_16x16x32_bf16 v[30:33], v[82:85], v[178:181], v[30:33]
	v_mfma_f32_16x16x32_bf16 v[26:29], v[102:105], v[178:181], v[26:29]
	v_mfma_f32_16x16x32_bf16 v[14:17], v[82:85], v[186:189], v[14:17]
	v_mfma_f32_16x16x32_bf16 v[10:13], v[102:105], v[186:189], v[10:13]
	v_mfma_f32_16x16x32_bf16 v[62:65], v[98:101], v[166:169], v[62:65]
	v_mfma_f32_16x16x32_bf16 v[58:61], v[106:109], v[166:169], v[58:61]
	v_mfma_f32_16x16x32_bf16 v[46:49], v[98:101], v[174:177], v[46:49]
	v_mfma_f32_16x16x32_bf16 v[42:45], v[106:109], v[174:177], v[42:45]
	v_mfma_f32_16x16x32_bf16 v[30:33], v[98:101], v[182:185], v[30:33]
	v_mfma_f32_16x16x32_bf16 v[26:29], v[106:109], v[182:185], v[26:29]
	v_mfma_f32_16x16x32_bf16 v[14:17], v[98:101], v[190:193], v[14:17]
	v_mfma_f32_16x16x32_bf16 v[10:13], v[106:109], v[190:193], v[10:13]
	v_mfma_f32_16x16x32_bf16 v[54:57], v[146:149], v[162:165], v[54:57]
	v_mfma_f32_16x16x32_bf16 v[50:53], v[154:157], v[162:165], v[50:53]
	v_mfma_f32_16x16x32_bf16 v[38:41], v[146:149], v[170:173], v[38:41]
	v_mfma_f32_16x16x32_bf16 v[34:37], v[154:157], v[170:173], v[34:37]
	v_mfma_f32_16x16x32_bf16 v[22:25], v[146:149], v[178:181], v[22:25]
	v_mfma_f32_16x16x32_bf16 v[18:21], v[154:157], v[178:181], v[18:21]
	v_mfma_f32_16x16x32_bf16 v[6:9], v[146:149], v[186:189], v[6:9]
	v_mfma_f32_16x16x32_bf16 v[2:5], v[154:157], v[186:189], v[2:5]
	v_mfma_f32_16x16x32_bf16 v[54:57], v[150:153], v[166:169], v[54:57]
	v_mfma_f32_16x16x32_bf16 v[50:53], v[158:161], v[166:169], v[50:53]
	v_mfma_f32_16x16x32_bf16 v[38:41], v[150:153], v[174:177], v[38:41]
	v_mfma_f32_16x16x32_bf16 v[34:37], v[158:161], v[174:177], v[34:37]
	v_mfma_f32_16x16x32_bf16 v[22:25], v[150:153], v[182:185], v[22:25]
	v_mfma_f32_16x16x32_bf16 v[18:21], v[158:161], v[182:185], v[18:21]
	v_mfma_f32_16x16x32_bf16 v[6:9], v[150:153], v[190:193], v[6:9]
	v_mfma_f32_16x16x32_bf16 v[2:5], v[158:161], v[190:193], v[2:5]
	s_setprio 0
	s_barrier
; #define PG8_STAGE(bufoff, gbase, voff) do { _Pragma("unroll") for (int _i = 0; _i < 2; ++_i) \
;         __builtin_amdgcn_global_load_lds((const unsigned*)((const char*)(gbase) + (voff)[_i]), (PG8_LAS unsigned*)(lds + (bufoff) + ldsw + _i * 8192), 16, 0, 0); } while (0)
; #define PG8_LDA(dst, b, h) do { _Pragma("unroll") for (int m = 0; m < 4; ++m) _Pragma("unroll") for (int k = 0; k < 2; ++k) dst[m][k] = *(const PG8_LAS bf16x8*)(lds + PG8_SA(b, h) + aoff + m * 2048 + k * 1024); } while (0)
; #define PG8_LDB(dst, b, h) do { _Pragma("unroll") for (int n = 0; n < 2; ++n) _Pragma("unroll") for (int k = 0; k < 2; ++k) dst[n][k] = *(const PG8_LAS bf16x8*)(lds + PG8_SB(b, h) + boff + n * 2048 + k * 1024); } while (0)
; #define PG8_MMA(ai, bj, At, Bt) do { __builtin_amdgcn_s_setprio(1); _Pragma("unroll") for (int m = 0; m < 4; ++m) _Pragma("unroll") for (int n = 0; n < 2; ++n) _Pragma("unroll") for (int k = 0; k < 2; ++k) \
;         acc[ai][bj][m][n] = __builtin_amdgcn_mfma_f32_16x16x32_bf16(Bt[n][k], At[m][k], acc[ai][bj][m][n], 0, 0, 0); __builtin_amdgcn_s_setprio(0); } while (0)
; #define PG8_WAIT_V(n) asm volatile("s_waitcnt vmcnt(" #n ")" ::: "memory")
; #define PG8_WAIT_L(n) asm volatile("s_waitcnt lgkmcnt(" #n ")" ::: "memory")
; #define PG8_BAR __builtin_amdgcn_s_barrier()
; #define PG8_SCHED __builtin_amdgcn_sched_barrier(0)
; template <class Epi, class Sched, bool ALIGN_EPI = false, bool SP2 = false>
; __device__ __forceinline__ void gemm_phase(PG8_LAS unsigned char* lds, const Gemm g, const Sched& S, const Epi& E) {
;     ...
;             PG8_LDB(B0, 1, 0); PG8_LDB(B1, 1, 1); PG8_SCHED; PG8_LDA(At, 1, 0); PG8_STAGE(PG8_SA(0, 1), a2 + hstep, voffA);
;             PG8_WAIT_V(8); PG8_WAIT_L(0); PG8_BAR; PG8_MMA(0, 0, At, B0); PG8_MMA(0, 1, At, B1); PG8_BAR; PG8_SCHED;
;             PG8_LDA(At, 1, 1); PG8_STAGE(PG8_SB(1, 0), b3, voffB); PG8_STAGE(PG8_SB(1, 1), b3 + hstep, voffB); PG8_STAGE(PG8_SA(1, 0), a3, voffA);
;             PG8_WAIT_V(8); PG8_WAIT_L(0); PG8_BAR; PG8_MMA(1, 0, At, B0); PG8_MMA(1, 1, At, B1); PG8_BAR; PG8_SCHED;
	s_mov_b32 m0, s31
	ds_read_b128 v[82:85], v246 offset:32768
	global_load_lds_dwordx4 v224, s[20:21]
	s_mov_b32 m0, s33
	ds_read_b128 v[98:101], v246 offset:33792
	global_load_lds_dwordx4 v226, s[20:21]
	ds_read_b128 v[102:105], v246 offset:34816
	ds_read_b128 v[106:109], v246 offset:35840
	ds_read_b128 v[146:149], v246 offset:49152
	ds_read_b128 v[150:153], v246 offset:50176
	ds_read_b128 v[154:157], v246 offset:51200
	ds_read_b128 v[158:161], v246 offset:52224
	ds_read_b128 v[162:165], v249 offset:32768
	ds_read_b128 v[166:169], v249 offset:33792
	ds_read_b128 v[170:173], v249 offset:34816
	ds_read_b128 v[174:177], v249 offset:35840
	ds_read_b128 v[178:181], v249 offset:36864
	ds_read_b128 v[182:185], v249 offset:37888
	ds_read_b128 v[186:189], v249 offset:38912
	ds_read_b128 v[190:193], v249 offset:39936
	s_waitcnt vmcnt(8) lgkmcnt(0)
	s_barrier
	s_setprio 1
	v_mfma_f32_16x16x32_bf16 v[142:145], v[82:85], v[162:165], v[142:145]
	v_mfma_f32_16x16x32_bf16 v[138:141], v[102:105], v[162:165], v[138:141]
	v_mfma_f32_16x16x32_bf16 v[126:129], v[82:85], v[170:173], v[126:129]
	v_mfma_f32_16x16x32_bf16 v[122:125], v[102:105], v[170:173], v[122:125]
	v_mfma_f32_16x16x32_bf16 v[110:113], v[82:85], v[178:181], v[110:113]
	v_mfma_f32_16x16x32_bf16 v[94:97], v[102:105], v[178:181], v[94:97]
	v_mfma_f32_16x16x32_bf16 v[78:81], v[82:85], v[186:189], v[78:81]
	v_mfma_f32_16x16x32_bf16 v[74:77], v[102:105], v[186:189], v[74:77]
	v_mfma_f32_16x16x32_bf16 v[142:145], v[98:101], v[166:169], v[142:145]
	v_mfma_f32_16x16x32_bf16 v[138:141], v[106:109], v[166:169], v[138:141]
	v_mfma_f32_16x16x32_bf16 v[126:129], v[98:101], v[174:177], v[126:129]
	v_mfma_f32_16x16x32_bf16 v[122:125], v[106:109], v[174:177], v[122:125]
	v_mfma_f32_16x16x32_bf16 v[110:113], v[98:101], v[182:185], v[110:113]
	v_mfma_f32_16x16x32_bf16 v[94:97], v[106:109], v[182:185], v[94:97]
	v_mfma_f32_16x16x32_bf16 v[78:81], v[98:101], v[190:193], v[78:81]
	v_mfma_f32_16x16x32_bf16 v[74:77], v[106:109], v[190:193], v[74:77]
	v_mfma_f32_16x16x32_bf16 v[134:137], v[146:149], v[162:165], v[134:137]
	v_mfma_f32_16x16x32_bf16 v[130:133], v[154:157], v[162:165], v[130:133]
	v_mfma_f32_16x16x32_bf16 v[118:121], v[146:149], v[170:173], v[118:121]
	v_mfma_f32_16x16x32_bf16 v[114:117], v[154:157], v[170:173], v[114:117]
	v_mfma_f32_16x16x32_bf16 v[90:93], v[146:149], v[178:181], v[90:93]
	v_mfma_f32_16x16x32_bf16 v[86:89], v[154:157], v[178:181], v[86:89]
	v_mfma_f32_16x16x32_bf16 v[70:73], v[146:149], v[186:189], v[70:73]
	v_mfma_f32_16x16x32_bf16 v[66:69], v[154:157], v[186:189], v[66:69]
	v_mfma_f32_16x16x32_bf16 v[134:137], v[150:153], v[166:169], v[134:137]
	v_mfma_f32_16x16x32_bf16 v[130:133], v[158:161], v[166:169], v[130:133]
	v_mfma_f32_16x16x32_bf16 v[118:121], v[150:153], v[174:177], v[118:121]
	v_mfma_f32_16x16x32_bf16 v[114:117], v[158:161], v[174:177], v[114:117]
	v_mfma_f32_16x16x32_bf16 v[90:93], v[150:153], v[182:185], v[90:93]
	v_mfma_f32_16x16x32_bf16 v[86:89], v[158:161], v[182:185], v[86:89]
	v_mfma_f32_16x16x32_bf16 v[70:73], v[150:153], v[190:193], v[70:73]
	v_mfma_f32_16x16x32_bf16 v[66:69], v[158:161], v[190:193], v[66:69]
	s_setprio 0
	s_barrier
	s_add_i32 m0, s22, 0x17f80
	ds_read_b128 v[162:165], v249 offset:49152
	global_load_lds_dwordx4 v0, s[80:81] offset:128
	s_add_i32 m0, s22, 0x19f80
	ds_read_b128 v[166:169], v249 offset:50176
	global_load_lds_dwordx4 v218, s[80:81] offset:128
	s_add_i32 m0, s22, 0x1bf80
	ds_read_b128 v[170:173], v249 offset:51200
	global_load_lds_dwordx4 v0, s[100:101] offset:128
	s_add_i32 m0, s22, 0x1df80
	ds_read_b128 v[174:177], v249 offset:52224
	global_load_lds_dwordx4 v218, s[100:101] offset:128
	s_sub_i32 m0, s39, 0x80
	ds_read_b128 v[178:181], v249 offset:53248
	global_load_lds_dwordx4 v0, s[20:21] offset:128
	s_sub_i32 m0, s65, 0x80
	ds_read_b128 v[182:185], v249 offset:54272
	global_load_lds_dwordx4 v218, s[20:21] offset:128
	ds_read_b128 v[186:189], v249 offset:55296
	ds_read_b128 v[190:193], v249 offset:56320
	s_waitcnt vmcnt(8) lgkmcnt(0)
	s_barrier
	s_setprio 1
	v_mfma_f32_16x16x32_bf16 v[62:65], v[82:85], v[162:165], v[62:65]
	v_mfma_f32_16x16x32_bf16 v[58:61], v[102:105], v[162:165], v[58:61]
	v_mfma_f32_16x16x32_bf16 v[46:49], v[82:85], v[170:173], v[46:49]
	v_mfma_f32_16x16x32_bf16 v[42:45], v[102:105], v[170:173], v[42:45]
	s_add_u32 s10, s10, 0x100
	v_mfma_f32_16x16x32_bf16 v[30:33], v[82:85], v[178:181], v[30:33]
	s_addc_u32 s11, s11, 0
	v_mfma_f32_16x16x32_bf16 v[26:29], v[102:105], v[178:181], v[26:29]
	s_add_u32 s62, s62, 0x100
	v_mfma_f32_16x16x32_bf16 v[14:17], v[82:85], v[186:189], v[14:17]
	s_addc_u32 s63, s63, 0
	v_mfma_f32_16x16x32_bf16 v[10:13], v[102:105], v[186:189], v[10:13]
	s_mov_b32 s20, s78
	v_mfma_f32_16x16x32_bf16 v[62:65], v[98:101], v[166:169], v[62:65]
	v_mfma_f32_16x16x32_bf16 v[58:61], v[106:109], v[166:169], v[58:61]
	v_mfma_f32_16x16x32_bf16 v[46:49], v[98:101], v[174:177], v[46:49]
	v_mfma_f32_16x16x32_bf16 v[42:45], v[106:109], v[174:177], v[42:45]
	v_mfma_f32_16x16x32_bf16 v[30:33], v[98:101], v[182:185], v[30:33]
	v_mfma_f32_16x16x32_bf16 v[26:29], v[106:109], v[182:185], v[26:29]
	v_mfma_f32_16x16x32_bf16 v[14:17], v[98:101], v[190:193], v[14:17]
	v_mfma_f32_16x16x32_bf16 v[10:13], v[106:109], v[190:193], v[10:13]
	v_mfma_f32_16x16x32_bf16 v[54:57], v[146:149], v[162:165], v[54:57]
	v_mfma_f32_16x16x32_bf16 v[50:53], v[154:157], v[162:165], v[50:53]
	v_mfma_f32_16x16x32_bf16 v[38:41], v[146:149], v[170:173], v[38:41]
	v_mfma_f32_16x16x32_bf16 v[34:37], v[154:157], v[170:173], v[34:37]
	v_mfma_f32_16x16x32_bf16 v[22:25], v[146:149], v[178:181], v[22:25]
	v_mfma_f32_16x16x32_bf16 v[18:21], v[154:157], v[178:181], v[18:21]
	v_mfma_f32_16x16x32_bf16 v[6:9], v[146:149], v[186:189], v[6:9]
	v_mfma_f32_16x16x32_bf16 v[2:5], v[154:157], v[186:189], v[2:5]
	v_mfma_f32_16x16x32_bf16 v[54:57], v[150:153], v[166:169], v[54:57]
	v_mfma_f32_16x16x32_bf16 v[50:53], v[158:161], v[166:169], v[50:53]
	v_mfma_f32_16x16x32_bf16 v[38:41], v[150:153], v[174:177], v[38:41]
	v_mfma_f32_16x16x32_bf16 v[34:37], v[158:161], v[174:177], v[34:37]
	v_mfma_f32_16x16x32_bf16 v[22:25], v[150:153], v[182:185], v[22:25]
	v_mfma_f32_16x16x32_bf16 v[18:21], v[158:161], v[182:185], v[18:21]
	v_mfma_f32_16x16x32_bf16 v[6:9], v[150:153], v[190:193], v[6:9]
	v_mfma_f32_16x16x32_bf16 v[2:5], v[158:161], v[190:193], v[2:5]
	s_setprio 0
	s_cmp_ge_i32 s78, s67
	s_barrier
	s_cbranch_scc0 .LBB0_570

; #define PG8_STAGE(bufoff, gbase, voff) do { _Pragma("unroll") for (int _i = 0; _i < 2; ++_i) \
;         __builtin_amdgcn_global_load_lds((const unsigned*)((const char*)(gbase) + (voff)[_i]), (PG8_LAS unsigned*)(lds + (bufoff) + ldsw + _i * 8192), 16, 0, 0); } while (0)
; #define PG8_LDA(dst, b, h) do { _Pragma("unroll") for (int m = 0; m < 4; ++m) _Pragma("unroll") for (int k = 0; k < 2; ++k) dst[m][k] = *(const PG8_LAS bf16x8*)(lds + PG8_SA(b, h) + aoff + m * 2048 + k * 1024); } while (0)
; #define PG8_LDB(dst, b, h) do { _Pragma("unroll") for (int n = 0; n < 2; ++n) _Pragma("unroll") for (int k = 0; k < 2; ++k) dst[n][k] = *(const PG8_LAS bf16x8*)(lds + PG8_SB(b, h) + boff + n * 2048 + k * 1024); } while (0)
; #define PG8_WAIT_V(n) asm volatile("s_waitcnt vmcnt(" #n ")" ::: "memory")
; #define PG8_WAIT_L(n) asm volatile("s_waitcnt lgkmcnt(" #n ")" ::: "memory")
; #define PG8_BAR __builtin_amdgcn_s_barrier()
; #define PG8_SCHED __builtin_amdgcn_sched_barrier(0)
; template <class Epi, class Sched, bool ALIGN_EPI = false, bool SP2 = false>
; __device__ __forceinline__ void gemm_phase(PG8_LAS unsigned char* lds, const Gemm g, const Sched& S, const Epi& E) {
;     ...
;         const char* nA = has_next ? (const char*)g.A + (size_t)nxt.pm * tstep : cA; const char* nB = has_next ? (const char*)g.Bt + (size_t)nxt.pn * tstep : cB;
;         for (int t = 0; t < nt; t += 2) {
;             const bool last = (t == nt - 2);
;             const char* a1 = cA + (size_t)(t + 1) * kstep;
;             const char* a2 = last ? nA : cA + (size_t)(t + 2) * kstep; const char* b2 = last ? nB : cB + (size_t)(t + 2) * kstep;
;             const char* a3 = a2 + kstep; const char* b3 = b2 + kstep;
;             if (last && has_next) S.a_ready(nxt);
;             if constexpr (SP2) {
;             PG8_LDB(B0, 0, 0); PG8_LDB(B1, 0, 1); PG8_SCHED; PG8_LDA(At, 0, 0); PG8_STAGE(PG8_SA(1, 1), a1 + hstep, voffA);
;             PG8_WAIT_V(8); PG8_WAIT_L(0); PG8_BAR; PG8_MMA(0, 0, At, B0); PG8_MMA(0, 1, At, B1); PG8_BAR; PG8_SCHED;
;             PG8_LDA(At, 0, 1); PG8_STAGE(PG8_SB(0, 0), b2, voffB); PG8_STAGE(PG8_SB(0, 1), b2 + hstep, voffB); PG8_STAGE(PG8_SA(0, 0), a2, voffA);
;             PG8_WAIT_V(8); PG8_WAIT_L(0); PG8_BAR; PG8_MMA(1, 0, At, B0); PG8_MMA(1, 1, At, B1); PG8_BAR; PG8_SCHED;
.Lz_enter_639:
	s_add_u32 s8, s52, 0x80
	s_addc_u32 s9, s53, 0
	s_add_u32 s52, s20, 0x100
	s_addc_u32 s53, s21, 0
	s_mov_b32 s20, 0
	ds_read_b128 v[130:133], v181
	ds_read_b128 v[134:137], v181 offset:1024
	ds_read_b128 v[138:141], v181 offset:2048
	ds_read_b128 v[142:145], v181 offset:3072
	ds_read_b128 v[146:149], v181 offset:16384
	ds_read_b128 v[150:153], v181 offset:17408
	ds_read_b128 v[166:169], v181 offset:18432
	ds_read_b128 v[170:173], v181 offset:19456
	s_add_i32 m0, s55, 0xc000
	ds_read_b128 v[174:177], v183
	ds_read_b128 v[184:187], v183 offset:1024
	ds_read_b128 v[188:191], v183 offset:2048
	ds_read_b128 v[192:195], v183 offset:3072
	ds_read_b128 v[196:199], v183 offset:4096
	ds_read_b128 v[200:203], v183 offset:5120
	ds_read_b128 v[204:207], v183 offset:6144
	global_load_lds_dwordx4 v162, s[8:9]
	s_add_i32 m0, s55, 0xe000
	ds_read_b128 v[208:211], v183 offset:7168
	global_load_lds_dwordx4 v164, s[8:9]
	s_waitcnt vmcnt(8) lgkmcnt(0)
	s_barrier
	s_setprio 1
	v_mfma_f32_16x16x32_bf16 v[122:125], v[130:133], v[174:177], 0
	v_mfma_f32_16x16x32_bf16 v[118:121], v[138:141], v[174:177], 0
	v_mfma_f32_16x16x32_bf16 v[106:109], v[130:133], v[188:191], 0
	v_mfma_f32_16x16x32_bf16 v[102:105], v[138:141], v[188:191], 0
	s_add_i32 s68, s20, 2
	v_mfma_f32_16x16x32_bf16 v[90:93], v[130:133], v[196:199], 0
	s_add_u32 s69, s8, 0x80
	v_mfma_f32_16x16x32_bf16 v[86:89], v[138:141], v[196:199], 0
	s_addc_u32 s21, s9, 0
	v_mfma_f32_16x16x32_bf16 v[74:77], v[130:133], v[204:207], 0
	s_cmp_eq_u32 s63, s20
	v_mfma_f32_16x16x32_bf16 v[70:73], v[138:141], v[204:207], 0
	s_cselect_b32 s21, s49, s21
	v_mfma_f32_16x16x32_bf16 v[122:125], v[134:137], v[184:187], v[122:125]
	s_cselect_b32 s20, s48, s69
	v_mfma_f32_16x16x32_bf16 v[118:121], v[142:145], v[184:187], v[118:121]
	s_cselect_b32 s71, s51, s53
	v_mfma_f32_16x16x32_bf16 v[106:109], v[134:137], v[192:195], v[106:109]
	s_cselect_b32 s70, s50, s52
	v_mfma_f32_16x16x32_bf16 v[102:105], v[142:145], v[192:195], v[102:105]
	v_mfma_f32_16x16x32_bf16 v[90:93], v[134:137], v[200:203], v[90:93]
	v_mfma_f32_16x16x32_bf16 v[86:89], v[142:145], v[200:203], v[86:89]
	v_mfma_f32_16x16x32_bf16 v[74:77], v[134:137], v[208:211], v[74:77]
	v_mfma_f32_16x16x32_bf16 v[70:73], v[142:145], v[208:211], v[70:73]
	v_mfma_f32_16x16x32_bf16 v[126:129], v[146:149], v[174:177], 0
	v_mfma_f32_16x16x32_bf16 v[114:117], v[166:169], v[174:177], 0
	v_mfma_f32_16x16x32_bf16 v[110:113], v[146:149], v[188:191], 0
	v_mfma_f32_16x16x32_bf16 v[98:101], v[166:169], v[188:191], 0
	v_mfma_f32_16x16x32_bf16 v[94:97], v[146:149], v[196:199], 0
	v_mfma_f32_16x16x32_bf16 v[82:85], v[166:169], v[196:199], 0
	v_mfma_f32_16x16x32_bf16 v[78:81], v[146:149], v[204:207], 0
	v_mfma_f32_16x16x32_bf16 v[66:69], v[166:169], v[204:207], 0
	v_mfma_f32_16x16x32_bf16 v[126:129], v[150:153], v[184:187], v[126:129]
	v_mfma_f32_16x16x32_bf16 v[114:117], v[170:173], v[184:187], v[114:117]
	v_mfma_f32_16x16x32_bf16 v[110:113], v[150:153], v[192:195], v[110:113]
	v_mfma_f32_16x16x32_bf16 v[98:101], v[170:173], v[192:195], v[98:101]
	v_mfma_f32_16x16x32_bf16 v[94:97], v[150:153], v[200:203], v[94:97]
	v_mfma_f32_16x16x32_bf16 v[82:85], v[170:173], v[200:203], v[82:85]
	v_mfma_f32_16x16x32_bf16 v[78:81], v[150:153], v[208:211], v[78:81]
	v_mfma_f32_16x16x32_bf16 v[66:69], v[170:173], v[208:211], v[66:69]
	s_setprio 0
	s_barrier
	s_add_i32 m0, s23, 0x10000
	s_add_u32 s100, s70, s10
	s_addc_u32 s101, s71, s11
	ds_read_b128 v[174:177], v183 offset:16384
	ds_read_b128 v[184:187], v183 offset:17408
	ds_read_b128 v[188:191], v183 offset:18432
	global_load_lds_dwordx4 v0, s[70:71]
	s_add_i32 m0, s23, 0x12000
	ds_read_b128 v[192:195], v183 offset:19456
	global_load_lds_dwordx4 v154, s[70:71]
	s_add_i32 m0, s23, 0x14000
	ds_read_b128 v[196:199], v183 offset:20480
	global_load_lds_dwordx4 v0, s[100:101]
	s_add_i32 m0, s23, 0x16000
	ds_read_b128 v[200:203], v183 offset:21504
	global_load_lds_dwordx4 v154, s[100:101]
	s_mov_b32 m0, s55
	ds_read_b128 v[204:207], v183 offset:22528
	global_load_lds_dwordx4 v158, s[20:21]
	s_mov_b32 m0, s56
	ds_read_b128 v[208:211], v183 offset:23552
	global_load_lds_dwordx4 v156, s[20:21]
	s_waitcnt vmcnt(8) lgkmcnt(0)
	s_barrier
	s_setprio 1
	v_mfma_f32_16x16x32_bf16 v[58:61], v[130:133], v[174:177], 0
	v_mfma_f32_16x16x32_bf16 v[54:57], v[138:141], v[174:177], 0
	v_mfma_f32_16x16x32_bf16 v[42:45], v[130:133], v[188:191], 0
	v_mfma_f32_16x16x32_bf16 v[38:41], v[138:141], v[188:191], 0
	v_mfma_f32_16x16x32_bf16 v[26:29], v[130:133], v[196:199], 0
	v_mfma_f32_16x16x32_bf16 v[22:25], v[138:141], v[196:199], 0
	v_mfma_f32_16x16x32_bf16 v[10:13], v[130:133], v[204:207], 0
	v_mfma_f32_16x16x32_bf16 v[6:9], v[138:141], v[204:207], 0
	v_mfma_f32_16x16x32_bf16 v[58:61], v[134:137], v[184:187], v[58:61]
	v_mfma_f32_16x16x32_bf16 v[54:57], v[142:145], v[184:187], v[54:57]
	v_mfma_f32_16x16x32_bf16 v[42:45], v[134:137], v[192:195], v[42:45]
	v_mfma_f32_16x16x32_bf16 v[38:41], v[142:145], v[192:195], v[38:41]
	v_mfma_f32_16x16x32_bf16 v[26:29], v[134:137], v[200:203], v[26:29]
	v_mfma_f32_16x16x32_bf16 v[22:25], v[142:145], v[200:203], v[22:25]
	v_mfma_f32_16x16x32_bf16 v[10:13], v[134:137], v[208:211], v[10:13]
	v_mfma_f32_16x16x32_bf16 v[6:9], v[142:145], v[208:211], v[6:9]
	v_mfma_f32_16x16x32_bf16 v[62:65], v[146:149], v[174:177], 0
	v_mfma_f32_16x16x32_bf16 v[50:53], v[166:169], v[174:177], 0
	v_mfma_f32_16x16x32_bf16 v[46:49], v[146:149], v[188:191], 0
	v_mfma_f32_16x16x32_bf16 v[34:37], v[166:169], v[188:191], 0
	v_mfma_f32_16x16x32_bf16 v[30:33], v[146:149], v[196:199], 0
	v_mfma_f32_16x16x32_bf16 v[18:21], v[166:169], v[196:199], 0
	v_mfma_f32_16x16x32_bf16 v[14:17], v[146:149], v[204:207], 0
	v_mfma_f32_16x16x32_bf16 v[2:5], v[166:169], v[204:207], 0
	v_mfma_f32_16x16x32_bf16 v[62:65], v[150:153], v[184:187], v[62:65]
	v_mfma_f32_16x16x32_bf16 v[50:53], v[170:173], v[184:187], v[50:53]
	v_mfma_f32_16x16x32_bf16 v[46:49], v[150:153], v[192:195], v[46:49]
	v_mfma_f32_16x16x32_bf16 v[34:37], v[170:173], v[192:195], v[34:37]
	v_mfma_f32_16x16x32_bf16 v[30:33], v[150:153], v[200:203], v[30:33]
	v_mfma_f32_16x16x32_bf16 v[18:21], v[170:173], v[200:203], v[18:21]
	v_mfma_f32_16x16x32_bf16 v[14:17], v[150:153], v[208:211], v[14:17]
	v_mfma_f32_16x16x32_bf16 v[2:5], v[170:173], v[208:211], v[2:5]
	s_setprio 0
	s_barrier
; #define PG8_STAGE(bufoff, gbase, voff) do { _Pragma("unroll") for (int _i = 0; _i < 2; ++_i) \
;         __builtin_amdgcn_global_load_lds((const unsigned*)((const char*)(gbase) + (voff)[_i]), (PG8_LAS unsigned*)(lds + (bufoff) + ldsw + _i * 8192), 16, 0, 0); } while (0)
; #define PG8_LDA(dst, b, h) do { _Pragma("unroll") for (int m = 0; m < 4; ++m) _Pragma("unroll") for (int k = 0; k < 2; ++k) dst[m][k] = *(const PG8_LAS bf16x8*)(lds + PG8_SA(b, h) + aoff + m * 2048 + k * 1024); } while (0)
; #define PG8_LDB(dst, b, h) do { _Pragma("unroll") for (int n = 0; n < 2; ++n) _Pragma("unroll") for (int k = 0; k < 2; ++k) dst[n][k] = *(const PG8_LAS bf16x8*)(lds + PG8_SB(b, h) + boff + n * 2048 + k * 1024); } while (0)
; #define PG8_MMA(ai, bj, At, Bt) do { __builtin_amdgcn_s_setprio(1); _Pragma("unroll") for (int m = 0; m < 4; ++m) _Pragma("unroll") for (int n = 0; n < 2; ++n) _Pragma("unroll") for (int k = 0; k < 2; ++k) \
;         acc[ai][bj][m][n] = __builtin_amdgcn_mfma_f32_16x16x32_bf16(Bt[n][k], At[m][k], acc[ai][bj][m][n], 0, 0, 0); __builtin_amdgcn_s_setprio(0); } while (0)
; #define PG8_WAIT_V(n) asm volatile("s_waitcnt vmcnt(" #n ")" ::: "memory")
; #define PG8_WAIT_L(n) asm volatile("s_waitcnt lgkmcnt(" #n ")" ::: "memory")
; #define PG8_BAR __builtin_amdgcn_s_barrier()
; #define PG8_SCHED __builtin_amdgcn_sched_barrier(0)
; template <class Epi, class Sched, bool ALIGN_EPI = false, bool SP2 = false>
; __device__ __forceinline__ void gemm_phase(PG8_LAS unsigned char* lds, const Gemm g, const Sched& S, const Epi& E) {
;     ...
;             PG8_LDB(B0, 1, 0); PG8_LDB(B1, 1, 1); PG8_SCHED; PG8_LDA(At, 1, 0); PG8_STAGE(PG8_SA(0, 1), a2 + hstep, voffA);
;             PG8_WAIT_V(8); PG8_WAIT_L(0); PG8_BAR; PG8_MMA(0, 0, At, B0); PG8_MMA(0, 1, At, B1); PG8_BAR; PG8_SCHED;
;             PG8_LDA(At, 1, 1); PG8_STAGE(PG8_SB(1, 0), b3, voffB); PG8_STAGE(PG8_SB(1, 1), b3 + hstep, voffB); PG8_STAGE(PG8_SA(1, 0), a3, voffA);
;             PG8_WAIT_V(8); PG8_WAIT_L(0); PG8_BAR; PG8_MMA(1, 0, At, B0); PG8_MMA(1, 1, At, B1); PG8_BAR; PG8_SCHED;
	ds_read_b128 v[130:133], v181 offset:32768
	ds_read_b128 v[134:137], v181 offset:33792
	ds_read_b128 v[138:141], v181 offset:34816
	ds_read_b128 v[142:145], v181 offset:35840
	ds_read_b128 v[146:149], v181 offset:49152
	ds_read_b128 v[150:153], v181 offset:50176
	ds_read_b128 v[166:169], v181 offset:51200
	ds_read_b128 v[170:173], v181 offset:52224
	s_mov_b32 m0, s57
	ds_read_b128 v[174:177], v183 offset:32768
	ds_read_b128 v[184:187], v183 offset:33792
	ds_read_b128 v[188:191], v183 offset:34816
	ds_read_b128 v[192:195], v183 offset:35840
	ds_read_b128 v[196:199], v183 offset:36864
	ds_read_b128 v[200:203], v183 offset:37888
	ds_read_b128 v[204:207], v183 offset:38912
	global_load_lds_dwordx4 v162, s[20:21]
	s_mov_b32 m0, s58
	ds_read_b128 v[208:211], v183 offset:39936
	global_load_lds_dwordx4 v164, s[20:21]
	s_waitcnt vmcnt(8) lgkmcnt(0)
	s_barrier
	s_setprio 1
	v_mfma_f32_16x16x32_bf16 v[122:125], v[130:133], v[174:177], v[122:125]
	v_mfma_f32_16x16x32_bf16 v[118:121], v[138:141], v[174:177], v[118:121]
	v_mfma_f32_16x16x32_bf16 v[106:109], v[130:133], v[188:191], v[106:109]
	v_mfma_f32_16x16x32_bf16 v[102:105], v[138:141], v[188:191], v[102:105]
	v_mfma_f32_16x16x32_bf16 v[90:93], v[130:133], v[196:199], v[90:93]
	v_mfma_f32_16x16x32_bf16 v[86:89], v[138:141], v[196:199], v[86:89]
	v_mfma_f32_16x16x32_bf16 v[74:77], v[130:133], v[204:207], v[74:77]
	v_mfma_f32_16x16x32_bf16 v[70:73], v[138:141], v[204:207], v[70:73]
	v_mfma_f32_16x16x32_bf16 v[122:125], v[134:137], v[184:187], v[122:125]
	v_mfma_f32_16x16x32_bf16 v[118:121], v[142:145], v[184:187], v[118:121]
	v_mfma_f32_16x16x32_bf16 v[106:109], v[134:137], v[192:195], v[106:109]
	v_mfma_f32_16x16x32_bf16 v[102:105], v[142:145], v[192:195], v[102:105]
	v_mfma_f32_16x16x32_bf16 v[90:93], v[134:137], v[200:203], v[90:93]
	v_mfma_f32_16x16x32_bf16 v[86:89], v[142:145], v[200:203], v[86:89]
	v_mfma_f32_16x16x32_bf16 v[74:77], v[134:137], v[208:211], v[74:77]
	v_mfma_f32_16x16x32_bf16 v[70:73], v[142:145], v[208:211], v[70:73]
	v_mfma_f32_16x16x32_bf16 v[126:129], v[146:149], v[174:177], v[126:129]
	v_mfma_f32_16x16x32_bf16 v[114:117], v[166:169], v[174:177], v[114:117]
	v_mfma_f32_16x16x32_bf16 v[110:113], v[146:149], v[188:191], v[110:113]
	v_mfma_f32_16x16x32_bf16 v[98:101], v[166:169], v[188:191], v[98:101]
	v_mfma_f32_16x16x32_bf16 v[94:97], v[146:149], v[196:199], v[94:97]
	v_mfma_f32_16x16x32_bf16 v[82:85], v[166:169], v[196:199], v[82:85]
	v_mfma_f32_16x16x32_bf16 v[78:81], v[146:149], v[204:207], v[78:81]
	v_mfma_f32_16x16x32_bf16 v[66:69], v[166:169], v[204:207], v[66:69]
	v_mfma_f32_16x16x32_bf16 v[126:129], v[150:153], v[184:187], v[126:129]
	v_mfma_f32_16x16x32_bf16 v[114:117], v[170:173], v[184:187], v[114:117]
	v_mfma_f32_16x16x32_bf16 v[110:113], v[150:153], v[192:195], v[110:113]
	v_mfma_f32_16x16x32_bf16 v[98:101], v[170:173], v[192:195], v[98:101]
	v_mfma_f32_16x16x32_bf16 v[94:97], v[150:153], v[200:203], v[94:97]
	v_mfma_f32_16x16x32_bf16 v[82:85], v[170:173], v[200:203], v[82:85]
	v_mfma_f32_16x16x32_bf16 v[78:81], v[150:153], v[208:211], v[78:81]
	v_mfma_f32_16x16x32_bf16 v[66:69], v[170:173], v[208:211], v[66:69]
	s_setprio 0
	s_barrier
	s_add_i32 m0, s23, 0x17f80
	ds_read_b128 v[174:177], v183 offset:49152
	ds_read_b128 v[184:187], v183 offset:50176
	ds_read_b128 v[188:191], v183 offset:51200
	global_load_lds_dwordx4 v0, s[70:71] offset:128
	s_add_i32 m0, s23, 0x19f80
	ds_read_b128 v[192:195], v183 offset:52224
	global_load_lds_dwordx4 v154, s[70:71] offset:128
	s_add_i32 m0, s23, 0x1bf80
	ds_read_b128 v[196:199], v183 offset:53248
	global_load_lds_dwordx4 v0, s[100:101] offset:128
	s_add_i32 m0, s23, 0x1df80
	ds_read_b128 v[200:203], v183 offset:54272
	global_load_lds_dwordx4 v154, s[100:101] offset:128
	s_sub_i32 m0, s59, 0x80
	ds_read_b128 v[204:207], v183 offset:55296
	global_load_lds_dwordx4 v158, s[20:21] offset:128
	s_sub_i32 m0, s60, 0x80
	ds_read_b128 v[208:211], v183 offset:56320
	global_load_lds_dwordx4 v156, s[20:21] offset:128
	s_waitcnt vmcnt(8) lgkmcnt(0)
	s_barrier
	s_setprio 1
	v_mfma_f32_16x16x32_bf16 v[58:61], v[130:133], v[174:177], v[58:61]
	v_mfma_f32_16x16x32_bf16 v[54:57], v[138:141], v[174:177], v[54:57]
	v_mfma_f32_16x16x32_bf16 v[42:45], v[130:133], v[188:191], v[42:45]
	v_mfma_f32_16x16x32_bf16 v[38:41], v[138:141], v[188:191], v[38:41]
	s_add_u32 s8, s8, 0x100
	v_mfma_f32_16x16x32_bf16 v[26:29], v[130:133], v[196:199], v[26:29]
	s_addc_u32 s9, s9, 0
	v_mfma_f32_16x16x32_bf16 v[22:25], v[138:141], v[196:199], v[22:25]
	s_add_u32 s52, s52, 0x100
	v_mfma_f32_16x16x32_bf16 v[10:13], v[130:133], v[204:207], v[10:13]
	s_addc_u32 s53, s53, 0
	v_mfma_f32_16x16x32_bf16 v[6:9], v[138:141], v[204:207], v[6:9]
	s_mov_b32 s20, s68
	v_mfma_f32_16x16x32_bf16 v[58:61], v[134:137], v[184:187], v[58:61]
	v_mfma_f32_16x16x32_bf16 v[54:57], v[142:145], v[184:187], v[54:57]
	v_mfma_f32_16x16x32_bf16 v[42:45], v[134:137], v[192:195], v[42:45]
	v_mfma_f32_16x16x32_bf16 v[38:41], v[142:145], v[192:195], v[38:41]
	v_mfma_f32_16x16x32_bf16 v[26:29], v[134:137], v[200:203], v[26:29]
	v_mfma_f32_16x16x32_bf16 v[22:25], v[142:145], v[200:203], v[22:25]
	v_mfma_f32_16x16x32_bf16 v[10:13], v[134:137], v[208:211], v[10:13]
	v_mfma_f32_16x16x32_bf16 v[6:9], v[142:145], v[208:211], v[6:9]
	v_mfma_f32_16x16x32_bf16 v[62:65], v[146:149], v[174:177], v[62:65]
	v_mfma_f32_16x16x32_bf16 v[50:53], v[166:169], v[174:177], v[50:53]
	v_mfma_f32_16x16x32_bf16 v[46:49], v[146:149], v[188:191], v[46:49]
	v_mfma_f32_16x16x32_bf16 v[34:37], v[166:169], v[188:191], v[34:37]
	v_mfma_f32_16x16x32_bf16 v[30:33], v[146:149], v[196:199], v[30:33]
	v_mfma_f32_16x16x32_bf16 v[18:21], v[166:169], v[196:199], v[18:21]
	v_mfma_f32_16x16x32_bf16 v[14:17], v[146:149], v[204:207], v[14:17]
	v_mfma_f32_16x16x32_bf16 v[2:5], v[166:169], v[204:207], v[2:5]
	v_mfma_f32_16x16x32_bf16 v[62:65], v[150:153], v[184:187], v[62:65]
	v_mfma_f32_16x16x32_bf16 v[50:53], v[170:173], v[184:187], v[50:53]
	v_mfma_f32_16x16x32_bf16 v[46:49], v[150:153], v[192:195], v[46:49]
	v_mfma_f32_16x16x32_bf16 v[34:37], v[170:173], v[192:195], v[34:37]
	v_mfma_f32_16x16x32_bf16 v[30:33], v[150:153], v[200:203], v[30:33]
	v_mfma_f32_16x16x32_bf16 v[18:21], v[170:173], v[200:203], v[18:21]
	v_mfma_f32_16x16x32_bf16 v[14:17], v[150:153], v[208:211], v[14:17]
	v_mfma_f32_16x16x32_bf16 v[2:5], v[170:173], v[208:211], v[2:5]
	s_setprio 0
	s_cmp_ge_i32 s68, s62
	s_barrier
	s_cbranch_scc1 .Lpz_exit_641
; #define PG8_STAGE(bufoff, gbase, voff) do { _Pragma("unroll") for (int _i = 0; _i < 2; ++_i) \
;         __builtin_amdgcn_global_load_lds((const unsigned*)((const char*)(gbase) + (voff)[_i]), (PG8_LAS unsigned*)(lds + (bufoff) + ldsw + _i * 8192), 16, 0, 0); } while (0)
; #define PG8_LDA(dst, b, h) do { _Pragma("unroll") for (int m = 0; m < 4; ++m) _Pragma("unroll") for (int k = 0; k < 2; ++k) dst[m][k] = *(const PG8_LAS bf16x8*)(lds + PG8_SA(b, h) + aoff + m * 2048 + k * 1024); } while (0)
; #define PG8_LDB(dst, b, h) do { _Pragma("unroll") for (int n = 0; n < 2; ++n) _Pragma("unroll") for (int k = 0; k < 2; ++k) dst[n][k] = *(const PG8_LAS bf16x8*)(lds + PG8_SB(b, h) + boff + n * 2048 + k * 1024); } while (0)
; #define PG8_MMA(ai, bj, At, Bt) do { __builtin_amdgcn_s_setprio(1); _Pragma("unroll") for (int m = 0; m < 4; ++m) _Pragma("unroll") for (int n = 0; n < 2; ++n) _Pragma("unroll") for (int k = 0; k < 2; ++k) \
;         acc[ai][bj][m][n] = __builtin_amdgcn_mfma_f32_16x16x32_bf16(Bt[n][k], At[m][k], acc[ai][bj][m][n], 0, 0, 0); __builtin_amdgcn_s_setprio(0); } while (0)
; #define PG8_WAIT_V(n) asm volatile("s_waitcnt vmcnt(" #n ")" ::: "memory")
; #define PG8_BAR __builtin_amdgcn_s_barrier()
; template <class Epi, class Sched, bool ALIGN_EPI = false, bool SP2 = false>
; __device__ __forceinline__ void gemm_phase(PG8_LAS unsigned char* lds, const Gemm g, const Sched& S, const Epi& E) {
;     ...
;         for (int t = 0; t < nt; t += 2) {
;             const bool last = (t == nt - 2);
;             const char* a1 = cA + (size_t)(t + 1) * kstep;
;             const char* a2 = last ? nA : cA + (size_t)(t + 2) * kstep; const char* b2 = last ? nB : cB + (size_t)(t + 2) * kstep;
;             const char* a3 = a2 + kstep; const char* b3 = b2 + kstep;
;             if (last && has_next) S.a_ready(nxt);
;             if constexpr (SP2) {
;             PG8_LDB(B0, 0, 0); PG8_LDB(B1, 0, 1); PG8_SCHED; PG8_LDA(At, 0, 0); PG8_STAGE(PG8_SA(1, 1), a1 + hstep, voffA);
;             PG8_WAIT_V(8); PG8_WAIT_L(0); PG8_BAR; PG8_MMA(0, 0, At, B0); PG8_MMA(0, 1, At, B1); PG8_BAR; PG8_SCHED;
;             PG8_LDA(At, 0, 1); PG8_STAGE(PG8_SB(0, 0), b2, voffB); PG8_STAGE(PG8_SB(0, 1), b2 + hstep, voffB); PG8_STAGE(PG8_SA(0, 0), a2, voffA);
;             PG8_WAIT_V(8); PG8_WAIT_L(0); PG8_BAR; PG8_MMA(1, 0, At, B0); PG8_MMA(1, 1, At, B1); PG8_BAR; PG8_SCHED;
.LBB0_641:
	ds_read_b128 v[130:133], v181
	ds_read_b128 v[134:137], v181 offset:1024
	ds_read_b128 v[138:141], v181 offset:2048
	ds_read_b128 v[142:145], v181 offset:3072
	ds_read_b128 v[146:149], v181 offset:16384
	ds_read_b128 v[150:153], v181 offset:17408
	ds_read_b128 v[166:169], v181 offset:18432
	ds_read_b128 v[170:173], v181 offset:19456
	s_add_i32 m0, s55, 0xc000
	ds_read_b128 v[174:177], v183
	ds_read_b128 v[184:187], v183 offset:1024
	ds_read_b128 v[188:191], v183 offset:2048
	ds_read_b128 v[192:195], v183 offset:3072
	ds_read_b128 v[196:199], v183 offset:4096
	ds_read_b128 v[200:203], v183 offset:5120
	ds_read_b128 v[204:207], v183 offset:6144
	global_load_lds_dwordx4 v162, s[8:9]
	s_add_i32 m0, s55, 0xe000
	ds_read_b128 v[208:211], v183 offset:7168
	global_load_lds_dwordx4 v164, s[8:9]
	s_waitcnt vmcnt(8) lgkmcnt(0)
	s_barrier
	s_setprio 1
	v_mfma_f32_16x16x32_bf16 v[122:125], v[130:133], v[174:177], v[122:125]
	v_mfma_f32_16x16x32_bf16 v[118:121], v[138:141], v[174:177], v[118:121]
	v_mfma_f32_16x16x32_bf16 v[106:109], v[130:133], v[188:191], v[106:109]
	v_mfma_f32_16x16x32_bf16 v[102:105], v[138:141], v[188:191], v[102:105]
	s_add_i32 s68, s20, 2
	v_mfma_f32_16x16x32_bf16 v[90:93], v[130:133], v[196:199], v[90:93]
	s_add_u32 s69, s8, 0x80
	v_mfma_f32_16x16x32_bf16 v[86:89], v[138:141], v[196:199], v[86:89]
	s_addc_u32 s21, s9, 0
	v_mfma_f32_16x16x32_bf16 v[74:77], v[130:133], v[204:207], v[74:77]
	s_cmp_eq_u32 s63, s20
	v_mfma_f32_16x16x32_bf16 v[70:73], v[138:141], v[204:207], v[70:73]
	s_cselect_b32 s21, s49, s21
	v_mfma_f32_16x16x32_bf16 v[122:125], v[134:137], v[184:187], v[122:125]
	s_cselect_b32 s20, s48, s69
	v_mfma_f32_16x16x32_bf16 v[118:121], v[142:145], v[184:187], v[118:121]
	s_cselect_b32 s71, s51, s53
	v_mfma_f32_16x16x32_bf16 v[106:109], v[134:137], v[192:195], v[106:109]
	s_cselect_b32 s70, s50, s52
	v_mfma_f32_16x16x32_bf16 v[102:105], v[142:145], v[192:195], v[102:105]
	v_mfma_f32_16x16x32_bf16 v[90:93], v[134:137], v[200:203], v[90:93]
	v_mfma_f32_16x16x32_bf16 v[86:89], v[142:145], v[200:203], v[86:89]
	v_mfma_f32_16x16x32_bf16 v[74:77], v[134:137], v[208:211], v[74:77]
	v_mfma_f32_16x16x32_bf16 v[70:73], v[142:145], v[208:211], v[70:73]
	v_mfma_f32_16x16x32_bf16 v[126:129], v[146:149], v[174:177], v[126:129]
	v_mfma_f32_16x16x32_bf16 v[114:117], v[166:169], v[174:177], v[114:117]
	v_mfma_f32_16x16x32_bf16 v[110:113], v[146:149], v[188:191], v[110:113]
	v_mfma_f32_16x16x32_bf16 v[98:101], v[166:169], v[188:191], v[98:101]
	v_mfma_f32_16x16x32_bf16 v[94:97], v[146:149], v[196:199], v[94:97]
	v_mfma_f32_16x16x32_bf16 v[82:85], v[166:169], v[196:199], v[82:85]
	v_mfma_f32_16x16x32_bf16 v[78:81], v[146:149], v[204:207], v[78:81]
	v_mfma_f32_16x16x32_bf16 v[66:69], v[166:169], v[204:207], v[66:69]
	v_mfma_f32_16x16x32_bf16 v[126:129], v[150:153], v[184:187], v[126:129]
	v_mfma_f32_16x16x32_bf16 v[114:117], v[170:173], v[184:187], v[114:117]
	v_mfma_f32_16x16x32_bf16 v[110:113], v[150:153], v[192:195], v[110:113]
	v_mfma_f32_16x16x32_bf16 v[98:101], v[170:173], v[192:195], v[98:101]
	v_mfma_f32_16x16x32_bf16 v[94:97], v[150:153], v[200:203], v[94:97]
	v_mfma_f32_16x16x32_bf16 v[82:85], v[170:173], v[200:203], v[82:85]
	v_mfma_f32_16x16x32_bf16 v[78:81], v[150:153], v[208:211], v[78:81]
	v_mfma_f32_16x16x32_bf16 v[66:69], v[170:173], v[208:211], v[66:69]
	s_setprio 0
	s_barrier
	s_add_i32 m0, s23, 0x10000
	s_add_u32 s100, s70, s10
	s_addc_u32 s101, s71, s11
	ds_read_b128 v[174:177], v183 offset:16384
	ds_read_b128 v[184:187], v183 offset:17408
	ds_read_b128 v[188:191], v183 offset:18432
	global_load_lds_dwordx4 v0, s[70:71]
	s_add_i32 m0, s23, 0x12000
	ds_read_b128 v[192:195], v183 offset:19456
	global_load_lds_dwordx4 v154, s[70:71]
	s_add_i32 m0, s23, 0x14000
	ds_read_b128 v[196:199], v183 offset:20480
	global_load_lds_dwordx4 v0, s[100:101]
	s_add_i32 m0, s23, 0x16000
	ds_read_b128 v[200:203], v183 offset:21504
	global_load_lds_dwordx4 v154, s[100:101]
	s_mov_b32 m0, s55
	ds_read_b128 v[204:207], v183 offset:22528
	global_load_lds_dwordx4 v158, s[20:21]
	s_mov_b32 m0, s56
	ds_read_b128 v[208:211], v183 offset:23552
	global_load_lds_dwordx4 v156, s[20:21]
	s_waitcnt vmcnt(8) lgkmcnt(0)
	s_barrier
	s_setprio 1
	v_mfma_f32_16x16x32_bf16 v[58:61], v[130:133], v[174:177], v[58:61]
	v_mfma_f32_16x16x32_bf16 v[54:57], v[138:141], v[174:177], v[54:57]
	v_mfma_f32_16x16x32_bf16 v[42:45], v[130:133], v[188:191], v[42:45]
	v_mfma_f32_16x16x32_bf16 v[38:41], v[138:141], v[188:191], v[38:41]
	v_mfma_f32_16x16x32_bf16 v[26:29], v[130:133], v[196:199], v[26:29]
	v_mfma_f32_16x16x32_bf16 v[22:25], v[138:141], v[196:199], v[22:25]
	v_mfma_f32_16x16x32_bf16 v[10:13], v[130:133], v[204:207], v[10:13]
	v_mfma_f32_16x16x32_bf16 v[6:9], v[138:141], v[204:207], v[6:9]
	v_mfma_f32_16x16x32_bf16 v[58:61], v[134:137], v[184:187], v[58:61]
	v_mfma_f32_16x16x32_bf16 v[54:57], v[142:145], v[184:187], v[54:57]
	v_mfma_f32_16x16x32_bf16 v[42:45], v[134:137], v[192:195], v[42:45]
	v_mfma_f32_16x16x32_bf16 v[38:41], v[142:145], v[192:195], v[38:41]
	v_mfma_f32_16x16x32_bf16 v[26:29], v[134:137], v[200:203], v[26:29]
	v_mfma_f32_16x16x32_bf16 v[22:25], v[142:145], v[200:203], v[22:25]
	v_mfma_f32_16x16x32_bf16 v[10:13], v[134:137], v[208:211], v[10:13]
	v_mfma_f32_16x16x32_bf16 v[6:9], v[142:145], v[208:211], v[6:9]
	v_mfma_f32_16x16x32_bf16 v[62:65], v[146:149], v[174:177], v[62:65]
	v_mfma_f32_16x16x32_bf16 v[50:53], v[166:169], v[174:177], v[50:53]
	v_mfma_f32_16x16x32_bf16 v[46:49], v[146:149], v[188:191], v[46:49]
	v_mfma_f32_16x16x32_bf16 v[34:37], v[166:169], v[188:191], v[34:37]
	v_mfma_f32_16x16x32_bf16 v[30:33], v[146:149], v[196:199], v[30:33]
	v_mfma_f32_16x16x32_bf16 v[18:21], v[166:169], v[196:199], v[18:21]
	v_mfma_f32_16x16x32_bf16 v[14:17], v[146:149], v[204:207], v[14:17]
	v_mfma_f32_16x16x32_bf16 v[2:5], v[166:169], v[204:207], v[2:5]
	v_mfma_f32_16x16x32_bf16 v[62:65], v[150:153], v[184:187], v[62:65]
	v_mfma_f32_16x16x32_bf16 v[50:53], v[170:173], v[184:187], v[50:53]
	v_mfma_f32_16x16x32_bf16 v[46:49], v[150:153], v[192:195], v[46:49]
	v_mfma_f32_16x16x32_bf16 v[34:37], v[170:173], v[192:195], v[34:37]
	v_mfma_f32_16x16x32_bf16 v[30:33], v[150:153], v[200:203], v[30:33]
	v_mfma_f32_16x16x32_bf16 v[18:21], v[170:173], v[200:203], v[18:21]
	v_mfma_f32_16x16x32_bf16 v[14:17], v[150:153], v[208:211], v[14:17]
	v_mfma_f32_16x16x32_bf16 v[2:5], v[170:173], v[208:211], v[2:5]
	s_setprio 0
	s_barrier
; #define PG8_STAGE(bufoff, gbase, voff) do { _Pragma("unroll") for (int _i = 0; _i < 2; ++_i) \
;         __builtin_amdgcn_global_load_lds((const unsigned*)((const char*)(gbase) + (voff)[_i]), (PG8_LAS unsigned*)(lds + (bufoff) + ldsw + _i * 8192), 16, 0, 0); } while (0)
; #define PG8_LDA(dst, b, h) do { _Pragma("unroll") for (int m = 0; m < 4; ++m) _Pragma("unroll") for (int k = 0; k < 2; ++k) dst[m][k] = *(const PG8_LAS bf16x8*)(lds + PG8_SA(b, h) + aoff + m * 2048 + k * 1024); } while (0)
; #define PG8_LDB(dst, b, h) do { _Pragma("unroll") for (int n = 0; n < 2; ++n) _Pragma("unroll") for (int k = 0; k < 2; ++k) dst[n][k] = *(const PG8_LAS bf16x8*)(lds + PG8_SB(b, h) + boff + n * 2048 + k * 1024); } while (0)
; #define PG8_MMA(ai, bj, At, Bt) do { __builtin_amdgcn_s_setprio(1); _Pragma("unroll") for (int m = 0; m < 4; ++m) _Pragma("unroll") for (int n = 0; n < 2; ++n) _Pragma("unroll") for (int k = 0; k < 2; ++k) \
;         acc[ai][bj][m][n] = __builtin_amdgcn_mfma_f32_16x16x32_bf16(Bt[n][k], At[m][k], acc[ai][bj][m][n], 0, 0, 0); __builtin_amdgcn_s_setprio(0); } while (0)
; #define PG8_WAIT_V(n) asm volatile("s_waitcnt vmcnt(" #n ")" ::: "memory")
; #define PG8_WAIT_L(n) asm volatile("s_waitcnt lgkmcnt(" #n ")" ::: "memory")
; #define PG8_BAR __builtin_amdgcn_s_barrier()
; #define PG8_SCHED __builtin_amdgcn_sched_barrier(0)
; template <class Epi, class Sched, bool ALIGN_EPI = false, bool SP2 = false>
; __device__ __forceinline__ void gemm_phase(PG8_LAS unsigned char* lds, const Gemm g, const Sched& S, const Epi& E) {
;     ...
;             PG8_LDB(B0, 1, 0); PG8_LDB(B1, 1, 1); PG8_SCHED; PG8_LDA(At, 1, 0); PG8_STAGE(PG8_SA(0, 1), a2 + hstep, voffA);
;             PG8_WAIT_V(8); PG8_WAIT_L(0); PG8_BAR; PG8_MMA(0, 0, At, B0); PG8_MMA(0, 1, At, B1); PG8_BAR; PG8_SCHED;
;             PG8_LDA(At, 1, 1); PG8_STAGE(PG8_SB(1, 0), b3, voffB); PG8_STAGE(PG8_SB(1, 1), b3 + hstep, voffB); PG8_STAGE(PG8_SA(1, 0), a3, voffA);
;             PG8_WAIT_V(8); PG8_WAIT_L(0); PG8_BAR; PG8_MMA(1, 0, At, B0); PG8_MMA(1, 1, At, B1); PG8_BAR; PG8_SCHED;
	ds_read_b128 v[130:133], v181 offset:32768
	ds_read_b128 v[134:137], v181 offset:33792
	ds_read_b128 v[138:141], v181 offset:34816
	ds_read_b128 v[142:145], v181 offset:35840
	ds_read_b128 v[146:149], v181 offset:49152
	ds_read_b128 v[150:153], v181 offset:50176
	ds_read_b128 v[166:169], v181 offset:51200
	ds_read_b128 v[170:173], v181 offset:52224
	s_mov_b32 m0, s57
	ds_read_b128 v[174:177], v183 offset:32768
	ds_read_b128 v[184:187], v183 offset:33792
	ds_read_b128 v[188:191], v183 offset:34816
	ds_read_b128 v[192:195], v183 offset:35840
	ds_read_b128 v[196:199], v183 offset:36864
	ds_read_b128 v[200:203], v183 offset:37888
	ds_read_b128 v[204:207], v183 offset:38912
	global_load_lds_dwordx4 v162, s[20:21]
	s_mov_b32 m0, s58
	ds_read_b128 v[208:211], v183 offset:39936
	global_load_lds_dwordx4 v164, s[20:21]
	s_waitcnt vmcnt(8) lgkmcnt(0)
	s_barrier
	s_setprio 1
	v_mfma_f32_16x16x32_bf16 v[122:125], v[130:133], v[174:177], v[122:125]
	v_mfma_f32_16x16x32_bf16 v[118:121], v[138:141], v[174:177], v[118:121]
	v_mfma_f32_16x16x32_bf16 v[106:109], v[130:133], v[188:191], v[106:109]
	v_mfma_f32_16x16x32_bf16 v[102:105], v[138:141], v[188:191], v[102:105]
	v_mfma_f32_16x16x32_bf16 v[90:93], v[130:133], v[196:199], v[90:93]
	v_mfma_f32_16x16x32_bf16 v[86:89], v[138:141], v[196:199], v[86:89]
	v_mfma_f32_16x16x32_bf16 v[74:77], v[130:133], v[204:207], v[74:77]
	v_mfma_f32_16x16x32_bf16 v[70:73], v[138:141], v[204:207], v[70:73]
	v_mfma_f32_16x16x32_bf16 v[122:125], v[134:137], v[184:187], v[122:125]
	v_mfma_f32_16x16x32_bf16 v[118:121], v[142:145], v[184:187], v[118:121]
	v_mfma_f32_16x16x32_bf16 v[106:109], v[134:137], v[192:195], v[106:109]
	v_mfma_f32_16x16x32_bf16 v[102:105], v[142:145], v[192:195], v[102:105]
	v_mfma_f32_16x16x32_bf16 v[90:93], v[134:137], v[200:203], v[90:93]
	v_mfma_f32_16x16x32_bf16 v[86:89], v[142:145], v[200:203], v[86:89]
	v_mfma_f32_16x16x32_bf16 v[74:77], v[134:137], v[208:211], v[74:77]
	v_mfma_f32_16x16x32_bf16 v[70:73], v[142:145], v[208:211], v[70:73]
	v_mfma_f32_16x16x32_bf16 v[126:129], v[146:149], v[174:177], v[126:129]
	v_mfma_f32_16x16x32_bf16 v[114:117], v[166:169], v[174:177], v[114:117]
	v_mfma_f32_16x16x32_bf16 v[110:113], v[146:149], v[188:191], v[110:113]
	v_mfma_f32_16x16x32_bf16 v[98:101], v[166:169], v[188:191], v[98:101]
	v_mfma_f32_16x16x32_bf16 v[94:97], v[146:149], v[196:199], v[94:97]
	v_mfma_f32_16x16x32_bf16 v[82:85], v[166:169], v[196:199], v[82:85]
	v_mfma_f32_16x16x32_bf16 v[78:81], v[146:149], v[204:207], v[78:81]
	v_mfma_f32_16x16x32_bf16 v[66:69], v[166:169], v[204:207], v[66:69]
	v_mfma_f32_16x16x32_bf16 v[126:129], v[150:153], v[184:187], v[126:129]
	v_mfma_f32_16x16x32_bf16 v[114:117], v[170:173], v[184:187], v[114:117]
	v_mfma_f32_16x16x32_bf16 v[110:113], v[150:153], v[192:195], v[110:113]
	v_mfma_f32_16x16x32_bf16 v[98:101], v[170:173], v[192:195], v[98:101]
	v_mfma_f32_16x16x32_bf16 v[94:97], v[150:153], v[200:203], v[94:97]
	v_mfma_f32_16x16x32_bf16 v[82:85], v[170:173], v[200:203], v[82:85]
	v_mfma_f32_16x16x32_bf16 v[78:81], v[150:153], v[208:211], v[78:81]
	v_mfma_f32_16x16x32_bf16 v[66:69], v[170:173], v[208:211], v[66:69]
	s_setprio 0
	s_barrier
	s_add_i32 m0, s23, 0x17f80
	ds_read_b128 v[174:177], v183 offset:49152
	ds_read_b128 v[184:187], v183 offset:50176
	ds_read_b128 v[188:191], v183 offset:51200
	global_load_lds_dwordx4 v0, s[70:71] offset:128
	s_add_i32 m0, s23, 0x19f80
	ds_read_b128 v[192:195], v183 offset:52224
	global_load_lds_dwordx4 v154, s[70:71] offset:128
	s_add_i32 m0, s23, 0x1bf80
	ds_read_b128 v[196:199], v183 offset:53248
	global_load_lds_dwordx4 v0, s[100:101] offset:128
	s_add_i32 m0, s23, 0x1df80
	ds_read_b128 v[200:203], v183 offset:54272
	global_load_lds_dwordx4 v154, s[100:101] offset:128
	s_sub_i32 m0, s59, 0x80
	ds_read_b128 v[204:207], v183 offset:55296
	global_load_lds_dwordx4 v158, s[20:21] offset:128
	s_sub_i32 m0, s60, 0x80
	ds_read_b128 v[208:211], v183 offset:56320
	global_load_lds_dwordx4 v156, s[20:21] offset:128
	s_waitcnt vmcnt(8) lgkmcnt(0)
	s_barrier
	s_setprio 1
	v_mfma_f32_16x16x32_bf16 v[58:61], v[130:133], v[174:177], v[58:61]
	v_mfma_f32_16x16x32_bf16 v[54:57], v[138:141], v[174:177], v[54:57]
	v_mfma_f32_16x16x32_bf16 v[42:45], v[130:133], v[188:191], v[42:45]
	v_mfma_f32_16x16x32_bf16 v[38:41], v[138:141], v[188:191], v[38:41]
	s_add_u32 s8, s8, 0x100
	v_mfma_f32_16x16x32_bf16 v[26:29], v[130:133], v[196:199], v[26:29]
	s_addc_u32 s9, s9, 0
	v_mfma_f32_16x16x32_bf16 v[22:25], v[138:141], v[196:199], v[22:25]
	s_add_u32 s52, s52, 0x100
	v_mfma_f32_16x16x32_bf16 v[10:13], v[130:133], v[204:207], v[10:13]
	s_addc_u32 s53, s53, 0
	v_mfma_f32_16x16x32_bf16 v[6:9], v[138:141], v[204:207], v[6:9]
	s_mov_b32 s20, s68
	v_mfma_f32_16x16x32_bf16 v[58:61], v[134:137], v[184:187], v[58:61]
	v_mfma_f32_16x16x32_bf16 v[54:57], v[142:145], v[184:187], v[54:57]
	v_mfma_f32_16x16x32_bf16 v[42:45], v[134:137], v[192:195], v[42:45]
	v_mfma_f32_16x16x32_bf16 v[38:41], v[142:145], v[192:195], v[38:41]
	v_mfma_f32_16x16x32_bf16 v[26:29], v[134:137], v[200:203], v[26:29]
	v_mfma_f32_16x16x32_bf16 v[22:25], v[142:145], v[200:203], v[22:25]
	v_mfma_f32_16x16x32_bf16 v[10:13], v[134:137], v[208:211], v[10:13]
	v_mfma_f32_16x16x32_bf16 v[6:9], v[142:145], v[208:211], v[6:9]
	v_mfma_f32_16x16x32_bf16 v[62:65], v[146:149], v[174:177], v[62:65]
	v_mfma_f32_16x16x32_bf16 v[50:53], v[166:169], v[174:177], v[50:53]
	v_mfma_f32_16x16x32_bf16 v[46:49], v[146:149], v[188:191], v[46:49]
	v_mfma_f32_16x16x32_bf16 v[34:37], v[166:169], v[188:191], v[34:37]
	v_mfma_f32_16x16x32_bf16 v[30:33], v[146:149], v[196:199], v[30:33]
	v_mfma_f32_16x16x32_bf16 v[18:21], v[166:169], v[196:199], v[18:21]
	v_mfma_f32_16x16x32_bf16 v[14:17], v[146:149], v[204:207], v[14:17]
	v_mfma_f32_16x16x32_bf16 v[2:5], v[166:169], v[204:207], v[2:5]
	v_mfma_f32_16x16x32_bf16 v[62:65], v[150:153], v[184:187], v[62:65]
	v_mfma_f32_16x16x32_bf16 v[50:53], v[170:173], v[184:187], v[50:53]
	v_mfma_f32_16x16x32_bf16 v[46:49], v[150:153], v[192:195], v[46:49]
	v_mfma_f32_16x16x32_bf16 v[34:37], v[170:173], v[192:195], v[34:37]
	v_mfma_f32_16x16x32_bf16 v[30:33], v[150:153], v[200:203], v[30:33]
	v_mfma_f32_16x16x32_bf16 v[18:21], v[170:173], v[200:203], v[18:21]
	v_mfma_f32_16x16x32_bf16 v[14:17], v[150:153], v[208:211], v[14:17]
	v_mfma_f32_16x16x32_bf16 v[2:5], v[170:173], v[208:211], v[2:5]
	s_setprio 0
	s_cmp_ge_i32 s68, s62
	s_barrier
	s_cbranch_scc0 .LBB0_641
